# strategy 4: one static s_setprio 1 for waves 4-7 before each GEMM unit loop, per-segment flips removed (on v8, baseline loop placement)
# speedup vs baseline: 1.0111x; 1.0091x over previous
; __device__ __forceinline__ void xcd_barrier(const XcdBarrier& b) {
;     asm volatile("s_waitcnt vmcnt(0)" ::: "memory");
;     __syncthreads();
;     if (threadIdx.x == 0) {
;         unsigned* bar = b.bar;
;         __builtin_amdgcn_s_waitcnt(0);
;         unsigned nloc = b.st[0], nx = b.st[1];
;         if (nloc == 0u) { xcd_barrier_complete(bar, b.x, nloc, nx); b.st[0] = nloc; b.st[1] = nx; }
.LBB0_75:
	s_load_dwordx4 s[4:7], s[90:91], 0x98
	s_waitcnt lgkmcnt(0)
	s_cmp_gt_i32 s7, 1
	s_cbranch_scc0 .LBB0_118
	s_setprio 0
	s_mov_b64 s[30:31], s[96:97]
	s_waitcnt vmcnt(0)
	v_cmp_eq_u32_e32 vcc, 0, v0
	s_barrier
	s_and_saveexec_b64 s[0:1], vcc
	s_cbranch_execz .LBB0_117
	v_mov_b32_e32 v1, s93
	s_waitcnt vmcnt(0) expcnt(0) lgkmcnt(0)
	ds_read_b32 v3, v1
	ds_read_b32 v1, v1 offset:4
	s_waitcnt lgkmcnt(1)
	v_cmp_ne_u32_e32 vcc, 0, v3
	s_cbranch_vccnz .LBB0_92
	s_add_u32 s6, s30, 0x1000
	s_addc_u32 s7, s31, 0
	s_load_dwordx2 s[4:5], s[94:95], 0x4
	s_add_u32 s8, s30, 0x1100
	s_addc_u32 s9, s31, 0
	s_add_u32 s10, s30, 0x1200
	s_addc_u32 s11, s31, 0
	s_add_u32 s12, s30, 0x1300
	s_waitcnt lgkmcnt(0)
	s_mul_i32 s3, s4, s92
	s_addc_u32 s13, s31, 0
	s_mul_i32 s3, s3, s5
	s_mov_b32 s22, 1
	s_mov_b64 s[4:5], 0
	v_mov_b64_e32 v[2:3], s[30:31]
	v_mov_b64_e32 v[4:5], s[6:7]
	v_mov_b64_e32 v[6:7], s[8:9]
	v_mov_b64_e32 v[8:9], s[10:11]
	v_mov_b64_e32 v[10:11], s[12:13]
	s_branch .LBB0_81

; #define PG8_STAGE(bufoff, gbase, voff) do { _Pragma("unroll") for (int _i = 0; _i < 2; ++_i) \
;         __builtin_amdgcn_global_load_lds((const unsigned*)((const char*)(gbase) + (voff)[_i]), (LAS unsigned*)(lds + (bufoff) + ldsw + _i * 8192), 16, 0, 0); } while (0)
; #define PG8_BAR __builtin_amdgcn_s_barrier()
; template <class Epi, class Sched>
; __device__ __forceinline__ void gemm_phase(LAS unsigned char* lds, const Gemm g, const Sched& S, const Epi& E) {
;     ...
;     unsigned voffA[2], voffB[2];
; #pragma unroll
;     for (int i = 0; i < 2; ++i) { int R, C; stage_rc(tid * 16 + i * 8192, R, C); const int Rb = Epi::PERM ? ((R & ~31) + perm32(R & 31)) : R;
;         voffA[i] = (unsigned)(R * g.lda + C) * 2u; voffB[i] = (unsigned)(Rb * g.ldb + C) * 2u; }
;     const size_t kstep = (size_t)(BK * 2);
;     const size_t hstepA = (size_t)HALF * g.lda * 2, hstepB = (size_t)HALF * g.ldb * 2;
;     const size_t tstepA = 2 * hstepA, tstepB = 2 * hstepB;
;     const unsigned ldsw = (unsigned)wid * 1024u;
;     const int aoff = lds_byte(wr * 64 + fr, fq * 8), boff = lds_byte(wc * 32 + fr, fq * 8);
;     ...
;     Unit cur, nxt; int ui = 0;
;     if (!S.next(0, cur)) return;
;     f32x4 acc[2][2][4][2];
; #pragma unroll
;     for (int a = 0; a < 2; ++a)
; #pragma unroll
;         for (int b = 0; b < 2; ++b)
; #pragma unroll
;             for (int m = 0; m < 4; ++m)
; #pragma unroll
;                 for (int n = 0; n < 2; ++n) acc[a][b][m][n] = (f32x4){0.f, 0.f, 0.f, 0.f};
;     bf16x8 At[4][2], B0[2][2], B1[2][2];
;     const char* cA = (const char*)g.A + (size_t)cur.pm * tstepA + (size_t)cur.ka * 2; const char* cB = (const char*)g.Bt + (size_t)cur.pn * tstepB;
;     S.a_ready(cur);
;     PG8_STAGE(PG8_SB(0, 0), cB, voffB); PG8_STAGE(PG8_SB(0, 1), cB + hstepB, voffB); PG8_STAGE(PG8_SA(0, 0), cA, voffA); PG8_STAGE(PG8_SA(0, 1), cA + hstepA, voffA);
;     if (wr == 1) PG8_BAR;
.LBB0_127:
	s_andn2_b64 vcc, exec, s[10:11]
	v_readlane_b32 s10, v254, 36
	s_or_b32 s65, s64, s10
	s_cbranch_vccnz .LBB0_261
	v_readlane_b32 s12, v253, 6
	s_mov_b64 s[10:11], s[90:91]
	v_mov_b32_e32 v14, v0
	v_readlane_b32 s13, v253, 7
	s_andn2_b64 vcc, exec, s[12:13]
	v_readfirstlane_b32 s16, v14
	s_mul_i32 s67, s65, 0x2b00000
	s_cbranch_vccnz .LBB0_144
	v_lshlrev_b32_e32 v3, 4, v14
	v_add_u32_e32 v2, 0x2000, v3
	v_ashrrev_i32_e32 v4, 31, v2
	v_lshrrev_b32_e32 v4, 22, v4
	v_add_u32_e32 v4, v2, v4
	v_ashrrev_i32_e32 v15, 10, v4
	s_load_dwordx2 s[14:15], s[10:11], 0x98
	v_mul_i32_i24_e32 v4, 0x400, v15
	v_sub_u32_e32 v2, v2, v4
	v_lshrrev_b32_e32 v4, 4, v2
	v_bitop3_b32 v2, v4, v2, 32 bitop3:0x6c
	v_ashrrev_i32_e32 v4, 31, v2
	s_waitcnt lgkmcnt(0)
	s_add_u32 s34, s14, 0x9000000
	v_lshrrev_b32_e32 v4, 26, v4
	s_addc_u32 s42, s15, 0
	v_add_u32_e32 v4, v2, v4
	s_waitcnt vmcnt(0)
	v_lshlrev_b32_e32 v6, 3, v15
	s_add_u32 s10, s14, s67
	v_ashrrev_i32_e32 v16, 6, v4
	v_and_b32_e32 v6, -16, v6
	s_addc_u32 s11, s15, 0
	v_add_u32_e32 v6, v16, v6
	s_add_u32 s43, s10, 0x21400000
	v_and_b32_e32 v7, 3, v16
	s_mov_b32 s10, 0xfffe0
	v_lshrrev_b32_e32 v8, 2, v6
	v_lshlrev_b32_e32 v9, 1, v6
	v_and_b32_e32 v4, 0xc0, v4
	v_and_or_b32 v7, v6, s10, v7
	v_and_b32_e32 v8, 4, v8
	v_and_b32_e32 v9, 24, v9
	v_sub_u32_e32 v2, v2, v4
	v_or3_b32 v7, v7, v8, v9
	v_lshlrev_b32_e32 v8, 5, v15
	v_ashrrev_i16_sdwa v2, v232, sext(v2) dst_sel:DWORD dst_unused:UNUSED_PAD src0_sel:DWORD src1_sel:BYTE_0
	v_and_b32_e32 v8, 32, v8
	v_bfe_i32 v17, v2, 0, 16
	v_add_lshl_u32 v4, v8, v17, 1
	v_lshl_add_u32 v2, v7, 12, v4
	v_lshl_add_u32 v134, v6, 12, v4
	v_bfe_i32 v4, v14, 27, 1
	v_lshrrev_b32_e32 v4, 22, v4
	v_add_u32_e32 v4, v3, v4
	v_and_b32_e32 v4, 0xfffffc00, v4
	v_sub_u32_e32 v3, v3, v4
	v_lshrrev_b32_e32 v4, 4, v3
	v_ashrrev_i32_e32 v6, 31, v14
	v_bitop3_b32 v3, v4, v3, 32 bitop3:0x6c
	v_lshrrev_b32_e32 v6, 26, v6
	v_ashrrev_i32_e32 v4, 31, v3
	v_add_u32_e32 v6, v14, v6
	v_lshrrev_b32_e32 v4, 26, v4
	v_ashrrev_i32_e32 v19, 6, v6
	v_add_u32_e32 v4, v3, v4
	v_lshlrev_b32_e32 v6, 3, v19
	v_ashrrev_i32_e32 v18, 6, v4
	v_and_b32_e32 v6, -16, v6
	s_addc_u32 s44, s11, 0
	s_ashr_i32 s18, s16, 6
	v_add_u32_e32 v6, v18, v6
	v_and_b32_e32 v7, 3, v18
	s_ashr_i32 s17, s16, 8
	s_lshl_b32 s45, s18, 10
	v_and_or_b32 v7, v6, s10, v7
	v_lshrrev_b32_e32 v8, 2, v6
	v_lshlrev_b32_e32 v9, 1, v6
	v_and_b32_e32 v4, 0xc0, v4
	v_readlane_b32 s10, v253, 55
	v_and_b32_e32 v8, 4, v8
	v_and_b32_e32 v9, 24, v9
	v_sub_u32_e32 v3, v3, v4
	v_readlane_b32 s11, v253, 56
	s_add_u32 s26, s34, s10
	v_or3_b32 v7, v7, v8, v9
	v_lshlrev_b32_e32 v8, 5, v19
	v_ashrrev_i16_sdwa v3, v232, sext(v3) dst_sel:DWORD dst_unused:UNUSED_PAD src0_sel:DWORD src1_sel:BYTE_0
	s_addc_u32 s27, s42, s11
	v_readlane_b32 s10, v253, 59
	v_and_b32_e32 v8, 32, v8
	v_bfe_i32 v20, v3, 0, 16
	v_readlane_b32 s11, v253, 60
	s_add_u32 s28, s43, s10
	v_add_lshl_u32 v3, v8, v20, 1
	s_addc_u32 s29, s44, s11
	s_add_i32 s46, s45, 0
	v_lshl_add_u32 v4, v7, 12, v3
	s_add_i32 m0, s46, 0x10000
	v_lshl_add_u32 v136, v6, 12, v3
	global_load_lds_dwordx4 v4, s[28:29]
	s_add_i32 m0, s46, 0x12000
	s_add_u32 s10, s28, 0x80000
	global_load_lds_dwordx4 v2, s[28:29]
	s_addc_u32 s11, s29, 0
	s_add_i32 m0, s46, 0x14000
	s_add_i32 s47, s46, 0x2000
	global_load_lds_dwordx4 v4, s[10:11]
	s_add_i32 m0, s46, 0x16000
	v_mov_b32_e32 v3, v5
	global_load_lds_dwordx4 v2, s[10:11]
	s_mov_b32 m0, s46
	s_add_u32 s10, s26, 0x80000
	global_load_lds_dwordx4 v136, s[26:27]
	s_mov_b32 m0, s47
	s_addc_u32 s11, s27, 0
	s_add_i32 s48, s46, 0x4000
	global_load_lds_dwordx4 v134, s[26:27]
	s_mov_b32 m0, s48
	s_add_i32 s49, s46, 0x6000
	global_load_lds_dwordx4 v136, s[10:11]
	s_mov_b32 m0, s49
	v_mov_b32_e32 v137, v5
	global_load_lds_dwordx4 v134, s[10:11]
	v_mov_b32_e32 v135, v5
	s_cmp_eq_u32 s17, 1
	v_lshl_add_u64 v[12:13], s[28:29], 0, v[4:5]
	v_lshl_add_u64 v[10:11], s[28:29], 0, v[2:3]
	v_lshl_add_u64 v[6:7], s[26:27], 0, v[136:137]
	s_cselect_b64 s[10:11], -1, 0
	s_cmp_lg_u32 s17, 1
	v_lshl_add_u64 v[8:9], s[26:27], 0, v[134:135]
	s_cbranch_scc1 .LBB0_131
	s_barrier
	s_setprio 1

; #define PG8_STAGE(bufoff, gbase, voff) do { _Pragma("unroll") for (int _i = 0; _i < 2; ++_i) \
;         __builtin_amdgcn_global_load_lds((const unsigned*)((const char*)(gbase) + (voff)[_i]), (LAS unsigned*)(lds + (bufoff) + ldsw + _i * 8192), 16, 0, 0); } while (0)
; #define PG8_WAIT_V(n) asm volatile("s_waitcnt vmcnt(" #n ")" ::: "memory")
; #define PG8_BAR __builtin_amdgcn_s_barrier()
; template <class Epi, class Sched>
; __device__ __forceinline__ void gemm_phase(LAS unsigned char* lds, const Gemm g, const Sched& S, const Epi& E) {
;     ...
;     PG8_WAIT_V(2); PG8_BAR;
;     PG8_STAGE(PG8_SB(1, 0), cB + kstep, voffB); PG8_STAGE(PG8_SA(1, 0), cA + kstep, voffA); PG8_STAGE(PG8_SB(1, 1), cB + hstepB + kstep, voffB);
;     PG8_WAIT_V(6); PG8_BAR;
;     for (;;) {
;         const bool has_next = S.next(ui + 1, nxt);
;         const char* nA = has_next ? (const char*)g.A + (size_t)nxt.pm * tstepA + (size_t)nxt.ka * 2 : cA; const char* nB = has_next ? (const char*)g.Bt + (size_t)nxt.pn * tstepB : cB;
;         for (int t = 0; t < nt; t += 2) {
.Lmy_rsfill_done:
	s_or_b64 exec, exec, s[100:101]
	s_mov_b32 s100, s54
	s_waitcnt lgkmcnt(0)
	s_barrier
	v_readlane_b32 s19, v253, 54
	s_branch .LBB0_134
	s_nop 0
	s_nop 0
	s_nop 0
	s_nop 0
	s_nop 0
	s_nop 0
	s_nop 0
	s_nop 0
	s_nop 0
	s_nop 0
	s_nop 0
	s_nop 0
	s_nop 0
	s_nop 0
	s_nop 0
	s_nop 0
	s_nop 0
	s_nop 0
	s_nop 0
	s_nop 0
	s_nop 0
	s_nop 0
	s_nop 0
	s_nop 0
	s_nop 0
	s_nop 0
	s_nop 0
	s_nop 0
	s_nop 0
	s_nop 0
	s_nop 0
	s_nop 0
	s_nop 0

; #define PG8_STAGE(bufoff, gbase, voff) do { _Pragma("unroll") for (int _i = 0; _i < 2; ++_i) \
;         __builtin_amdgcn_global_load_lds((const unsigned*)((const char*)(gbase) + (voff)[_i]), (LAS unsigned*)(lds + (bufoff) + ldsw + _i * 8192), 16, 0, 0); } while (0)
; #define PG8_LDA(dst, b, h) do { _Pragma("unroll") for (int m = 0; m < 4; ++m) _Pragma("unroll") for (int k = 0; k < 2; ++k) dst[m][k] = *(const LAS bf16x8*)(lds + PG8_SA(b, h) + aoff + m * 2048 + k * 1024); } while (0)
; #define PG8_LDB(dst, b, h) do { _Pragma("unroll") for (int n = 0; n < 2; ++n) _Pragma("unroll") for (int k = 0; k < 2; ++k) dst[n][k] = *(const LAS bf16x8*)(lds + PG8_SB(b, h) + boff + n * 2048 + k * 1024); } while (0)
; #define PG8_MMA(ai, bj, At, Bt) do { __builtin_amdgcn_s_setprio(1); _Pragma("unroll") for (int m = 0; m < 4; ++m) _Pragma("unroll") for (int n = 0; n < 2; ++n) _Pragma("unroll") for (int k = 0; k < 2; ++k) \
;         acc[ai][bj][m][n] = __builtin_amdgcn_mfma_f32_16x16x32_bf16(Bt[n][k], At[m][k], acc[ai][bj][m][n], 0, 0, 0); __builtin_amdgcn_s_setprio(0); } while (0)
; #define PG8_WAIT_V(n) asm volatile("s_waitcnt vmcnt(" #n ")" ::: "memory")
; #define PG8_WAIT_L(n) asm volatile("s_waitcnt lgkmcnt(" #n ")" ::: "memory")
; #define PG8_BAR __builtin_amdgcn_s_barrier()
; #define PG8_SCHED __builtin_amdgcn_sched_barrier(0)
; template <class Epi, class Sched>
; __device__ __forceinline__ void gemm_phase(LAS unsigned char* lds, const Gemm g, const Sched& S, const Epi& E) {
;     ...
;             PG8_LDB(B0, 0, 0); PG8_LDB(B1, 0, 1); PG8_SCHED; PG8_LDA(At, 0, 0); PG8_STAGE(PG8_SA(1, 1), a1 + hstepA, voffA);
;             PG8_WAIT_V(8); PG8_WAIT_L(0); PG8_BAR; PG8_MMA(0, 0, At, B0); PG8_MMA(0, 1, At, B1); PG8_BAR; PG8_SCHED;
;             PG8_LDA(At, 0, 1); PG8_STAGE(PG8_SB(0, 0), b2, voffB); PG8_STAGE(PG8_SB(0, 1), b2 + hstepB, voffB); PG8_STAGE(PG8_SA(0, 0), a2, voffA);
;             PG8_WAIT_V(8); PG8_WAIT_L(0); PG8_BAR; PG8_MMA(1, 0, At, B0); PG8_MMA(1, 1, At, B1); PG8_BAR; PG8_SCHED;
.LBB0_137:
	s_add_u32 s28, s26, 0xfff80080
	s_addc_u32 s29, s27, -1
	s_add_i32 s60, 0, 0x10000
	s_cmp_eq_u32 s59, 28
	s_cselect_b32 s41, s21, s29
	s_cselect_b32 s40, s55, s28
	s_cselect_b32 s29, s19, s58
	s_cselect_b32 s28, s56, s57
	s_add_i32 s62, 0, 0x14000
	v_add_u32_e32 v154, s60, v159
	v_add_u32_e32 v174, s62, v159
	ds_read_b128 v[142:145], v154
	ds_read_b128 v[146:149], v154 offset:1024
	ds_read_b128 v[150:153], v154 offset:2048
	ds_read_b128 v[154:157], v154 offset:3072
	ds_read_b128 v[162:165], v174
	ds_read_b128 v[166:169], v174 offset:1024
	ds_read_b128 v[170:173], v174 offset:2048
	ds_read_b128 v[174:177], v174 offset:3072
	v_lshl_add_u64 v[224:225], s[26:27], 0, v[138:139]
	s_add_i32 m0, s46, 0xc000
	ds_read_b128 v[178:181], v161
	ds_read_b128 v[182:185], v161 offset:1024
	ds_read_b128 v[186:189], v161 offset:2048
	ds_read_b128 v[190:193], v161 offset:3072
	ds_read_b128 v[194:197], v161 offset:4096
	ds_read_b128 v[212:215], v161 offset:5120
	ds_read_b128 v[216:219], v161 offset:6144
	ds_read_b128 v[220:223], v161 offset:7168
	global_load_lds_dwordx4 v[224:225], off
	v_lshl_add_u64 v[224:225], s[26:27], 0, v[140:141]
	s_add_i32 m0, s46, 0xe000
	s_nop 0
	global_load_lds_dwordx4 v[224:225], off
	s_waitcnt vmcnt(8)
	s_waitcnt lgkmcnt(0)
	s_barrier
	s_waitcnt lgkmcnt(0)
	v_mfma_f32_16x16x32_bf16 v[130:133], v[142:145], v[178:181], v[130:133]
	v_mfma_f32_16x16x32_bf16 v[122:125], v[150:153], v[178:181], v[122:125]
	v_mfma_f32_16x16x32_bf16 v[114:117], v[142:145], v[186:189], v[114:117]
	v_mfma_f32_16x16x32_bf16 v[106:109], v[150:153], v[186:189], v[106:109]
	v_mfma_f32_16x16x32_bf16 v[98:101], v[142:145], v[194:197], v[98:101]
	v_mfma_f32_16x16x32_bf16 v[90:93], v[150:153], v[194:197], v[90:93]
	v_mfma_f32_16x16x32_bf16 v[82:85], v[142:145], v[216:219], v[82:85]
	v_mfma_f32_16x16x32_bf16 v[74:77], v[150:153], v[216:219], v[74:77]
	v_mfma_f32_16x16x32_bf16 v[130:133], v[146:149], v[182:185], v[130:133]
	v_mfma_f32_16x16x32_bf16 v[122:125], v[154:157], v[182:185], v[122:125]
	v_mfma_f32_16x16x32_bf16 v[114:117], v[146:149], v[190:193], v[114:117]
	v_mfma_f32_16x16x32_bf16 v[106:109], v[154:157], v[190:193], v[106:109]
	v_mfma_f32_16x16x32_bf16 v[98:101], v[146:149], v[212:215], v[98:101]
	v_mfma_f32_16x16x32_bf16 v[90:93], v[154:157], v[212:215], v[90:93]
	v_mfma_f32_16x16x32_bf16 v[82:85], v[146:149], v[220:223], v[82:85]
	v_mfma_f32_16x16x32_bf16 v[74:77], v[154:157], v[220:223], v[74:77]
	v_mfma_f32_16x16x32_bf16 v[126:129], v[162:165], v[178:181], v[126:129]
	v_mfma_f32_16x16x32_bf16 v[118:121], v[170:173], v[178:181], v[118:121]
	v_mfma_f32_16x16x32_bf16 v[110:113], v[162:165], v[186:189], v[110:113]
	v_mfma_f32_16x16x32_bf16 v[102:105], v[170:173], v[186:189], v[102:105]
	v_mfma_f32_16x16x32_bf16 v[94:97], v[162:165], v[194:197], v[94:97]
	v_mfma_f32_16x16x32_bf16 v[86:89], v[170:173], v[194:197], v[86:89]
	v_mfma_f32_16x16x32_bf16 v[78:81], v[162:165], v[216:219], v[78:81]
	v_mfma_f32_16x16x32_bf16 v[70:73], v[170:173], v[216:219], v[70:73]
	v_mfma_f32_16x16x32_bf16 v[126:129], v[166:169], v[182:185], v[126:129]
	v_mfma_f32_16x16x32_bf16 v[118:121], v[174:177], v[182:185], v[118:121]
	v_mfma_f32_16x16x32_bf16 v[110:113], v[166:169], v[190:193], v[110:113]
	v_mfma_f32_16x16x32_bf16 v[102:105], v[174:177], v[190:193], v[102:105]
	v_mfma_f32_16x16x32_bf16 v[94:97], v[166:169], v[212:215], v[94:97]
	v_mfma_f32_16x16x32_bf16 v[86:89], v[174:177], v[212:215], v[86:89]
	v_mfma_f32_16x16x32_bf16 v[78:81], v[166:169], v[220:223], v[78:81]
	v_mfma_f32_16x16x32_bf16 v[70:73], v[174:177], v[220:223], v[70:73]
	s_barrier
	s_add_i32 s60, s60, s45
	v_lshl_add_u64 v[224:225], s[28:29], 0, v[4:5]
	s_mov_b32 m0, s60
	ds_read_b128 v[178:181], v161 offset:16384
	ds_read_b128 v[182:185], v161 offset:17408
	ds_read_b128 v[186:189], v161 offset:18432
	ds_read_b128 v[190:193], v161 offset:19456
	ds_read_b128 v[194:197], v161 offset:20480
	ds_read_b128 v[212:215], v161 offset:21504
	ds_read_b128 v[216:219], v161 offset:22528
	ds_read_b128 v[220:223], v161 offset:23552
	global_load_lds_dwordx4 v[224:225], off
	s_add_i32 m0, s60, 0x2000
	s_add_u32 s60, s28, 0x80000
	v_lshl_add_u64 v[226:227], s[28:29], 0, v[2:3]
	s_addc_u32 s61, s29, 0
	s_add_i32 s62, s62, s45
	global_load_lds_dwordx4 v[226:227], off
	v_lshl_add_u64 v[228:229], s[60:61], 0, v[4:5]
	s_mov_b32 m0, s62
	v_lshl_add_u64 v[230:231], s[40:41], 0, v[134:135]
	global_load_lds_dwordx4 v[228:229], off
	v_lshl_add_u64 v[228:229], s[60:61], 0, v[2:3]
	s_add_i32 m0, s62, 0x2000
	s_nop 0
	global_load_lds_dwordx4 v[228:229], off
	v_lshl_add_u64 v[228:229], s[40:41], 0, v[136:137]
	s_mov_b32 m0, s46
	s_nop 0
	global_load_lds_dwordx4 v[228:229], off
	s_mov_b32 m0, s47
	s_nop 0
	global_load_lds_dwordx4 v[230:231], off
	s_waitcnt vmcnt(8)
	s_waitcnt lgkmcnt(0)
	s_barrier
; #define PG8_STAGE(bufoff, gbase, voff) do { _Pragma("unroll") for (int _i = 0; _i < 2; ++_i) \
;         __builtin_amdgcn_global_load_lds((const unsigned*)((const char*)(gbase) + (voff)[_i]), (LAS unsigned*)(lds + (bufoff) + ldsw + _i * 8192), 16, 0, 0); } while (0)
; #define PG8_LDA(dst, b, h) do { _Pragma("unroll") for (int m = 0; m < 4; ++m) _Pragma("unroll") for (int k = 0; k < 2; ++k) dst[m][k] = *(const LAS bf16x8*)(lds + PG8_SA(b, h) + aoff + m * 2048 + k * 1024); } while (0)
; #define PG8_LDB(dst, b, h) do { _Pragma("unroll") for (int n = 0; n < 2; ++n) _Pragma("unroll") for (int k = 0; k < 2; ++k) dst[n][k] = *(const LAS bf16x8*)(lds + PG8_SB(b, h) + boff + n * 2048 + k * 1024); } while (0)
; #define PG8_MMA(ai, bj, At, Bt) do { __builtin_amdgcn_s_setprio(1); _Pragma("unroll") for (int m = 0; m < 4; ++m) _Pragma("unroll") for (int n = 0; n < 2; ++n) _Pragma("unroll") for (int k = 0; k < 2; ++k) \
;         acc[ai][bj][m][n] = __builtin_amdgcn_mfma_f32_16x16x32_bf16(Bt[n][k], At[m][k], acc[ai][bj][m][n], 0, 0, 0); __builtin_amdgcn_s_setprio(0); } while (0)
; #define PG8_WAIT_V(n) asm volatile("s_waitcnt vmcnt(" #n ")" ::: "memory")
; #define PG8_WAIT_L(n) asm volatile("s_waitcnt lgkmcnt(" #n ")" ::: "memory")
; #define PG8_BAR __builtin_amdgcn_s_barrier()
; #define PG8_SCHED __builtin_amdgcn_sched_barrier(0)
; template <class Epi, class Sched>
; __device__ __forceinline__ void gemm_phase(LAS unsigned char* lds, const Gemm g, const Sched& S, const Epi& E) {
;     ...
;             PG8_WAIT_V(8); PG8_WAIT_L(0); PG8_BAR; PG8_MMA(1, 0, At, B0); PG8_MMA(1, 1, At, B1); PG8_BAR; PG8_SCHED;
;             PG8_LDB(B0, 1, 0); PG8_LDB(B1, 1, 1); PG8_SCHED; PG8_LDA(At, 1, 0); PG8_STAGE(PG8_SA(0, 1), a2 + hstepA, voffA);
;             PG8_WAIT_V(8); PG8_WAIT_L(0); PG8_BAR; PG8_MMA(0, 0, At, B0); PG8_MMA(0, 1, At, B1); PG8_BAR; PG8_SCHED;
	s_waitcnt lgkmcnt(0)
	v_mfma_f32_16x16x32_bf16 v[66:69], v[142:145], v[178:181], v[66:69]
	v_mfma_f32_16x16x32_bf16 v[58:61], v[150:153], v[178:181], v[58:61]
	v_mfma_f32_16x16x32_bf16 v[50:53], v[142:145], v[186:189], v[50:53]
	v_mfma_f32_16x16x32_bf16 v[42:45], v[150:153], v[186:189], v[42:45]
	v_mfma_f32_16x16x32_bf16 v[34:37], v[142:145], v[194:197], v[34:37]
	v_mfma_f32_16x16x32_bf16 v[26:29], v[150:153], v[194:197], v[26:29]
	v_mfma_f32_16x16x32_bf16 v[18:21], v[142:145], v[216:219], v[18:21]
	v_mfma_f32_16x16x32_bf16 v[10:13], v[150:153], v[216:219], v[10:13]
	v_mfma_f32_16x16x32_bf16 v[66:69], v[146:149], v[182:185], v[66:69]
	v_mfma_f32_16x16x32_bf16 v[58:61], v[154:157], v[182:185], v[58:61]
	v_mfma_f32_16x16x32_bf16 v[50:53], v[146:149], v[190:193], v[50:53]
	v_mfma_f32_16x16x32_bf16 v[42:45], v[154:157], v[190:193], v[42:45]
	v_mfma_f32_16x16x32_bf16 v[34:37], v[146:149], v[212:215], v[34:37]
	v_mfma_f32_16x16x32_bf16 v[26:29], v[154:157], v[212:215], v[26:29]
	v_mfma_f32_16x16x32_bf16 v[18:21], v[146:149], v[220:223], v[18:21]
	v_mfma_f32_16x16x32_bf16 v[10:13], v[154:157], v[220:223], v[10:13]
	v_mfma_f32_16x16x32_bf16 v[62:65], v[162:165], v[178:181], v[62:65]
	v_mfma_f32_16x16x32_bf16 v[54:57], v[170:173], v[178:181], v[54:57]
	v_mfma_f32_16x16x32_bf16 v[46:49], v[162:165], v[186:189], v[46:49]
	v_mfma_f32_16x16x32_bf16 v[38:41], v[170:173], v[186:189], v[38:41]
	v_mfma_f32_16x16x32_bf16 v[30:33], v[162:165], v[194:197], v[30:33]
	v_mfma_f32_16x16x32_bf16 v[22:25], v[170:173], v[194:197], v[22:25]
	v_mfma_f32_16x16x32_bf16 v[14:17], v[162:165], v[216:219], v[14:17]
	v_mfma_f32_16x16x32_bf16 v[6:9], v[170:173], v[216:219], v[6:9]
	v_mfma_f32_16x16x32_bf16 v[62:65], v[166:169], v[182:185], v[62:65]
	v_mfma_f32_16x16x32_bf16 v[54:57], v[174:177], v[182:185], v[54:57]
	v_mfma_f32_16x16x32_bf16 v[46:49], v[166:169], v[190:193], v[46:49]
	v_mfma_f32_16x16x32_bf16 v[38:41], v[174:177], v[190:193], v[38:41]
	v_mfma_f32_16x16x32_bf16 v[30:33], v[166:169], v[212:215], v[30:33]
	v_mfma_f32_16x16x32_bf16 v[22:25], v[174:177], v[212:215], v[22:25]
	v_mfma_f32_16x16x32_bf16 v[14:17], v[166:169], v[220:223], v[14:17]
	v_mfma_f32_16x16x32_bf16 v[6:9], v[174:177], v[220:223], v[6:9]
	s_barrier
	s_add_i32 s60, 0, 0x18000
	s_add_i32 s61, 0, 0x1c000
	v_add_u32_e32 v154, s60, v159
	v_add_u32_e32 v174, s61, v159
	ds_read_b128 v[142:145], v154
	ds_read_b128 v[146:149], v154 offset:1024
	ds_read_b128 v[150:153], v154 offset:2048
	ds_read_b128 v[154:157], v154 offset:3072
	ds_read_b128 v[162:165], v174
	ds_read_b128 v[166:169], v174 offset:1024
	ds_read_b128 v[170:173], v174 offset:2048
	ds_read_b128 v[174:177], v174 offset:3072
	s_add_u32 s40, s40, 0x80000
	s_addc_u32 s41, s41, 0
	s_mov_b32 m0, s48
	v_lshl_add_u64 v[236:237], s[40:41], 0, v[136:137]
	ds_read_b128 v[178:181], v161 offset:32768
	ds_read_b128 v[182:185], v161 offset:33792
	ds_read_b128 v[186:189], v161 offset:34816
	ds_read_b128 v[190:193], v161 offset:35840
	ds_read_b128 v[194:197], v161 offset:36864
	ds_read_b128 v[212:215], v161 offset:37888
	ds_read_b128 v[216:219], v161 offset:38912
	ds_read_b128 v[220:223], v161 offset:39936
	global_load_lds_dwordx4 v[236:237], off
	v_lshl_add_u64 v[236:237], s[40:41], 0, v[134:135]
	s_mov_b32 m0, s49
	s_nop 0
	global_load_lds_dwordx4 v[236:237], off
	s_waitcnt vmcnt(8)
	s_waitcnt lgkmcnt(0)
	s_barrier
	s_waitcnt lgkmcnt(0)
	v_mfma_f32_16x16x32_bf16 v[130:133], v[142:145], v[178:181], v[130:133]
	v_mfma_f32_16x16x32_bf16 v[122:125], v[150:153], v[178:181], v[122:125]
	v_mfma_f32_16x16x32_bf16 v[114:117], v[142:145], v[186:189], v[114:117]
	v_mfma_f32_16x16x32_bf16 v[106:109], v[150:153], v[186:189], v[106:109]
	v_mfma_f32_16x16x32_bf16 v[98:101], v[142:145], v[194:197], v[98:101]
	v_mfma_f32_16x16x32_bf16 v[90:93], v[150:153], v[194:197], v[90:93]
	v_mfma_f32_16x16x32_bf16 v[82:85], v[142:145], v[216:219], v[82:85]
	v_mfma_f32_16x16x32_bf16 v[74:77], v[150:153], v[216:219], v[74:77]
	v_mfma_f32_16x16x32_bf16 v[130:133], v[146:149], v[182:185], v[130:133]
	v_mfma_f32_16x16x32_bf16 v[122:125], v[154:157], v[182:185], v[122:125]
	v_mfma_f32_16x16x32_bf16 v[114:117], v[146:149], v[190:193], v[114:117]
	v_mfma_f32_16x16x32_bf16 v[106:109], v[154:157], v[190:193], v[106:109]
	v_mfma_f32_16x16x32_bf16 v[98:101], v[146:149], v[212:215], v[98:101]
	v_mfma_f32_16x16x32_bf16 v[90:93], v[154:157], v[212:215], v[90:93]
	v_mfma_f32_16x16x32_bf16 v[82:85], v[146:149], v[220:223], v[82:85]
	v_mfma_f32_16x16x32_bf16 v[74:77], v[154:157], v[220:223], v[74:77]
	v_mfma_f32_16x16x32_bf16 v[126:129], v[162:165], v[178:181], v[126:129]
	v_mfma_f32_16x16x32_bf16 v[118:121], v[170:173], v[178:181], v[118:121]
	v_mfma_f32_16x16x32_bf16 v[110:113], v[162:165], v[186:189], v[110:113]
	v_mfma_f32_16x16x32_bf16 v[102:105], v[170:173], v[186:189], v[102:105]
	v_mfma_f32_16x16x32_bf16 v[94:97], v[162:165], v[194:197], v[94:97]
	v_mfma_f32_16x16x32_bf16 v[86:89], v[170:173], v[194:197], v[86:89]
	v_mfma_f32_16x16x32_bf16 v[78:81], v[162:165], v[216:219], v[78:81]
	v_mfma_f32_16x16x32_bf16 v[70:73], v[170:173], v[216:219], v[70:73]
	v_mfma_f32_16x16x32_bf16 v[126:129], v[166:169], v[182:185], v[126:129]
	v_mfma_f32_16x16x32_bf16 v[118:121], v[174:177], v[182:185], v[118:121]
	v_mfma_f32_16x16x32_bf16 v[110:113], v[166:169], v[190:193], v[110:113]
	v_mfma_f32_16x16x32_bf16 v[102:105], v[174:177], v[190:193], v[102:105]
	v_mfma_f32_16x16x32_bf16 v[94:97], v[166:169], v[212:215], v[94:97]
	v_mfma_f32_16x16x32_bf16 v[86:89], v[174:177], v[212:215], v[86:89]
	v_mfma_f32_16x16x32_bf16 v[78:81], v[166:169], v[220:223], v[78:81]
	v_mfma_f32_16x16x32_bf16 v[70:73], v[174:177], v[220:223], v[70:73]
	s_barrier
; #define PG8_STAGE(bufoff, gbase, voff) do { _Pragma("unroll") for (int _i = 0; _i < 2; ++_i) \
;         __builtin_amdgcn_global_load_lds((const unsigned*)((const char*)(gbase) + (voff)[_i]), (LAS unsigned*)(lds + (bufoff) + ldsw + _i * 8192), 16, 0, 0); } while (0)
; #define PG8_LDA(dst, b, h) do { _Pragma("unroll") for (int m = 0; m < 4; ++m) _Pragma("unroll") for (int k = 0; k < 2; ++k) dst[m][k] = *(const LAS bf16x8*)(lds + PG8_SA(b, h) + aoff + m * 2048 + k * 1024); } while (0)
; #define PG8_MMA(ai, bj, At, Bt) do { __builtin_amdgcn_s_setprio(1); _Pragma("unroll") for (int m = 0; m < 4; ++m) _Pragma("unroll") for (int n = 0; n < 2; ++n) _Pragma("unroll") for (int k = 0; k < 2; ++k) \
;         acc[ai][bj][m][n] = __builtin_amdgcn_mfma_f32_16x16x32_bf16(Bt[n][k], At[m][k], acc[ai][bj][m][n], 0, 0, 0); __builtin_amdgcn_s_setprio(0); } while (0)
; #define PG8_WAIT_V(n) asm volatile("s_waitcnt vmcnt(" #n ")" ::: "memory")
; #define PG8_WAIT_L(n) asm volatile("s_waitcnt lgkmcnt(" #n ")" ::: "memory")
; #define PG8_BAR __builtin_amdgcn_s_barrier()
; #define PG8_SCHED __builtin_amdgcn_sched_barrier(0)
; template <class Epi, class Sched>
; __device__ __forceinline__ void gemm_phase(LAS unsigned char* lds, const Gemm g, const Sched& S, const Epi& E) {
;     ...
;             PG8_LDA(At, 1, 1); PG8_STAGE(PG8_SB(1, 0), b3, voffB); PG8_STAGE(PG8_SB(1, 1), b3 + hstepB, voffB); PG8_STAGE(PG8_SA(1, 0), a3, voffA);
;             PG8_WAIT_V(8); PG8_WAIT_L(0); PG8_BAR; PG8_MMA(1, 0, At, B0); PG8_MMA(1, 1, At, B1); PG8_BAR; PG8_SCHED;
;         }
;         if (wr == 0) PG8_BAR;
	s_add_i32 s40, s60, s45
	v_lshl_add_u64 v[224:225], v[224:225], 0, s[36:37]
	s_mov_b32 m0, s40
	ds_read_b128 v[178:181], v161 offset:49152
	ds_read_b128 v[182:185], v161 offset:50176
	ds_read_b128 v[186:189], v161 offset:51200
	ds_read_b128 v[190:193], v161 offset:52224
	ds_read_b128 v[194:197], v161 offset:53248
	ds_read_b128 v[212:215], v161 offset:54272
	ds_read_b128 v[216:219], v161 offset:55296
	ds_read_b128 v[220:223], v161 offset:56320
	global_load_lds_dwordx4 v[224:225], off
	s_add_i32 m0, s40, 0x2000
	s_add_u32 s28, s28, 0x80080
	v_lshl_add_u64 v[224:225], v[226:227], 0, s[36:37]
	s_addc_u32 s29, s29, 0
	s_add_i32 s40, s61, s45
	global_load_lds_dwordx4 v[224:225], off
	v_lshl_add_u64 v[224:225], s[28:29], 0, v[4:5]
	s_mov_b32 m0, s40
	s_nop 0
	global_load_lds_dwordx4 v[224:225], off
	v_lshl_add_u64 v[224:225], s[28:29], 0, v[2:3]
	s_add_i32 m0, s40, 0x2000
	s_nop 0
	global_load_lds_dwordx4 v[224:225], off
	v_lshl_add_u64 v[224:225], v[228:229], 0, s[36:37]
	s_mov_b32 m0, s50
	s_nop 0
	global_load_lds_dwordx4 v[224:225], off
	v_lshl_add_u64 v[224:225], v[230:231], 0, s[36:37]
	s_mov_b32 m0, s51
	s_nop 0
	global_load_lds_dwordx4 v[224:225], off
	s_waitcnt vmcnt(8)
	s_waitcnt lgkmcnt(0)
	s_barrier
	s_waitcnt lgkmcnt(0)
	v_mfma_f32_16x16x32_bf16 v[66:69], v[142:145], v[178:181], v[66:69]
	v_mfma_f32_16x16x32_bf16 v[58:61], v[150:153], v[178:181], v[58:61]
	v_mfma_f32_16x16x32_bf16 v[50:53], v[142:145], v[186:189], v[50:53]
	v_mfma_f32_16x16x32_bf16 v[42:45], v[150:153], v[186:189], v[42:45]
	v_mfma_f32_16x16x32_bf16 v[34:37], v[142:145], v[194:197], v[34:37]
	v_mfma_f32_16x16x32_bf16 v[26:29], v[150:153], v[194:197], v[26:29]
	v_mfma_f32_16x16x32_bf16 v[18:21], v[142:145], v[216:219], v[18:21]
	v_mfma_f32_16x16x32_bf16 v[10:13], v[150:153], v[216:219], v[10:13]
	v_mfma_f32_16x16x32_bf16 v[66:69], v[146:149], v[182:185], v[66:69]
	v_mfma_f32_16x16x32_bf16 v[58:61], v[154:157], v[182:185], v[58:61]
	v_mfma_f32_16x16x32_bf16 v[50:53], v[146:149], v[190:193], v[50:53]
	v_mfma_f32_16x16x32_bf16 v[42:45], v[154:157], v[190:193], v[42:45]
	v_mfma_f32_16x16x32_bf16 v[34:37], v[146:149], v[212:215], v[34:37]
	v_mfma_f32_16x16x32_bf16 v[26:29], v[154:157], v[212:215], v[26:29]
	v_mfma_f32_16x16x32_bf16 v[18:21], v[146:149], v[220:223], v[18:21]
	v_mfma_f32_16x16x32_bf16 v[10:13], v[154:157], v[220:223], v[10:13]
	v_mfma_f32_16x16x32_bf16 v[62:65], v[162:165], v[178:181], v[62:65]
	v_mfma_f32_16x16x32_bf16 v[54:57], v[170:173], v[178:181], v[54:57]
	v_mfma_f32_16x16x32_bf16 v[46:49], v[162:165], v[186:189], v[46:49]
	v_mfma_f32_16x16x32_bf16 v[38:41], v[170:173], v[186:189], v[38:41]
	v_mfma_f32_16x16x32_bf16 v[30:33], v[162:165], v[194:197], v[30:33]
	v_mfma_f32_16x16x32_bf16 v[22:25], v[170:173], v[194:197], v[22:25]
	v_mfma_f32_16x16x32_bf16 v[14:17], v[162:165], v[216:219], v[14:17]
	v_mfma_f32_16x16x32_bf16 v[6:9], v[170:173], v[216:219], v[6:9]
	v_mfma_f32_16x16x32_bf16 v[62:65], v[166:169], v[182:185], v[62:65]
	v_mfma_f32_16x16x32_bf16 v[54:57], v[174:177], v[182:185], v[54:57]
	v_mfma_f32_16x16x32_bf16 v[46:49], v[166:169], v[190:193], v[46:49]
	v_mfma_f32_16x16x32_bf16 v[38:41], v[174:177], v[190:193], v[38:41]
	v_mfma_f32_16x16x32_bf16 v[30:33], v[166:169], v[212:215], v[30:33]
	v_mfma_f32_16x16x32_bf16 v[22:25], v[174:177], v[212:215], v[22:25]
	v_mfma_f32_16x16x32_bf16 v[14:17], v[166:169], v[220:223], v[14:17]
	v_mfma_f32_16x16x32_bf16 v[6:9], v[174:177], v[220:223], v[6:9]
	s_barrier
	s_add_i32 s59, s59, 2
	s_add_u32 s26, s26, 0x100
	s_addc_u32 s27, s27, 0
	s_add_u32 s57, s57, 0x100
	s_addc_u32 s58, s58, 0
	s_cmp_gt_u32 s59, 29
	s_cbranch_scc0 .LBB0_137
	s_and_b64 vcc, exec, s[16:17]
	s_cbranch_vccz .LBB0_140
	s_barrier

; #define PG8_WAIT_V(n) asm volatile("s_waitcnt vmcnt(" #n ")" ::: "memory")
; #define PG8_BAR __builtin_amdgcn_s_barrier()
; template <class Epi, class Sched>
; __device__ __forceinline__ void gemm_phase(LAS unsigned char* lds, const Gemm g, const Sched& S, const Epi& E) {
;     ...
;     PG8_WAIT_V(0);
;     PG8_BAR;
.LBB0_143:
	s_setprio 0
	s_waitcnt vmcnt(0)
	s_barrier

; #define ENDP(k) do { if ((k) + 1 < hi) { _Pragma("nounroll") for (int rb_ = 0; rb_ < DUPN(7); ++rb_) { XcdBarrier bb_ = bar; asm volatile("" : "+s"(bb_.bar)); xcd_barrier(bb_); } } } while (0)
; __device__ __forceinline__ void xcd_barrier(const XcdBarrier& b) {
;     asm volatile("s_waitcnt vmcnt(0)" ::: "memory");
;     __syncthreads();
;     if (threadIdx.x == 0) {
;         unsigned* bar = b.bar;
;         __builtin_amdgcn_s_waitcnt(0);
;         unsigned nloc = b.st[0], nx = b.st[1];
;         if (nloc == 0u) { xcd_barrier_complete(bar, b.x, nloc, nx); b.st[0] = nloc; b.st[1] = nx; }
;         const unsigned k1 = b.st[2] + 1u, rank = b.st[3]; b.st[2] = k1;
;         (void)__hip_atomic_fetch_add(&bar[XB_XSUB(b.x)], 1u, __ATOMIC_RELAXED, __HIP_MEMORY_SCOPE_AGENT);
; __global__ void __launch_bounds__(512, 2) mk_fwd(Args args) {
;     ...
;                 ENDP(pf);
.LBB0_218:
	v_readlane_b32 s8, v253, 1
	s_add_i32 s34, s66, 1
	v_readlane_b32 s11, v253, 4
	s_cmp_ge_i32 s34, s11
	v_readlane_b32 s9, v253, 2
	v_readlane_b32 s10, v253, 3
	s_cbranch_scc1 .LBB0_231
	s_setprio 0
	s_mov_b64 s[10:11], s[96:97]
	s_waitcnt vmcnt(0)
	s_barrier
	s_mov_b64 s[8:9], exec
	v_readlane_b32 s12, v254, 21
	v_readlane_b32 s13, v254, 22
	s_and_b64 s[12:13], s[8:9], s[12:13]
	v_readlane_b32 s70, v254, 23
	v_readlane_b32 s71, v254, 24
	s_mov_b64 exec, s[12:13]
	s_cbranch_execz .LBB0_260
	v_mov_b32_e32 v2, s93
	s_waitcnt vmcnt(0) expcnt(0) lgkmcnt(0)
	ds_read_b32 v4, v2
	ds_read_b32 v2, v2 offset:4
	s_waitcnt lgkmcnt(1)
	v_cmp_ne_u32_e32 vcc, 0, v4
	s_cbranch_vccnz .LBB0_235
	s_load_dwordx2 s[16:17], s[94:95], 0x4
	s_add_u32 s12, s10, 0x1000
	s_addc_u32 s13, s11, 0
	s_add_u32 s14, s10, 0x1100
	s_addc_u32 s15, s11, 0
	s_waitcnt lgkmcnt(0)
	s_mul_i32 s46, s16, s92
	s_add_u32 s16, s10, 0x1200
	s_mul_i32 s46, s46, s17
	s_addc_u32 s17, s11, 0
	s_add_u32 s18, s10, 0x1300
	s_addc_u32 s19, s11, 0
	s_mov_b32 s47, 1
	s_mov_b64 s[20:21], 0
	s_branch .LBB0_224

; #define PG8_STAGE(bufoff, gbase, voff) do { _Pragma("unroll") for (int _i = 0; _i < 2; ++_i) \
;         __builtin_amdgcn_global_load_lds((const unsigned*)((const char*)(gbase) + (voff)[_i]), (LAS unsigned*)(lds + (bufoff) + ldsw + _i * 8192), 16, 0, 0); } while (0)
; #define PG8_BAR __builtin_amdgcn_s_barrier()
; template <class Epi, class Sched>
; __device__ __forceinline__ void gemm_phase(LAS unsigned char* lds, const Gemm g, const Sched& S, const Epi& E) {
;     ...
;     unsigned voffA[2], voffB[2];
; #pragma unroll
;     for (int i = 0; i < 2; ++i) { int R, C; stage_rc(tid * 16 + i * 8192, R, C); const int Rb = Epi::PERM ? ((R & ~31) + perm32(R & 31)) : R;
;         voffA[i] = (unsigned)(R * g.lda + C) * 2u; voffB[i] = (unsigned)(Rb * g.ldb + C) * 2u; }
;     const size_t kstep = (size_t)(BK * 2);
;     const size_t hstepA = (size_t)HALF * g.lda * 2, hstepB = (size_t)HALF * g.ldb * 2;
;     const size_t tstepA = 2 * hstepA, tstepB = 2 * hstepB;
;     const unsigned ldsw = (unsigned)wid * 1024u;
;     const int aoff = lds_byte(wr * 64 + fr, fq * 8), boff = lds_byte(wc * 32 + fr, fq * 8);
;     ...
;     Unit cur, nxt; int ui = 0;
;     if (!S.next(0, cur)) return;
;     f32x4 acc[2][2][4][2];
; #pragma unroll
;     for (int a = 0; a < 2; ++a)
; #pragma unroll
;         for (int b = 0; b < 2; ++b)
; #pragma unroll
;             for (int m = 0; m < 4; ++m)
; #pragma unroll
;                 for (int n = 0; n < 2; ++n) acc[a][b][m][n] = (f32x4){0.f, 0.f, 0.f, 0.f};
;     bf16x8 At[4][2], B0[2][2], B1[2][2];
;     const char* cA = (const char*)g.A + (size_t)cur.pm * tstepA + (size_t)cur.ka * 2; const char* cB = (const char*)g.Bt + (size_t)cur.pn * tstepB;
;     S.a_ready(cur);
;     PG8_STAGE(PG8_SB(0, 0), cB, voffB); PG8_STAGE(PG8_SB(0, 1), cB + hstepB, voffB); PG8_STAGE(PG8_SA(0, 0), cA, voffA); PG8_STAGE(PG8_SA(0, 1), cA + hstepA, voffA);
;     if (wr == 1) PG8_BAR;
.LBB0_264:
	v_readlane_b32 s12, v253, 41
	v_mov_b32_e32 v143, v0
	v_readlane_b32 s13, v253, 42
	s_andn2_b64 vcc, exec, s[12:13]
	v_readfirstlane_b32 s45, v143
	s_cbranch_vccnz .LBB0_424
	v_lshlrev_b32_e32 v3, 4, v143
	v_add_u32_e32 v2, 0x2000, v3
	v_ashrrev_i32_e32 v4, 31, v2
	v_lshrrev_b32_e32 v4, 22, v4
	v_add_u32_e32 v4, v2, v4
	s_waitcnt vmcnt(0)
	v_ashrrev_i32_e32 v6, 10, v4
	v_mul_i32_i24_e32 v4, 0x400, v6
	v_sub_u32_e32 v2, v2, v4
	v_lshrrev_b32_e32 v4, 4, v2
	v_bitop3_b32 v2, v4, v2, 32 bitop3:0x6c
	v_ashrrev_i32_e32 v4, 31, v2
	v_lshrrev_b32_e32 v4, 26, v4
	s_load_dwordx2 s[12:13], s[10:11], 0x98
	s_load_dwordx2 s[14:15], s[4:5], 0x0
	v_add_u32_e32 v4, v2, v4
	v_ashrrev_i32_e32 v7, 6, v4
	v_and_b32_e32 v4, 0xc0, v4
	s_ashr_i32 s44, s45, 6
	v_sub_u32_e32 v2, v2, v4
	v_bfe_i32 v4, v143, 27, 1
	s_ashr_i32 s47, s45, 8
	s_lshl_b32 s11, s44, 10
	v_lshrrev_b32_e32 v4, 22, v4
	s_waitcnt lgkmcnt(0)
	s_add_u32 s34, s12, 0xd000000
	v_add_u32_e32 v4, v3, v4
	s_addc_u32 s42, s13, 0
	s_mul_i32 s65, s65, 0x1580000
	v_and_b32_e32 v4, 0xfffffc00, v4
	s_add_u32 s4, s12, s65
	v_lshlrev_b32_e32 v8, 3, v6
	v_sub_u32_e32 v3, v3, v4
	s_addc_u32 s5, s13, 0
	v_and_b32_e32 v8, 0x1fffff0, v8
	v_lshrrev_b32_e32 v4, 4, v3
	s_waitcnt vmcnt(4)
	v_ashrrev_i32_e32 v11, 31, v143
	s_add_u32 s43, s4, 0x36c00000
	v_add_u32_e32 v8, v7, v8
	s_movk_i32 s4, 0x1580
	v_bitop3_b32 v3, v4, v3, 32 bitop3:0x6c
	v_lshrrev_b32_e32 v11, 26, v11
	v_mul_lo_u32 v9, v8, s4
	v_lshlrev_b32_e32 v8, 5, v6
	v_ashrrev_i32_e32 v4, 31, v3
	v_add_u32_e32 v11, v143, v11
	v_and_b32_e32 v8, 32, v8
	v_ashrrev_i16_sdwa v2, v232, sext(v2) dst_sel:DWORD dst_unused:UNUSED_PAD src0_sel:DWORD src1_sel:BYTE_0
	v_lshrrev_b32_e32 v4, 26, v4
	v_ashrrev_i32_e32 v11, 6, v11
	v_or_b32_e32 v10, v9, v8
	v_bfe_i32 v9, v2, 0, 16
	v_add_u32_e32 v4, v3, v4
	v_lshlrev_b32_e32 v12, 3, v11
	v_add_lshl_u32 v2, v10, v9, 1
	v_ashrrev_i32_e32 v10, 6, v4
	v_and_b32_e32 v12, 0x1fffff0, v12
	s_addc_u32 s49, s5, 0
	v_add_u32_e32 v12, v10, v12
	v_readlane_b32 s5, v253, 61
	v_mul_lo_u32 v13, v12, s4
	s_mul_i32 s4, s5, 0x2b0000
	v_and_b32_e32 v4, 0xc0, v4
	s_add_u32 s20, s34, s4
	s_mul_hi_i32 s4, s5, 0x2b0000
	v_readlane_b32 s5, v254, 13
	v_lshlrev_b32_e32 v12, 5, v11
	v_sub_u32_e32 v3, v3, v4
	s_addc_u32 s21, s42, s4
	s_mul_i32 s4, s5, 0x2b0000
	v_and_b32_e32 v12, 32, v12
	v_ashrrev_i16_sdwa v3, v232, sext(v3) dst_sel:DWORD dst_unused:UNUSED_PAD src0_sel:DWORD src1_sel:BYTE_0
	s_add_u32 s24, s43, s4
	s_mul_hi_i32 s4, s5, 0x2b0000
	v_or_b32_e32 v14, v13, v12
	v_bfe_i32 v13, v3, 0, 16
	s_addc_u32 s25, s49, s4
	s_add_i32 s50, s11, 0
	v_add_lshl_u32 v4, v14, v13, 1
	s_add_i32 m0, s50, 0x10000
	s_nop 0
	global_load_lds_dwordx4 v4, s[24:25]
	s_add_i32 m0, s50, 0x12000
	s_add_u32 s4, s24, 0x158000
	global_load_lds_dwordx4 v2, s[24:25]
	s_addc_u32 s5, s25, 0
	s_add_i32 m0, s50, 0x14000
	s_add_i32 s51, s50, 0x2000
	global_load_lds_dwordx4 v4, s[4:5]
	s_add_i32 m0, s50, 0x16000
	s_nop 0
	global_load_lds_dwordx4 v2, s[4:5]
	s_mov_b32 m0, s50
	s_add_u32 s4, s20, 0x158000
	global_load_lds_dwordx4 v4, s[20:21]
	s_mov_b32 m0, s51
	s_addc_u32 s5, s21, 0
	s_add_i32 s52, s50, 0x4000
	global_load_lds_dwordx4 v2, s[20:21]
	s_mov_b32 m0, s52
	s_add_i32 s53, s50, 0x6000
	global_load_lds_dwordx4 v4, s[4:5]
	s_mov_b32 m0, s53
	s_cmp_eq_u32 s47, 1
	global_load_lds_dwordx4 v2, s[4:5]
	s_cselect_b64 s[16:17], -1, 0
	s_cmp_lg_u32 s47, 1
	s_cbranch_scc1 .LBB0_267
	s_barrier
	s_setprio 1
; #define PG8_STAGE(bufoff, gbase, voff) do { _Pragma("unroll") for (int _i = 0; _i < 2; ++_i) \
;         __builtin_amdgcn_global_load_lds((const unsigned*)((const char*)(gbase) + (voff)[_i]), (LAS unsigned*)(lds + (bufoff) + ldsw + _i * 8192), 16, 0, 0); } while (0)
; #define PG8_WAIT_V(n) asm volatile("s_waitcnt vmcnt(" #n ")" ::: "memory")
; #define PG8_BAR __builtin_amdgcn_s_barrier()
; template <class Epi, class Sched>
; __device__ __forceinline__ void gemm_phase(LAS unsigned char* lds, const Gemm g, const Sched& S, const Epi& E) {
;     ...
;     f32x4 acc[2][2][4][2];
; #pragma unroll
;     for (int a = 0; a < 2; ++a)
; #pragma unroll
;         for (int b = 0; b < 2; ++b)
; #pragma unroll
;             for (int m = 0; m < 4; ++m)
; #pragma unroll
;                 for (int n = 0; n < 2; ++n) acc[a][b][m][n] = (f32x4){0.f, 0.f, 0.f, 0.f};
;     bf16x8 At[4][2], B0[2][2], B1[2][2];
;     const char* cA = (const char*)g.A + (size_t)cur.pm * tstepA + (size_t)cur.ka * 2; const char* cB = (const char*)g.Bt + (size_t)cur.pn * tstepB;
;     S.a_ready(cur);
;     PG8_STAGE(PG8_SB(0, 0), cB, voffB); PG8_STAGE(PG8_SB(0, 1), cB + hstepB, voffB); PG8_STAGE(PG8_SA(0, 0), cA, voffA); PG8_STAGE(PG8_SA(0, 1), cA + hstepA, voffA);
;     if (wr == 1) PG8_BAR;
;     PG8_WAIT_V(2); PG8_BAR;
;     PG8_STAGE(PG8_SB(1, 0), cB + kstep, voffB); PG8_STAGE(PG8_SA(1, 0), cA + kstep, voffA); PG8_STAGE(PG8_SB(1, 1), cB + hstepB + kstep, voffB);
;     PG8_WAIT_V(6); PG8_BAR;
.LBB0_267:
	v_lshl_add_u64 v[14:15], s[24:25], 0, v[4:5]
	v_mov_b32_e32 v3, v5
	v_and_b32_e32 v142, 15, v143
	v_and_b32_e32 v22, 48, v143
	v_lshlrev_b32_e32 v23, 2, v143
	v_lshl_add_u64 v[16:17], s[24:25], 0, v[2:3]
	s_and_b32 s48, s44, 3
	v_lshl_or_b32 v22, v142, 6, v22
	s_lshl_b32 s4, s47, 13
	v_and_b32_e32 v23, 32, v23
	s_add_i32 m0, s50, 0x18000
	v_lshl_add_u64 v[14:15], v[14:15], 0, s[36:37]
	v_lshl_add_u64 v[18:19], s[20:21], 0, v[4:5]
	v_bitop3_b32 v24, v22, s4, v23 bitop3:0xde
	s_lshl_b32 s4, s48, 12
	s_waitcnt vmcnt(2)
	s_barrier
	global_load_lds_dwordx4 v[14:15], off
	v_lshl_add_u64 v[14:15], v[16:17], 0, s[36:37]
	s_add_i32 m0, s50, 0x1a000
	s_add_i32 s54, s50, 0x8000
	s_add_i32 s55, s50, 0xa000
	v_lshl_add_u64 v[20:21], s[20:21], 0, v[2:3]
	v_bitop3_b32 v144, v22, s4, v23 bitop3:0xde
	global_load_lds_dwordx4 v[14:15], off
	v_lshl_add_u64 v[14:15], v[18:19], 0, s[36:37]
	s_mov_b32 m0, s54
	s_add_u32 s4, s24, 0x158080
	global_load_lds_dwordx4 v[14:15], off
	v_lshl_add_u64 v[14:15], v[20:21], 0, s[36:37]
	s_mov_b32 m0, s55
	s_addc_u32 s5, s25, 0
	global_load_lds_dwordx4 v[14:15], off
	s_add_i32 m0, s50, 0x1c000
	v_lshl_add_u64 v[14:15], s[4:5], 0, v[4:5]
	global_load_lds_dwordx4 v[14:15], off
	v_lshl_add_u64 v[14:15], s[4:5], 0, v[2:3]
	s_add_i32 m0, s50, 0x1e000
	s_movk_i32 s10, 0x1580
	global_load_lds_dwordx4 v[14:15], off
	v_lshrrev_b32_e32 v11, 1, v11
	v_mul_lo_u32 v10, v10, s10
	s_mov_b32 s22, 0x15800
	v_mad_u64_u32 v[10:11], s[4:5], v11, s22, v[10:11]
	v_or_b32_e32 v10, v10, v12
	v_add_lshl_u32 v134, v10, v13, 1
	v_lshrrev_b32_e32 v10, 1, v6
	v_mul_lo_u32 v6, v7, s10
	v_mad_u64_u32 v[6:7], s[4:5], v10, s22, v[6:7]
	s_waitcnt vmcnt(6)
	v_or_b32_e32 v6, v6, v8
	s_cmpk_lt_u32 s45, 0x100
	v_add_lshl_u32 v136, v6, v9, 1
	v_mov_b32_e32 v6, 0
	v_readlane_b32 s4, v254, 13
	s_cselect_b64 s[18:19], -1, 0
	v_mov_b32_e32 v135, v5
	v_mov_b32_e32 v137, v5
	s_mov_b32 s59, 0
	v_add_u32_e32 v145, 0, v24
	s_mov_b32 s10, s4
	v_readlane_b32 s46, v253, 61
	v_mov_b32_e32 v7, v6
	v_mov_b32_e32 v8, v6
	v_mov_b32_e32 v9, v6
	v_mov_b32_e32 v10, v6
	v_mov_b32_e32 v11, v6
	v_mov_b32_e32 v12, v6
	v_mov_b32_e32 v13, v6
	v_mov_b32_e32 v14, v6
	v_mov_b32_e32 v15, v6
	v_mov_b32_e32 v16, v6
	v_mov_b32_e32 v17, v6
	v_mov_b32_e32 v18, v6
	v_mov_b32_e32 v19, v6
	v_mov_b32_e32 v20, v6
	v_mov_b32_e32 v21, v6
	v_mov_b32_e32 v22, v6
	v_mov_b32_e32 v23, v6
	v_mov_b32_e32 v24, v6
	v_mov_b32_e32 v25, v6
	v_mov_b32_e32 v30, v6
	v_mov_b32_e32 v31, v6
	v_mov_b32_e32 v32, v6
	v_mov_b32_e32 v33, v6
	v_mov_b32_e32 v38, v6
	v_mov_b32_e32 v39, v6
	v_mov_b32_e32 v40, v6
	v_mov_b32_e32 v41, v6
	v_mov_b32_e32 v46, v6
	v_mov_b32_e32 v47, v6
	v_mov_b32_e32 v48, v6
	v_mov_b32_e32 v49, v6
	v_mov_b32_e32 v26, v6
	v_mov_b32_e32 v27, v6
	v_mov_b32_e32 v28, v6
	v_mov_b32_e32 v29, v6
	v_mov_b32_e32 v34, v6
	v_mov_b32_e32 v35, v6
	v_mov_b32_e32 v36, v6
	v_mov_b32_e32 v37, v6
	v_mov_b32_e32 v42, v6
	v_mov_b32_e32 v43, v6
	v_mov_b32_e32 v44, v6
	v_mov_b32_e32 v45, v6
	v_mov_b32_e32 v50, v6
	v_mov_b32_e32 v51, v6
	v_mov_b32_e32 v52, v6
	v_mov_b32_e32 v53, v6
	v_mov_b32_e32 v54, v6
	v_mov_b32_e32 v55, v6
	v_mov_b32_e32 v56, v6
	v_mov_b32_e32 v57, v6
	v_mov_b32_e32 v58, v6
	v_mov_b32_e32 v59, v6
	v_mov_b32_e32 v60, v6
	v_mov_b32_e32 v61, v6
	v_mov_b32_e32 v62, v6
	v_mov_b32_e32 v63, v6
	v_mov_b32_e32 v64, v6
	v_mov_b32_e32 v65, v6
	v_mov_b32_e32 v66, v6
	v_mov_b32_e32 v67, v6
	v_mov_b32_e32 v68, v6
	v_mov_b32_e32 v69, v6
	v_mov_b32_e32 v70, v6
	v_mov_b32_e32 v71, v6
	v_mov_b32_e32 v72, v6
	v_mov_b32_e32 v73, v6
	v_mov_b32_e32 v74, v6
	v_mov_b32_e32 v75, v6
	v_mov_b32_e32 v76, v6
	v_mov_b32_e32 v77, v6
	v_mov_b32_e32 v78, v6
	v_mov_b32_e32 v79, v6
	v_mov_b32_e32 v80, v6
	v_mov_b32_e32 v81, v6
	v_mov_b32_e32 v82, v6
	v_mov_b32_e32 v83, v6
	v_mov_b32_e32 v84, v6
	v_mov_b32_e32 v85, v6
	v_mov_b32_e32 v86, v6
	v_mov_b32_e32 v87, v6
	v_mov_b32_e32 v88, v6
	v_mov_b32_e32 v89, v6
	v_mov_b32_e32 v94, v6
	v_mov_b32_e32 v95, v6
	v_mov_b32_e32 v96, v6
	v_mov_b32_e32 v97, v6
	v_mov_b32_e32 v102, v6
	v_mov_b32_e32 v103, v6
	v_mov_b32_e32 v104, v6
	v_mov_b32_e32 v105, v6
	v_mov_b32_e32 v114, v6
	v_mov_b32_e32 v115, v6
	v_mov_b32_e32 v116, v6
	v_mov_b32_e32 v117, v6
	v_mov_b32_e32 v90, v6
	v_mov_b32_e32 v91, v6
	v_mov_b32_e32 v92, v6
	v_mov_b32_e32 v93, v6
	v_mov_b32_e32 v98, v6
	v_mov_b32_e32 v99, v6
	v_mov_b32_e32 v100, v6
	v_mov_b32_e32 v101, v6
	v_mov_b32_e32 v106, v6
	v_mov_b32_e32 v107, v6
	v_mov_b32_e32 v108, v6
	v_mov_b32_e32 v109, v6
	v_mov_b32_e32 v110, v6
	v_mov_b32_e32 v111, v6
	v_mov_b32_e32 v112, v6
	v_mov_b32_e32 v113, v6
	v_mov_b32_e32 v118, v6
	v_mov_b32_e32 v119, v6
	v_mov_b32_e32 v120, v6
	v_mov_b32_e32 v121, v6
	v_mov_b32_e32 v122, v6
	v_mov_b32_e32 v123, v6
	v_mov_b32_e32 v124, v6
	v_mov_b32_e32 v125, v6
	v_mov_b32_e32 v126, v6
	v_mov_b32_e32 v127, v6
	v_mov_b32_e32 v128, v6
	v_mov_b32_e32 v129, v6
	v_mov_b32_e32 v130, v6
	v_mov_b32_e32 v131, v6
	v_mov_b32_e32 v132, v6
	v_mov_b32_e32 v133, v6
	s_barrier
	s_branch .LBB0_270
	s_nop 0
	s_nop 0
	s_nop 0
	s_nop 0
	s_nop 0
	s_nop 0
	s_nop 0
	s_nop 0
	s_nop 0
	s_nop 0
	s_nop 0
	s_nop 0
	s_nop 0
	s_nop 0
	s_nop 0
	s_nop 0
	s_nop 0
	s_nop 0
	s_nop 0
	s_nop 0
	s_nop 0
	s_nop 0
	s_nop 0
	s_nop 0
	s_nop 0
	s_nop 0
	s_nop 0
	s_nop 0
	s_nop 0
	s_nop 0
	s_nop 0
	s_nop 0
	s_nop 0
	s_nop 0
	s_nop 0
	s_nop 0
	s_nop 0
	s_nop 0
	s_nop 0
	s_nop 0
	s_nop 0
	s_nop 0
	s_nop 0

; #define PG8_STAGE(bufoff, gbase, voff) do { _Pragma("unroll") for (int _i = 0; _i < 2; ++_i) \
;         __builtin_amdgcn_global_load_lds((const unsigned*)((const char*)(gbase) + (voff)[_i]), (LAS unsigned*)(lds + (bufoff) + ldsw + _i * 8192), 16, 0, 0); } while (0)
; #define PG8_LDA(dst, b, h) do { _Pragma("unroll") for (int m = 0; m < 4; ++m) _Pragma("unroll") for (int k = 0; k < 2; ++k) dst[m][k] = *(const LAS bf16x8*)(lds + PG8_SA(b, h) + aoff + m * 2048 + k * 1024); } while (0)
; #define PG8_LDB(dst, b, h) do { _Pragma("unroll") for (int n = 0; n < 2; ++n) _Pragma("unroll") for (int k = 0; k < 2; ++k) dst[n][k] = *(const LAS bf16x8*)(lds + PG8_SB(b, h) + boff + n * 2048 + k * 1024); } while (0)
; #define PG8_MMA(ai, bj, At, Bt) do { __builtin_amdgcn_s_setprio(1); _Pragma("unroll") for (int m = 0; m < 4; ++m) _Pragma("unroll") for (int n = 0; n < 2; ++n) _Pragma("unroll") for (int k = 0; k < 2; ++k) \
;         acc[ai][bj][m][n] = __builtin_amdgcn_mfma_f32_16x16x32_bf16(Bt[n][k], At[m][k], acc[ai][bj][m][n], 0, 0, 0); __builtin_amdgcn_s_setprio(0); } while (0)
; #define PG8_WAIT_V(n) asm volatile("s_waitcnt vmcnt(" #n ")" ::: "memory")
; #define PG8_WAIT_L(n) asm volatile("s_waitcnt lgkmcnt(" #n ")" ::: "memory")
; #define PG8_BAR __builtin_amdgcn_s_barrier()
; #define PG8_SCHED __builtin_amdgcn_sched_barrier(0)
; template <class Epi, class Sched>
; __device__ __forceinline__ void gemm_phase(LAS unsigned char* lds, const Gemm g, const Sched& S, const Epi& E) {
;     ...
;             PG8_LDB(B0, 0, 0); PG8_LDB(B1, 0, 1); PG8_SCHED; PG8_LDA(At, 0, 0); PG8_STAGE(PG8_SA(1, 1), a1 + hstepA, voffA);
;             PG8_WAIT_V(8); PG8_WAIT_L(0); PG8_BAR; PG8_MMA(0, 0, At, B0); PG8_MMA(0, 1, At, B1); PG8_BAR; PG8_SCHED;
;             PG8_LDA(At, 0, 1); PG8_STAGE(PG8_SB(0, 0), b2, voffB); PG8_STAGE(PG8_SB(0, 1), b2 + hstepB, voffB); PG8_STAGE(PG8_SA(0, 0), a2, voffA);
;             PG8_WAIT_V(8); PG8_WAIT_L(0); PG8_BAR; PG8_MMA(1, 0, At, B0); PG8_MMA(1, 1, At, B1); PG8_BAR; PG8_SCHED;
.LBB0_281:
	s_add_u32 s26, s20, s24
	s_addc_u32 s27, s21, s25
	s_add_u32 s26, s26, 0x100
	s_addc_u32 s27, s27, 0
	s_add_u32 s63, s60, s24
	s_addc_u32 s65, s61, s25
	s_add_i32 s67, 0, 0x10000
	s_cmpk_eq_i32 s24, 0x2a00
	s_cselect_b32 s29, s5, s27
	s_cselect_b32 s28, s4, s26
	s_cselect_b32 s27, s23, s65
	s_cselect_b32 s26, s22, s63
	s_add_i32 s63, 0, 0x14000
	v_add_u32_e32 v158, s67, v144
	v_add_u32_e32 v174, s63, v144
	ds_read_b128 v[146:149], v158
	ds_read_b128 v[150:153], v158 offset:1024
	ds_read_b128 v[154:157], v158 offset:2048
	ds_read_b128 v[158:161], v158 offset:3072
	ds_read_b128 v[162:165], v174
	ds_read_b128 v[166:169], v174 offset:1024
	ds_read_b128 v[170:173], v174 offset:2048
	ds_read_b128 v[174:177], v174 offset:3072
	v_lshl_add_u64 v[224:225], v[138:139], 0, s[24:25]
	s_add_i32 m0, s50, 0xc000
	ds_read_b128 v[178:181], v145
	ds_read_b128 v[182:185], v145 offset:1024
	ds_read_b128 v[186:189], v145 offset:2048
	ds_read_b128 v[190:193], v145 offset:3072
	ds_read_b128 v[194:197], v145 offset:4096
	ds_read_b128 v[212:215], v145 offset:5120
	ds_read_b128 v[216:219], v145 offset:6144
	ds_read_b128 v[220:223], v145 offset:7168
	global_load_lds_dwordx4 v[224:225], off
	v_lshl_add_u64 v[224:225], v[140:141], 0, s[24:25]
	s_add_i32 m0, s50, 0xe000
	s_nop 0
	global_load_lds_dwordx4 v[224:225], off
	s_waitcnt vmcnt(8)
	s_waitcnt lgkmcnt(0)
	s_barrier
	s_waitcnt lgkmcnt(0)
	v_mfma_f32_16x16x32_bf16 v[130:133], v[146:149], v[178:181], v[130:133]
	v_mfma_f32_16x16x32_bf16 v[126:129], v[154:157], v[178:181], v[126:129]
	v_mfma_f32_16x16x32_bf16 v[122:125], v[146:149], v[186:189], v[122:125]
	v_mfma_f32_16x16x32_bf16 v[118:121], v[154:157], v[186:189], v[118:121]
	v_mfma_f32_16x16x32_bf16 v[110:113], v[146:149], v[194:197], v[110:113]
	v_mfma_f32_16x16x32_bf16 v[106:109], v[154:157], v[194:197], v[106:109]
	v_mfma_f32_16x16x32_bf16 v[98:101], v[146:149], v[216:219], v[98:101]
	v_mfma_f32_16x16x32_bf16 v[90:93], v[154:157], v[216:219], v[90:93]
	v_mfma_f32_16x16x32_bf16 v[130:133], v[150:153], v[182:185], v[130:133]
	v_mfma_f32_16x16x32_bf16 v[126:129], v[158:161], v[182:185], v[126:129]
	v_mfma_f32_16x16x32_bf16 v[122:125], v[150:153], v[190:193], v[122:125]
	v_mfma_f32_16x16x32_bf16 v[118:121], v[158:161], v[190:193], v[118:121]
	v_mfma_f32_16x16x32_bf16 v[110:113], v[150:153], v[212:215], v[110:113]
	v_mfma_f32_16x16x32_bf16 v[106:109], v[158:161], v[212:215], v[106:109]
	v_mfma_f32_16x16x32_bf16 v[98:101], v[150:153], v[220:223], v[98:101]
	v_mfma_f32_16x16x32_bf16 v[90:93], v[158:161], v[220:223], v[90:93]
	v_mfma_f32_16x16x32_bf16 v[114:117], v[162:165], v[178:181], v[114:117]
	v_mfma_f32_16x16x32_bf16 v[102:105], v[170:173], v[178:181], v[102:105]
	v_mfma_f32_16x16x32_bf16 v[94:97], v[162:165], v[186:189], v[94:97]
	v_mfma_f32_16x16x32_bf16 v[86:89], v[170:173], v[186:189], v[86:89]
	v_mfma_f32_16x16x32_bf16 v[82:85], v[162:165], v[194:197], v[82:85]
	v_mfma_f32_16x16x32_bf16 v[78:81], v[170:173], v[194:197], v[78:81]
	v_mfma_f32_16x16x32_bf16 v[74:77], v[162:165], v[216:219], v[74:77]
	v_mfma_f32_16x16x32_bf16 v[70:73], v[170:173], v[216:219], v[70:73]
	v_mfma_f32_16x16x32_bf16 v[114:117], v[166:169], v[182:185], v[114:117]
	v_mfma_f32_16x16x32_bf16 v[102:105], v[174:177], v[182:185], v[102:105]
	v_mfma_f32_16x16x32_bf16 v[94:97], v[166:169], v[190:193], v[94:97]
	v_mfma_f32_16x16x32_bf16 v[86:89], v[174:177], v[190:193], v[86:89]
	v_mfma_f32_16x16x32_bf16 v[82:85], v[166:169], v[212:215], v[82:85]
	v_mfma_f32_16x16x32_bf16 v[78:81], v[174:177], v[212:215], v[78:81]
	v_mfma_f32_16x16x32_bf16 v[74:77], v[166:169], v[220:223], v[74:77]
	v_mfma_f32_16x16x32_bf16 v[70:73], v[174:177], v[220:223], v[70:73]
	s_barrier
	s_add_i32 s65, s67, s11
	v_lshl_add_u64 v[224:225], s[26:27], 0, v[4:5]
	s_mov_b32 m0, s65
	ds_read_b128 v[178:181], v145 offset:16384
	ds_read_b128 v[182:185], v145 offset:17408
	ds_read_b128 v[186:189], v145 offset:18432
	ds_read_b128 v[190:193], v145 offset:19456
	ds_read_b128 v[194:197], v145 offset:20480
	ds_read_b128 v[212:215], v145 offset:21504
	ds_read_b128 v[216:219], v145 offset:22528
	ds_read_b128 v[220:223], v145 offset:23552
	global_load_lds_dwordx4 v[224:225], off
	s_add_i32 m0, s65, 0x2000
	s_add_u32 s68, s26, 0x158000
	v_lshl_add_u64 v[226:227], s[26:27], 0, v[2:3]
	s_addc_u32 s69, s27, 0
	s_add_i32 s63, s63, s11
	global_load_lds_dwordx4 v[226:227], off
	v_lshl_add_u64 v[228:229], s[68:69], 0, v[4:5]
	s_mov_b32 m0, s63
	v_lshl_add_u64 v[230:231], s[28:29], 0, v[2:3]
	global_load_lds_dwordx4 v[228:229], off
	v_lshl_add_u64 v[228:229], s[68:69], 0, v[2:3]
	s_add_i32 m0, s63, 0x2000
	s_nop 0
	global_load_lds_dwordx4 v[228:229], off
	v_lshl_add_u64 v[228:229], s[28:29], 0, v[4:5]
	s_mov_b32 m0, s50
	s_nop 0
	global_load_lds_dwordx4 v[228:229], off
	s_mov_b32 m0, s51
	s_nop 0
	global_load_lds_dwordx4 v[230:231], off
	s_waitcnt vmcnt(8)
	s_waitcnt lgkmcnt(0)
	s_barrier
; #define PG8_STAGE(bufoff, gbase, voff) do { _Pragma("unroll") for (int _i = 0; _i < 2; ++_i) \
;         __builtin_amdgcn_global_load_lds((const unsigned*)((const char*)(gbase) + (voff)[_i]), (LAS unsigned*)(lds + (bufoff) + ldsw + _i * 8192), 16, 0, 0); } while (0)
; #define PG8_LDA(dst, b, h) do { _Pragma("unroll") for (int m = 0; m < 4; ++m) _Pragma("unroll") for (int k = 0; k < 2; ++k) dst[m][k] = *(const LAS bf16x8*)(lds + PG8_SA(b, h) + aoff + m * 2048 + k * 1024); } while (0)
; #define PG8_LDB(dst, b, h) do { _Pragma("unroll") for (int n = 0; n < 2; ++n) _Pragma("unroll") for (int k = 0; k < 2; ++k) dst[n][k] = *(const LAS bf16x8*)(lds + PG8_SB(b, h) + boff + n * 2048 + k * 1024); } while (0)
; #define PG8_MMA(ai, bj, At, Bt) do { __builtin_amdgcn_s_setprio(1); _Pragma("unroll") for (int m = 0; m < 4; ++m) _Pragma("unroll") for (int n = 0; n < 2; ++n) _Pragma("unroll") for (int k = 0; k < 2; ++k) \
;         acc[ai][bj][m][n] = __builtin_amdgcn_mfma_f32_16x16x32_bf16(Bt[n][k], At[m][k], acc[ai][bj][m][n], 0, 0, 0); __builtin_amdgcn_s_setprio(0); } while (0)
; #define PG8_WAIT_V(n) asm volatile("s_waitcnt vmcnt(" #n ")" ::: "memory")
; #define PG8_WAIT_L(n) asm volatile("s_waitcnt lgkmcnt(" #n ")" ::: "memory")
; #define PG8_BAR __builtin_amdgcn_s_barrier()
; #define PG8_SCHED __builtin_amdgcn_sched_barrier(0)
; template <class Epi, class Sched>
; __device__ __forceinline__ void gemm_phase(LAS unsigned char* lds, const Gemm g, const Sched& S, const Epi& E) {
;     ...
;             PG8_WAIT_V(8); PG8_WAIT_L(0); PG8_BAR; PG8_MMA(1, 0, At, B0); PG8_MMA(1, 1, At, B1); PG8_BAR; PG8_SCHED;
;             PG8_LDB(B0, 1, 0); PG8_LDB(B1, 1, 1); PG8_SCHED; PG8_LDA(At, 1, 0); PG8_STAGE(PG8_SA(0, 1), a2 + hstepA, voffA);
;             PG8_WAIT_V(8); PG8_WAIT_L(0); PG8_BAR; PG8_MMA(0, 0, At, B0); PG8_MMA(0, 1, At, B1); PG8_BAR; PG8_SCHED;
	s_waitcnt lgkmcnt(0)
	v_mfma_f32_16x16x32_bf16 v[66:69], v[146:149], v[178:181], v[66:69]
	v_mfma_f32_16x16x32_bf16 v[62:65], v[154:157], v[178:181], v[62:65]
	v_mfma_f32_16x16x32_bf16 v[58:61], v[146:149], v[186:189], v[58:61]
	v_mfma_f32_16x16x32_bf16 v[54:57], v[154:157], v[186:189], v[54:57]
	v_mfma_f32_16x16x32_bf16 v[50:53], v[146:149], v[194:197], v[50:53]
	v_mfma_f32_16x16x32_bf16 v[42:45], v[154:157], v[194:197], v[42:45]
	v_mfma_f32_16x16x32_bf16 v[34:37], v[146:149], v[216:219], v[34:37]
	v_mfma_f32_16x16x32_bf16 v[26:29], v[154:157], v[216:219], v[26:29]
	v_mfma_f32_16x16x32_bf16 v[66:69], v[150:153], v[182:185], v[66:69]
	v_mfma_f32_16x16x32_bf16 v[62:65], v[158:161], v[182:185], v[62:65]
	v_mfma_f32_16x16x32_bf16 v[58:61], v[150:153], v[190:193], v[58:61]
	v_mfma_f32_16x16x32_bf16 v[54:57], v[158:161], v[190:193], v[54:57]
	v_mfma_f32_16x16x32_bf16 v[50:53], v[150:153], v[212:215], v[50:53]
	v_mfma_f32_16x16x32_bf16 v[42:45], v[158:161], v[212:215], v[42:45]
	v_mfma_f32_16x16x32_bf16 v[34:37], v[150:153], v[220:223], v[34:37]
	v_mfma_f32_16x16x32_bf16 v[26:29], v[158:161], v[220:223], v[26:29]
	v_mfma_f32_16x16x32_bf16 v[46:49], v[162:165], v[178:181], v[46:49]
	v_mfma_f32_16x16x32_bf16 v[38:41], v[170:173], v[178:181], v[38:41]
	v_mfma_f32_16x16x32_bf16 v[30:33], v[162:165], v[186:189], v[30:33]
	v_mfma_f32_16x16x32_bf16 v[22:25], v[170:173], v[186:189], v[22:25]
	v_mfma_f32_16x16x32_bf16 v[18:21], v[162:165], v[194:197], v[18:21]
	v_mfma_f32_16x16x32_bf16 v[14:17], v[170:173], v[194:197], v[14:17]
	v_mfma_f32_16x16x32_bf16 v[10:13], v[162:165], v[216:219], v[10:13]
	v_mfma_f32_16x16x32_bf16 v[6:9], v[170:173], v[216:219], v[6:9]
	v_mfma_f32_16x16x32_bf16 v[46:49], v[166:169], v[182:185], v[46:49]
	v_mfma_f32_16x16x32_bf16 v[38:41], v[174:177], v[182:185], v[38:41]
	v_mfma_f32_16x16x32_bf16 v[30:33], v[166:169], v[190:193], v[30:33]
	v_mfma_f32_16x16x32_bf16 v[22:25], v[174:177], v[190:193], v[22:25]
	v_mfma_f32_16x16x32_bf16 v[18:21], v[166:169], v[212:215], v[18:21]
	v_mfma_f32_16x16x32_bf16 v[14:17], v[174:177], v[212:215], v[14:17]
	v_mfma_f32_16x16x32_bf16 v[10:13], v[166:169], v[220:223], v[10:13]
	v_mfma_f32_16x16x32_bf16 v[6:9], v[174:177], v[220:223], v[6:9]
	s_barrier
	s_add_i32 s63, 0, 0x18000
	s_add_i32 s65, 0, 0x1c000
	v_add_u32_e32 v158, s63, v144
	v_add_u32_e32 v174, s65, v144
	ds_read_b128 v[146:149], v158
	ds_read_b128 v[150:153], v158 offset:1024
	ds_read_b128 v[154:157], v158 offset:2048
	ds_read_b128 v[158:161], v158 offset:3072
	ds_read_b128 v[162:165], v174
	ds_read_b128 v[166:169], v174 offset:1024
	ds_read_b128 v[170:173], v174 offset:2048
	ds_read_b128 v[174:177], v174 offset:3072
	s_add_u32 s28, s28, 0x158000
	s_addc_u32 s29, s29, 0
	s_mov_b32 m0, s52
	v_lshl_add_u64 v[236:237], s[28:29], 0, v[4:5]
	ds_read_b128 v[178:181], v145 offset:32768
	ds_read_b128 v[182:185], v145 offset:33792
	ds_read_b128 v[186:189], v145 offset:34816
	ds_read_b128 v[190:193], v145 offset:35840
	ds_read_b128 v[194:197], v145 offset:36864
	ds_read_b128 v[212:215], v145 offset:37888
	ds_read_b128 v[216:219], v145 offset:38912
	ds_read_b128 v[220:223], v145 offset:39936
	global_load_lds_dwordx4 v[236:237], off
	v_lshl_add_u64 v[236:237], s[28:29], 0, v[2:3]
	s_mov_b32 m0, s53
	s_nop 0
	global_load_lds_dwordx4 v[236:237], off
	s_waitcnt vmcnt(8)
	s_waitcnt lgkmcnt(0)
	s_barrier
	s_waitcnt lgkmcnt(0)
	v_mfma_f32_16x16x32_bf16 v[130:133], v[146:149], v[178:181], v[130:133]
	v_mfma_f32_16x16x32_bf16 v[126:129], v[154:157], v[178:181], v[126:129]
	v_mfma_f32_16x16x32_bf16 v[122:125], v[146:149], v[186:189], v[122:125]
	v_mfma_f32_16x16x32_bf16 v[118:121], v[154:157], v[186:189], v[118:121]
	v_mfma_f32_16x16x32_bf16 v[110:113], v[146:149], v[194:197], v[110:113]
	v_mfma_f32_16x16x32_bf16 v[106:109], v[154:157], v[194:197], v[106:109]
	v_mfma_f32_16x16x32_bf16 v[98:101], v[146:149], v[216:219], v[98:101]
	v_mfma_f32_16x16x32_bf16 v[90:93], v[154:157], v[216:219], v[90:93]
	v_mfma_f32_16x16x32_bf16 v[130:133], v[150:153], v[182:185], v[130:133]
	v_mfma_f32_16x16x32_bf16 v[126:129], v[158:161], v[182:185], v[126:129]
	v_mfma_f32_16x16x32_bf16 v[122:125], v[150:153], v[190:193], v[122:125]
	v_mfma_f32_16x16x32_bf16 v[118:121], v[158:161], v[190:193], v[118:121]
	v_mfma_f32_16x16x32_bf16 v[110:113], v[150:153], v[212:215], v[110:113]
	v_mfma_f32_16x16x32_bf16 v[106:109], v[158:161], v[212:215], v[106:109]
	v_mfma_f32_16x16x32_bf16 v[98:101], v[150:153], v[220:223], v[98:101]
	v_mfma_f32_16x16x32_bf16 v[90:93], v[158:161], v[220:223], v[90:93]
	v_mfma_f32_16x16x32_bf16 v[114:117], v[162:165], v[178:181], v[114:117]
	v_mfma_f32_16x16x32_bf16 v[102:105], v[170:173], v[178:181], v[102:105]
	v_mfma_f32_16x16x32_bf16 v[94:97], v[162:165], v[186:189], v[94:97]
	v_mfma_f32_16x16x32_bf16 v[86:89], v[170:173], v[186:189], v[86:89]
	v_mfma_f32_16x16x32_bf16 v[82:85], v[162:165], v[194:197], v[82:85]
	v_mfma_f32_16x16x32_bf16 v[78:81], v[170:173], v[194:197], v[78:81]
	v_mfma_f32_16x16x32_bf16 v[74:77], v[162:165], v[216:219], v[74:77]
	v_mfma_f32_16x16x32_bf16 v[70:73], v[170:173], v[216:219], v[70:73]
	v_mfma_f32_16x16x32_bf16 v[114:117], v[166:169], v[182:185], v[114:117]
	v_mfma_f32_16x16x32_bf16 v[102:105], v[174:177], v[182:185], v[102:105]
	v_mfma_f32_16x16x32_bf16 v[94:97], v[166:169], v[190:193], v[94:97]
	v_mfma_f32_16x16x32_bf16 v[86:89], v[174:177], v[190:193], v[86:89]
	v_mfma_f32_16x16x32_bf16 v[82:85], v[166:169], v[212:215], v[82:85]
	v_mfma_f32_16x16x32_bf16 v[78:81], v[174:177], v[212:215], v[78:81]
	v_mfma_f32_16x16x32_bf16 v[74:77], v[166:169], v[220:223], v[74:77]
	v_mfma_f32_16x16x32_bf16 v[70:73], v[174:177], v[220:223], v[70:73]
	s_barrier
; #define PG8_STAGE(bufoff, gbase, voff) do { _Pragma("unroll") for (int _i = 0; _i < 2; ++_i) \
;         __builtin_amdgcn_global_load_lds((const unsigned*)((const char*)(gbase) + (voff)[_i]), (LAS unsigned*)(lds + (bufoff) + ldsw + _i * 8192), 16, 0, 0); } while (0)
; #define PG8_LDA(dst, b, h) do { _Pragma("unroll") for (int m = 0; m < 4; ++m) _Pragma("unroll") for (int k = 0; k < 2; ++k) dst[m][k] = *(const LAS bf16x8*)(lds + PG8_SA(b, h) + aoff + m * 2048 + k * 1024); } while (0)
; #define PG8_MMA(ai, bj, At, Bt) do { __builtin_amdgcn_s_setprio(1); _Pragma("unroll") for (int m = 0; m < 4; ++m) _Pragma("unroll") for (int n = 0; n < 2; ++n) _Pragma("unroll") for (int k = 0; k < 2; ++k) \
;         acc[ai][bj][m][n] = __builtin_amdgcn_mfma_f32_16x16x32_bf16(Bt[n][k], At[m][k], acc[ai][bj][m][n], 0, 0, 0); __builtin_amdgcn_s_setprio(0); } while (0)
; #define PG8_WAIT_V(n) asm volatile("s_waitcnt vmcnt(" #n ")" ::: "memory")
; #define PG8_WAIT_L(n) asm volatile("s_waitcnt lgkmcnt(" #n ")" ::: "memory")
; #define PG8_BAR __builtin_amdgcn_s_barrier()
; #define PG8_SCHED __builtin_amdgcn_sched_barrier(0)
; template <class Epi, class Sched>
; __device__ __forceinline__ void gemm_phase(LAS unsigned char* lds, const Gemm g, const Sched& S, const Epi& E) {
;     ...
;             PG8_LDA(At, 1, 1); PG8_STAGE(PG8_SB(1, 0), b3, voffB); PG8_STAGE(PG8_SB(1, 1), b3 + hstepB, voffB); PG8_STAGE(PG8_SA(1, 0), a3, voffA);
;             PG8_WAIT_V(8); PG8_WAIT_L(0); PG8_BAR; PG8_MMA(1, 0, At, B0); PG8_MMA(1, 1, At, B1); PG8_BAR; PG8_SCHED;
;         }
;         if (wr == 0) PG8_BAR;
	s_add_i32 s28, s63, s11
	v_lshl_add_u64 v[224:225], v[224:225], 0, s[36:37]
	s_mov_b32 m0, s28
	ds_read_b128 v[178:181], v145 offset:49152
	ds_read_b128 v[182:185], v145 offset:50176
	ds_read_b128 v[186:189], v145 offset:51200
	ds_read_b128 v[190:193], v145 offset:52224
	ds_read_b128 v[194:197], v145 offset:53248
	ds_read_b128 v[212:215], v145 offset:54272
	ds_read_b128 v[216:219], v145 offset:55296
	ds_read_b128 v[220:223], v145 offset:56320
	global_load_lds_dwordx4 v[224:225], off
	s_add_i32 m0, s28, 0x2000
	s_add_u32 s26, s26, 0x158080
	v_lshl_add_u64 v[224:225], v[226:227], 0, s[36:37]
	s_addc_u32 s27, s27, 0
	s_add_i32 s28, s65, s11
	global_load_lds_dwordx4 v[224:225], off
	v_lshl_add_u64 v[224:225], s[26:27], 0, v[4:5]
	s_mov_b32 m0, s28
	s_nop 0
	global_load_lds_dwordx4 v[224:225], off
	v_lshl_add_u64 v[224:225], s[26:27], 0, v[2:3]
	s_add_i32 m0, s28, 0x2000
	s_nop 0
	global_load_lds_dwordx4 v[224:225], off
	v_lshl_add_u64 v[224:225], v[228:229], 0, s[36:37]
	s_mov_b32 m0, s54
	s_nop 0
	global_load_lds_dwordx4 v[224:225], off
	v_lshl_add_u64 v[224:225], v[230:231], 0, s[36:37]
	s_mov_b32 m0, s55
	s_nop 0
	global_load_lds_dwordx4 v[224:225], off
	s_waitcnt vmcnt(8)
	s_waitcnt lgkmcnt(0)
	s_barrier
	s_waitcnt lgkmcnt(0)
	v_mfma_f32_16x16x32_bf16 v[66:69], v[146:149], v[178:181], v[66:69]
	v_mfma_f32_16x16x32_bf16 v[62:65], v[154:157], v[178:181], v[62:65]
	v_mfma_f32_16x16x32_bf16 v[58:61], v[146:149], v[186:189], v[58:61]
	v_mfma_f32_16x16x32_bf16 v[54:57], v[154:157], v[186:189], v[54:57]
	v_mfma_f32_16x16x32_bf16 v[50:53], v[146:149], v[194:197], v[50:53]
	v_mfma_f32_16x16x32_bf16 v[42:45], v[154:157], v[194:197], v[42:45]
	v_mfma_f32_16x16x32_bf16 v[34:37], v[146:149], v[216:219], v[34:37]
	v_mfma_f32_16x16x32_bf16 v[26:29], v[154:157], v[216:219], v[26:29]
	v_mfma_f32_16x16x32_bf16 v[66:69], v[150:153], v[182:185], v[66:69]
	v_mfma_f32_16x16x32_bf16 v[62:65], v[158:161], v[182:185], v[62:65]
	v_mfma_f32_16x16x32_bf16 v[58:61], v[150:153], v[190:193], v[58:61]
	v_mfma_f32_16x16x32_bf16 v[54:57], v[158:161], v[190:193], v[54:57]
	v_mfma_f32_16x16x32_bf16 v[50:53], v[150:153], v[212:215], v[50:53]
	v_mfma_f32_16x16x32_bf16 v[42:45], v[158:161], v[212:215], v[42:45]
	v_mfma_f32_16x16x32_bf16 v[34:37], v[150:153], v[220:223], v[34:37]
	v_mfma_f32_16x16x32_bf16 v[26:29], v[158:161], v[220:223], v[26:29]
	v_mfma_f32_16x16x32_bf16 v[46:49], v[162:165], v[178:181], v[46:49]
	v_mfma_f32_16x16x32_bf16 v[38:41], v[170:173], v[178:181], v[38:41]
	v_mfma_f32_16x16x32_bf16 v[30:33], v[162:165], v[186:189], v[30:33]
	v_mfma_f32_16x16x32_bf16 v[22:25], v[170:173], v[186:189], v[22:25]
	v_mfma_f32_16x16x32_bf16 v[18:21], v[162:165], v[194:197], v[18:21]
	v_mfma_f32_16x16x32_bf16 v[14:17], v[170:173], v[194:197], v[14:17]
	v_mfma_f32_16x16x32_bf16 v[10:13], v[162:165], v[216:219], v[10:13]
	v_mfma_f32_16x16x32_bf16 v[6:9], v[170:173], v[216:219], v[6:9]
	v_mfma_f32_16x16x32_bf16 v[46:49], v[166:169], v[182:185], v[46:49]
	v_mfma_f32_16x16x32_bf16 v[38:41], v[174:177], v[182:185], v[38:41]
	v_mfma_f32_16x16x32_bf16 v[30:33], v[166:169], v[190:193], v[30:33]
	v_mfma_f32_16x16x32_bf16 v[22:25], v[174:177], v[190:193], v[22:25]
	v_mfma_f32_16x16x32_bf16 v[18:21], v[166:169], v[212:215], v[18:21]
	v_mfma_f32_16x16x32_bf16 v[14:17], v[174:177], v[212:215], v[14:17]
	v_mfma_f32_16x16x32_bf16 v[10:13], v[166:169], v[220:223], v[10:13]
	v_mfma_f32_16x16x32_bf16 v[6:9], v[174:177], v[220:223], v[6:9]
	s_barrier
	s_add_i32 s62, s62, 2
	s_add_u32 s24, s24, 0x100
	s_addc_u32 s25, s25, 0
	s_cmpk_gt_u32 s62, 0x53
	s_cbranch_scc0 .LBB0_281
	s_and_b64 vcc, exec, s[18:19]
	s_cbranch_vccz .LBB0_284
	s_barrier

; #define ENDP(k) do { if ((k) + 1 < hi) { _Pragma("nounroll") for (int rb_ = 0; rb_ < DUPN(7); ++rb_) { XcdBarrier bb_ = bar; asm volatile("" : "+s"(bb_.bar)); xcd_barrier(bb_); } } } while (0)
; __device__ __forceinline__ void xcd_barrier(const XcdBarrier& b) {
;     asm volatile("s_waitcnt vmcnt(0)" ::: "memory");
;     __syncthreads();
;     if (threadIdx.x == 0) {
;         unsigned* bar = b.bar;
;         __builtin_amdgcn_s_waitcnt(0);
;         unsigned nloc = b.st[0], nx = b.st[1];
;         if (nloc == 0u) { xcd_barrier_complete(bar, b.x, nloc, nx); b.st[0] = nloc; b.st[1] = nx; }
;         const unsigned k1 = b.st[2] + 1u, rank = b.st[3]; b.st[2] = k1;
;         (void)__hip_atomic_fetch_add(&bar[XB_XSUB(b.x)], 1u, __ATOMIC_RELAXED, __HIP_MEMORY_SCOPE_AGENT);
; __global__ void __launch_bounds__(512, 2) mk_fwd(Args args) {
;     ...
;                 ENDP(pf + 1);
.LBB0_424:
	s_waitcnt lgkmcnt(0)
	v_readlane_b32 s8, v253, 1
	s_add_i32 s66, s66, 2
	v_readlane_b32 s11, v253, 4
	s_cmp_ge_i32 s66, s11
	v_readlane_b32 s9, v253, 2
	v_readlane_b32 s10, v253, 3
	s_cbranch_scc1 .LBB0_498
	s_setprio 0
	s_mov_b64 s[8:9], s[96:97]
	s_waitcnt vmcnt(0)
	s_barrier
	s_mov_b64 s[4:5], exec
	v_readlane_b32 s10, v254, 21
	v_readlane_b32 s11, v254, 22
	s_and_b64 s[10:11], s[4:5], s[10:11]
	s_mov_b64 exec, s[10:11]
	s_cbranch_execz .LBB0_497
	v_mov_b32_e32 v2, s93
	s_waitcnt vmcnt(0) expcnt(0) lgkmcnt(0)
	ds_read_b32 v4, v2
	ds_read_b32 v2, v2 offset:4
	s_waitcnt lgkmcnt(1)
	v_cmp_ne_u32_e32 vcc, 0, v4
	s_cbranch_vccnz .LBB0_472
	s_load_dwordx2 s[14:15], s[94:95], 0x4
	s_add_u32 s10, s8, 0x1000
	s_addc_u32 s11, s9, 0
	s_add_u32 s12, s8, 0x1100
	s_addc_u32 s13, s9, 0
	s_waitcnt lgkmcnt(0)
	s_mul_i32 s34, s14, s92
	s_add_u32 s14, s8, 0x1200
	s_mul_i32 s34, s34, s15
	s_addc_u32 s15, s9, 0
	s_add_u32 s16, s8, 0x1300
	s_addc_u32 s17, s9, 0
	s_mov_b32 s44, 1
	s_mov_b64 s[18:19], 0
	s_branch .LBB0_430

; #define PG8_STAGE(bufoff, gbase, voff) do { _Pragma("unroll") for (int _i = 0; _i < 2; ++_i) \
;         __builtin_amdgcn_global_load_lds((const unsigned*)((const char*)(gbase) + (voff)[_i]), (LAS unsigned*)(lds + (bufoff) + ldsw + _i * 8192), 16, 0, 0); } while (0)
; #define PG8_WAIT_V(n) asm volatile("s_waitcnt vmcnt(" #n ")" ::: "memory")
; #define PG8_BAR __builtin_amdgcn_s_barrier()
;     __device__ __forceinline__ void operator()(const f32x4 (&acc)[2][2][4][2], const Unit& u, int wr, int wc, int fr, int fq) const {
;         const int row0 = u.pm * BM + wr * 64 + fr, j0 = 8 * fq, cbase = u.pn * BM + 64 * wc;
;         const f32x4 ba0 = *(const f32x4*)(bias + cbase + j0), ba1 = *(const f32x4*)(bias + cbase + j0 + 4), bb0 = *(const f32x4*)(bias + cbase + 32 + j0), bb1 = *(const f32x4*)(bias + cbase + 32 + j0 + 4);
; template <class Epi, class Sched>
; __device__ __forceinline__ void gemm_phase(LAS unsigned char* lds, const Gemm g, const Sched& S, const Epi& E) {
;     ...
;     const char* cA = (const char*)g.A + (size_t)cur.pm * tstepA + (size_t)cur.ka * 2; const char* cB = (const char*)g.Bt + (size_t)cur.pn * tstepB;
;     S.a_ready(cur);
;     PG8_STAGE(PG8_SB(0, 0), cB, voffB); PG8_STAGE(PG8_SB(0, 1), cB + hstepB, voffB); PG8_STAGE(PG8_SA(0, 0), cA, voffA); PG8_STAGE(PG8_SA(0, 1), cA + hstepA, voffA);
;     if (wr == 1) PG8_BAR;
;     PG8_WAIT_V(2); PG8_BAR;
;     PG8_STAGE(PG8_SB(1, 0), cB + kstep, voffB); PG8_STAGE(PG8_SA(1, 0), cA + kstep, voffA); PG8_STAGE(PG8_SB(1, 1), cB + hstepB + kstep, voffB);
;     PG8_WAIT_V(6); PG8_BAR;
.LBB0_504:
	s_load_dwordx2 s[8:9], s[6:7], 0x98
	s_load_dwordx2 s[14:15], s[6:7], 0x70
	s_waitcnt lgkmcnt(0)
	s_add_u32 s47, s8, 0x9000000
	s_addc_u32 s48, s9, 0
	s_add_u32 s34, s8, 0x45c00000
	s_addc_u32 s46, s9, 0
	s_add_u32 s6, s8, 0xd000000
	s_addc_u32 s7, s9, 0
	s_add_u32 s12, s8, 0xa00000
	s_addc_u32 s13, s9, 0
	s_add_u32 s10, s8, 0xb00000
	s_addc_u32 s11, s9, 0
	s_add_u32 s8, s8, 0x100000
	s_addc_u32 s9, s9, 0
	s_and_b64 vcc, exec, s[4:5]
	s_cbranch_vccnz .LBB0_538
	v_ashrrev_i32_e32 v2, 31, v4
	v_lshrrev_b32_e32 v2, 26, v2
	v_add_u32_e32 v2, v4, v2
	v_ashrrev_i32_e32 v14, 6, v2
	v_bfe_i32 v2, v4, 27, 1
	v_lshlrev_b32_e32 v3, 4, v4
	v_lshrrev_b32_e32 v2, 22, v2
	v_add_u32_e32 v2, v3, v2
	v_and_b32_e32 v2, 0xfffffc00, v2
	v_sub_u32_e32 v2, v3, v2
	s_waitcnt vmcnt(0)
	v_lshrrev_b32_e32 v6, 4, v2
	v_bitop3_b32 v2, v6, v2, 32 bitop3:0x6c
	v_ashrrev_i32_e32 v7, 31, v2
	v_lshrrev_b32_e32 v7, 26, v7
	v_add_u32_e32 v7, v2, v7
	v_lshlrev_b32_e32 v6, 3, v14
	v_ashrrev_i32_e32 v15, 6, v7
	v_and_b32_e32 v7, 0xc0, v7
	v_and_b32_e32 v6, -16, v6
	v_sub_u32_e32 v2, v2, v7
	v_add_u32_e32 v6, v15, v6
	v_lshlrev_b32_e32 v8, 5, v14
	v_ashrrev_i16_sdwa v2, v232, sext(v2) dst_sel:DWORD dst_unused:UNUSED_PAD src0_sel:DWORD src1_sel:BYTE_0
	v_and_b32_e32 v8, 32, v8
	v_bfe_i32 v16, v2, 0, 16
	v_lshlrev_b32_e32 v2, 1, v6
	v_lshrrev_b32_e32 v7, 2, v6
	v_and_b32_e32 v9, 3, v15
	s_mov_b32 s4, 0xfffe0
	v_and_b32_e32 v2, 24, v2
	v_and_b32_e32 v7, 4, v7
	v_and_or_b32 v9, v6, s4, v9
	v_add_lshl_u32 v8, v8, v16, 1
	v_add_u32_e32 v3, 0x2000, v3
	v_or3_b32 v7, v9, v7, v2
	v_lshl_add_u32 v2, v6, 12, v8
	v_ashrrev_i32_e32 v6, 31, v3
	v_lshrrev_b32_e32 v6, 22, v6
	v_add_u32_e32 v6, v3, v6
	v_ashrrev_i32_e32 v17, 10, v6
	v_mul_i32_i24_e32 v6, 0x400, v17
	v_sub_u32_e32 v3, v3, v6
	v_lshrrev_b32_e32 v6, 4, v3
	v_bitop3_b32 v3, v6, v3, 32 bitop3:0x6c
	v_lshl_add_u32 v212, v7, 12, v8
	v_ashrrev_i32_e32 v7, 31, v3
	v_lshrrev_b32_e32 v7, 26, v7
	v_lshlrev_b32_e32 v6, 3, v17
	v_add_u32_e32 v7, v3, v7
	v_and_b32_e32 v6, -16, v6
	v_ashrrev_i32_e32 v18, 6, v7
	s_ashr_i32 s17, s16, 6
	v_add_u32_e32 v6, v18, v6
	v_and_b32_e32 v9, 3, v18
	s_ashr_i32 s29, s28, 31
	v_and_or_b32 v9, v6, s4, v9
	s_ashr_i32 s18, s16, 8
	s_lshl_b32 s49, s17, 10
	s_lshl_b64 s[4:5], s[28:29], 20
	s_add_u32 s38, s47, s4
	v_and_b32_e32 v7, 0xc0, v7
	s_addc_u32 s39, s48, s5
	s_ashr_i32 s27, s26, 31
	v_sub_u32_e32 v3, v3, v7
	s_lshl_b64 s[4:5], s[26:27], 20
	v_ashrrev_i16_sdwa v3, v232, sext(v3) dst_sel:DWORD dst_unused:UNUSED_PAD src0_sel:DWORD src1_sel:BYTE_0
	s_add_u32 s42, s34, s4
	v_lshlrev_b32_e32 v8, 5, v17
	v_bfe_i32 v19, v3, 0, 16
	v_lshlrev_b32_e32 v3, 1, v6
	v_lshrrev_b32_e32 v7, 2, v6
	s_addc_u32 s43, s46, s5
	s_add_i32 s50, s49, 0
	v_and_b32_e32 v8, 32, v8
	v_and_b32_e32 v3, 24, v3
	v_and_b32_e32 v7, 4, v7
	s_add_i32 m0, s50, 0x10000
	v_or3_b32 v3, v9, v7, v3
	v_add_lshl_u32 v7, v8, v19, 1
	global_load_lds_dwordx4 v212, s[42:43]
	s_add_i32 m0, s50, 0x12000
	v_lshl_add_u32 v216, v3, 12, v7
	s_add_u32 s4, s42, 0x80000
	global_load_lds_dwordx4 v216, s[42:43]
	s_addc_u32 s5, s43, 0
	s_add_i32 m0, s50, 0x14000
	s_add_i32 s51, s50, 0x2000
	global_load_lds_dwordx4 v212, s[4:5]
	s_add_i32 m0, s50, 0x16000
	v_lshl_add_u32 v214, v6, 12, v7
	global_load_lds_dwordx4 v216, s[4:5]
	s_mov_b32 m0, s50
	s_add_u32 s4, s38, 0x80000
	global_load_lds_dwordx4 v2, s[38:39]
	s_mov_b32 m0, s51
	s_addc_u32 s5, s39, 0
	s_add_i32 s52, s50, 0x4000
	global_load_lds_dwordx4 v214, s[38:39]
	s_mov_b32 m0, s52
	s_add_i32 s53, s50, 0x6000
	global_load_lds_dwordx4 v2, s[4:5]
	s_mov_b32 m0, s53
	v_mov_b32_e32 v213, v5
	global_load_lds_dwordx4 v214, s[4:5]
	v_mov_b32_e32 v217, v5
	v_mov_b32_e32 v3, v5
	v_mov_b32_e32 v215, v5
	s_cmp_eq_u32 s18, 1
	s_waitcnt vmcnt(0)
	v_lshl_add_u64 v[12:13], s[42:43], 0, v[212:213]
	v_lshl_add_u64 v[10:11], s[42:43], 0, v[216:217]
	v_lshl_add_u64 v[6:7], s[38:39], 0, v[2:3]
	s_cselect_b64 s[4:5], -1, 0
	s_cmp_lg_u32 s18, 1
	v_lshl_add_u64 v[8:9], s[38:39], 0, v[214:215]
	s_cbranch_scc1 .LBB0_507
	s_barrier
	s_setprio 1
.LBB0_507:
	v_lshrrev_b32_e32 v20, 1, v4
	v_and_b32_e32 v20, 24, v20
	v_and_b32_e32 v21, 15, v4
	v_lshlrev_b32_e32 v22, 1, v20
	v_lshlrev_b32_e32 v4, 2, v4
	s_and_b32 s20, s17, 3
	v_lshl_or_b32 v235, s18, 6, v21
	v_lshl_or_b32 v21, v21, 6, v22
	s_lshl_b32 s17, s18, 13
	v_and_b32_e32 v4, 32, v4
	s_add_i32 m0, s50, 0x18000
	v_lshl_add_u64 v[12:13], v[12:13], 0, s[36:37]
	v_bitop3_b32 v22, v21, s17, v4 bitop3:0xde
	s_lshl_b32 s17, s20, 12
	s_waitcnt vmcnt(2)
	s_barrier
	global_load_lds_dwordx4 v[12:13], off
	v_lshl_add_u64 v[10:11], v[10:11], 0, s[36:37]
	s_add_i32 m0, s50, 0x1a000
	s_add_i32 s54, s50, 0x8000
	s_add_i32 s55, s50, 0xa000
	global_load_lds_dwordx4 v[10:11], off
	v_lshl_add_u64 v[6:7], v[6:7], 0, s[36:37]
	s_mov_b32 m0, s54
	s_add_u32 s18, s42, 0x80080
	global_load_lds_dwordx4 v[6:7], off
	v_lshl_add_u64 v[6:7], v[8:9], 0, s[36:37]
	s_mov_b32 m0, s55
	s_addc_u32 s19, s43, 0
	global_load_lds_dwordx4 v[6:7], off
	s_add_i32 m0, s50, 0x1c000
	v_lshl_add_u64 v[6:7], s[18:19], 0, v[212:213]
	global_load_lds_dwordx4 v[6:7], off
	v_lshl_add_u64 v[6:7], s[18:19], 0, v[216:217]
	s_add_i32 m0, s50, 0x1e000
	v_bitop3_b32 v236, v21, s17, v4 bitop3:0xde
	global_load_lds_dwordx4 v[6:7], off
	v_lshlrev_b32_e32 v4, 2, v20
	v_lshl_add_u64 v[218:219], s[12:13], 0, v[4:5]
	v_lshl_add_u64 v[220:221], s[10:11], 0, v[4:5]
	v_lshl_add_u64 v[222:223], s[14:15], 0, v[4:5]
	v_lshlrev_b32_e32 v4, 15, v14
	v_and_b32_e32 v4, 0xffff0000, v4
	v_lshl_add_u32 v4, v15, 12, v4
	v_and_b32_e32 v6, 1, v14
	v_lshl_or_b32 v4, v6, 6, v4
	v_lshl_add_u32 v224, v16, 1, v4
	v_lshlrev_b32_e32 v4, 15, v17
	v_and_b32_e32 v4, 0xffff0000, v4
	s_waitcnt vmcnt(6)
	v_lshl_add_u32 v4, v18, 12, v4
	v_and_b32_e32 v6, 1, v17
	s_cmpk_lt_u32 s16, 0x100
	v_lshl_or_b32 v4, v6, 6, v4
	s_cselect_b64 s[16:17], -1, 0
	s_lshl_b32 s56, s20, 6
	v_mov_b32_e32 v225, v5
	v_lshl_add_u32 v226, v19, 1, v4
	v_mov_b32_e32 v227, v5
	s_mov_b32 s57, 0
	v_add_u32_e32 v237, 0, v22
	v_lshlrev_b32_e32 v4, 1, v20
	s_barrier
	s_branch .LBB0_510
	s_nop 0
	s_nop 0
	s_nop 0
	s_nop 0
	s_nop 0
	s_nop 0
	s_nop 0
	s_nop 0
	s_nop 0
	s_nop 0
	s_nop 0
	s_nop 0
	s_nop 0
	s_nop 0
	s_nop 0
	s_nop 0

; #define PG8_STAGE(bufoff, gbase, voff) do { _Pragma("unroll") for (int _i = 0; _i < 2; ++_i) \
;         __builtin_amdgcn_global_load_lds((const unsigned*)((const char*)(gbase) + (voff)[_i]), (LAS unsigned*)(lds + (bufoff) + ldsw + _i * 8192), 16, 0, 0); } while (0)
; #define PG8_LDA(dst, b, h) do { _Pragma("unroll") for (int m = 0; m < 4; ++m) _Pragma("unroll") for (int k = 0; k < 2; ++k) dst[m][k] = *(const LAS bf16x8*)(lds + PG8_SA(b, h) + aoff + m * 2048 + k * 1024); } while (0)
; #define PG8_LDB(dst, b, h) do { _Pragma("unroll") for (int n = 0; n < 2; ++n) _Pragma("unroll") for (int k = 0; k < 2; ++k) dst[n][k] = *(const LAS bf16x8*)(lds + PG8_SB(b, h) + boff + n * 2048 + k * 1024); } while (0)
; #define PG8_MMA(ai, bj, At, Bt) do { __builtin_amdgcn_s_setprio(1); _Pragma("unroll") for (int m = 0; m < 4; ++m) _Pragma("unroll") for (int n = 0; n < 2; ++n) _Pragma("unroll") for (int k = 0; k < 2; ++k) \
;         acc[ai][bj][m][n] = __builtin_amdgcn_mfma_f32_16x16x32_bf16(Bt[n][k], At[m][k], acc[ai][bj][m][n], 0, 0, 0); __builtin_amdgcn_s_setprio(0); } while (0)
; #define PG8_WAIT_V(n) asm volatile("s_waitcnt vmcnt(" #n ")" ::: "memory")
; #define PG8_WAIT_L(n) asm volatile("s_waitcnt lgkmcnt(" #n ")" ::: "memory")
; #define PG8_BAR __builtin_amdgcn_s_barrier()
; #define PG8_SCHED __builtin_amdgcn_sched_barrier(0)
; template <class Epi, class Sched>
; __device__ __forceinline__ void gemm_phase(LAS unsigned char* lds, const Gemm g, const Sched& S, const Epi& E) {
;     ...
;             PG8_LDB(B0, 0, 0); PG8_LDB(B1, 0, 1); PG8_SCHED; PG8_LDA(At, 0, 0); PG8_STAGE(PG8_SA(1, 1), a1 + hstepA, voffA);
;             PG8_WAIT_V(8); PG8_WAIT_L(0); PG8_BAR; PG8_MMA(0, 0, At, B0); PG8_MMA(0, 1, At, B1); PG8_BAR; PG8_SCHED;
;             PG8_LDA(At, 0, 1); PG8_STAGE(PG8_SB(0, 0), b2, voffB); PG8_STAGE(PG8_SB(0, 1), b2 + hstepB, voffB); PG8_STAGE(PG8_SA(0, 0), a2, voffA);
;             PG8_WAIT_V(8); PG8_WAIT_L(0); PG8_BAR; PG8_MMA(1, 0, At, B0); PG8_MMA(1, 1, At, B1); PG8_BAR; PG8_SCHED;
.LBB0_513:
	s_add_u32 s42, s38, 0xfff80080
	s_addc_u32 s43, s39, -1
	s_add_i32 s61, 0, 0x10000
	s_cmp_eq_u32 s60, 28
	s_cselect_b32 s45, s21, s43
	s_cselect_b32 s44, s27, s42
	s_cselect_b32 s43, s19, s59
	s_cselect_b32 s42, s29, s58
	s_add_i32 s64, 0, 0x14000
	v_add_u32_e32 v98, s61, v236
	v_add_u32_e32 v162, s64, v236
	ds_read_b128 v[86:89], v98
	ds_read_b128 v[90:93], v98 offset:1024
	ds_read_b128 v[94:97], v98 offset:2048
	ds_read_b128 v[98:101], v98 offset:3072
	ds_read_b128 v[150:153], v162
	ds_read_b128 v[154:157], v162 offset:1024
	ds_read_b128 v[158:161], v162 offset:2048
	ds_read_b128 v[162:165], v162 offset:3072
	v_lshl_add_u64 v[228:229], s[38:39], 0, v[224:225]
	s_add_i32 m0, s50, 0xc000
	ds_read_b128 v[166:169], v237
	ds_read_b128 v[170:173], v237 offset:1024
	ds_read_b128 v[174:177], v237 offset:2048
	ds_read_b128 v[178:181], v237 offset:3072
	ds_read_b128 v[182:185], v237 offset:4096
	ds_read_b128 v[186:189], v237 offset:5120
	ds_read_b128 v[190:193], v237 offset:6144
	ds_read_b128 v[194:197], v237 offset:7168
	global_load_lds_dwordx4 v[228:229], off
	v_lshl_add_u64 v[228:229], s[38:39], 0, v[226:227]
	s_add_i32 m0, s50, 0xe000
	s_nop 0
	global_load_lds_dwordx4 v[228:229], off
	s_waitcnt vmcnt(8)
	s_waitcnt lgkmcnt(0)
	s_barrier
	s_waitcnt lgkmcnt(0)
	v_mfma_f32_16x16x32_bf16 v[146:149], v[86:89], v[166:169], v[146:149]
	v_mfma_f32_16x16x32_bf16 v[142:145], v[94:97], v[166:169], v[142:145]
	v_mfma_f32_16x16x32_bf16 v[130:133], v[86:89], v[174:177], v[130:133]
	v_mfma_f32_16x16x32_bf16 v[126:129], v[94:97], v[174:177], v[126:129]
	v_mfma_f32_16x16x32_bf16 v[114:117], v[86:89], v[182:185], v[114:117]
	v_mfma_f32_16x16x32_bf16 v[110:113], v[94:97], v[182:185], v[110:113]
	v_mfma_f32_16x16x32_bf16 v[82:85], v[86:89], v[190:193], v[82:85]
	v_mfma_f32_16x16x32_bf16 v[78:81], v[94:97], v[190:193], v[78:81]
	v_mfma_f32_16x16x32_bf16 v[146:149], v[90:93], v[170:173], v[146:149]
	v_mfma_f32_16x16x32_bf16 v[142:145], v[98:101], v[170:173], v[142:145]
	v_mfma_f32_16x16x32_bf16 v[130:133], v[90:93], v[178:181], v[130:133]
	v_mfma_f32_16x16x32_bf16 v[126:129], v[98:101], v[178:181], v[126:129]
	v_mfma_f32_16x16x32_bf16 v[114:117], v[90:93], v[186:189], v[114:117]
	v_mfma_f32_16x16x32_bf16 v[110:113], v[98:101], v[186:189], v[110:113]
	v_mfma_f32_16x16x32_bf16 v[82:85], v[90:93], v[194:197], v[82:85]
	v_mfma_f32_16x16x32_bf16 v[78:81], v[98:101], v[194:197], v[78:81]
	v_mfma_f32_16x16x32_bf16 v[138:141], v[150:153], v[166:169], v[138:141]
	v_mfma_f32_16x16x32_bf16 v[134:137], v[158:161], v[166:169], v[134:137]
	v_mfma_f32_16x16x32_bf16 v[122:125], v[150:153], v[174:177], v[122:125]
	v_mfma_f32_16x16x32_bf16 v[118:121], v[158:161], v[174:177], v[118:121]
	v_mfma_f32_16x16x32_bf16 v[106:109], v[150:153], v[182:185], v[106:109]
	v_mfma_f32_16x16x32_bf16 v[102:105], v[158:161], v[182:185], v[102:105]
	v_mfma_f32_16x16x32_bf16 v[74:77], v[150:153], v[190:193], v[74:77]
	v_mfma_f32_16x16x32_bf16 v[70:73], v[158:161], v[190:193], v[70:73]
	v_mfma_f32_16x16x32_bf16 v[138:141], v[154:157], v[170:173], v[138:141]
	v_mfma_f32_16x16x32_bf16 v[134:137], v[162:165], v[170:173], v[134:137]
	v_mfma_f32_16x16x32_bf16 v[122:125], v[154:157], v[178:181], v[122:125]
	v_mfma_f32_16x16x32_bf16 v[118:121], v[162:165], v[178:181], v[118:121]
	v_mfma_f32_16x16x32_bf16 v[106:109], v[154:157], v[186:189], v[106:109]
	v_mfma_f32_16x16x32_bf16 v[102:105], v[162:165], v[186:189], v[102:105]
	v_mfma_f32_16x16x32_bf16 v[74:77], v[154:157], v[194:197], v[74:77]
	v_mfma_f32_16x16x32_bf16 v[70:73], v[162:165], v[194:197], v[70:73]
	s_barrier
	s_add_i32 s61, s61, s49
	v_lshl_add_u64 v[228:229], s[42:43], 0, v[212:213]
	s_mov_b32 m0, s61
	ds_read_b128 v[166:169], v237 offset:16384
	ds_read_b128 v[170:173], v237 offset:17408
	ds_read_b128 v[174:177], v237 offset:18432
	ds_read_b128 v[178:181], v237 offset:19456
	ds_read_b128 v[182:185], v237 offset:20480
	ds_read_b128 v[186:189], v237 offset:21504
	ds_read_b128 v[190:193], v237 offset:22528
	ds_read_b128 v[194:197], v237 offset:23552
	global_load_lds_dwordx4 v[228:229], off
	s_add_i32 m0, s61, 0x2000
	s_add_u32 s62, s42, 0x80000
	v_lshl_add_u64 v[230:231], s[42:43], 0, v[216:217]
	s_addc_u32 s63, s43, 0
	s_add_i32 s61, s64, s49
	global_load_lds_dwordx4 v[230:231], off
	v_lshl_add_u64 v[238:239], s[62:63], 0, v[212:213]
	s_mov_b32 m0, s61
	v_lshl_add_u64 v[240:241], s[44:45], 0, v[214:215]
	global_load_lds_dwordx4 v[238:239], off
	v_lshl_add_u64 v[238:239], s[62:63], 0, v[216:217]
	s_add_i32 m0, s61, 0x2000
	s_nop 0
	global_load_lds_dwordx4 v[238:239], off
	v_lshl_add_u64 v[238:239], s[44:45], 0, v[2:3]
	s_mov_b32 m0, s50
	s_nop 0
	global_load_lds_dwordx4 v[238:239], off
	s_mov_b32 m0, s51
	s_nop 0
	global_load_lds_dwordx4 v[240:241], off
	s_waitcnt vmcnt(8)
	s_waitcnt lgkmcnt(0)
	s_barrier
; #define PG8_STAGE(bufoff, gbase, voff) do { _Pragma("unroll") for (int _i = 0; _i < 2; ++_i) \
;         __builtin_amdgcn_global_load_lds((const unsigned*)((const char*)(gbase) + (voff)[_i]), (LAS unsigned*)(lds + (bufoff) + ldsw + _i * 8192), 16, 0, 0); } while (0)
; #define PG8_LDA(dst, b, h) do { _Pragma("unroll") for (int m = 0; m < 4; ++m) _Pragma("unroll") for (int k = 0; k < 2; ++k) dst[m][k] = *(const LAS bf16x8*)(lds + PG8_SA(b, h) + aoff + m * 2048 + k * 1024); } while (0)
; #define PG8_LDB(dst, b, h) do { _Pragma("unroll") for (int n = 0; n < 2; ++n) _Pragma("unroll") for (int k = 0; k < 2; ++k) dst[n][k] = *(const LAS bf16x8*)(lds + PG8_SB(b, h) + boff + n * 2048 + k * 1024); } while (0)
; #define PG8_MMA(ai, bj, At, Bt) do { __builtin_amdgcn_s_setprio(1); _Pragma("unroll") for (int m = 0; m < 4; ++m) _Pragma("unroll") for (int n = 0; n < 2; ++n) _Pragma("unroll") for (int k = 0; k < 2; ++k) \
;         acc[ai][bj][m][n] = __builtin_amdgcn_mfma_f32_16x16x32_bf16(Bt[n][k], At[m][k], acc[ai][bj][m][n], 0, 0, 0); __builtin_amdgcn_s_setprio(0); } while (0)
; #define PG8_WAIT_V(n) asm volatile("s_waitcnt vmcnt(" #n ")" ::: "memory")
; #define PG8_WAIT_L(n) asm volatile("s_waitcnt lgkmcnt(" #n ")" ::: "memory")
; #define PG8_BAR __builtin_amdgcn_s_barrier()
; #define PG8_SCHED __builtin_amdgcn_sched_barrier(0)
; template <class Epi, class Sched>
; __device__ __forceinline__ void gemm_phase(LAS unsigned char* lds, const Gemm g, const Sched& S, const Epi& E) {
;     ...
;             PG8_WAIT_V(8); PG8_WAIT_L(0); PG8_BAR; PG8_MMA(1, 0, At, B0); PG8_MMA(1, 1, At, B1); PG8_BAR; PG8_SCHED;
;             PG8_LDB(B0, 1, 0); PG8_LDB(B1, 1, 1); PG8_SCHED; PG8_LDA(At, 1, 0); PG8_STAGE(PG8_SA(0, 1), a2 + hstepA, voffA);
;             PG8_WAIT_V(8); PG8_WAIT_L(0); PG8_BAR; PG8_MMA(0, 0, At, B0); PG8_MMA(0, 1, At, B1); PG8_BAR; PG8_SCHED;
	s_waitcnt lgkmcnt(0)
	v_mfma_f32_16x16x32_bf16 v[66:69], v[86:89], v[166:169], v[66:69]
	v_mfma_f32_16x16x32_bf16 v[62:65], v[94:97], v[166:169], v[62:65]
	v_mfma_f32_16x16x32_bf16 v[50:53], v[86:89], v[174:177], v[50:53]
	v_mfma_f32_16x16x32_bf16 v[46:49], v[94:97], v[174:177], v[46:49]
	v_mfma_f32_16x16x32_bf16 v[34:37], v[86:89], v[182:185], v[34:37]
	v_mfma_f32_16x16x32_bf16 v[30:33], v[94:97], v[182:185], v[30:33]
	v_mfma_f32_16x16x32_bf16 v[18:21], v[86:89], v[190:193], v[18:21]
	v_mfma_f32_16x16x32_bf16 v[14:17], v[94:97], v[190:193], v[14:17]
	v_mfma_f32_16x16x32_bf16 v[66:69], v[90:93], v[170:173], v[66:69]
	v_mfma_f32_16x16x32_bf16 v[62:65], v[98:101], v[170:173], v[62:65]
	v_mfma_f32_16x16x32_bf16 v[50:53], v[90:93], v[178:181], v[50:53]
	v_mfma_f32_16x16x32_bf16 v[46:49], v[98:101], v[178:181], v[46:49]
	v_mfma_f32_16x16x32_bf16 v[34:37], v[90:93], v[186:189], v[34:37]
	v_mfma_f32_16x16x32_bf16 v[30:33], v[98:101], v[186:189], v[30:33]
	v_mfma_f32_16x16x32_bf16 v[18:21], v[90:93], v[194:197], v[18:21]
	v_mfma_f32_16x16x32_bf16 v[14:17], v[98:101], v[194:197], v[14:17]
	v_mfma_f32_16x16x32_bf16 v[58:61], v[150:153], v[166:169], v[58:61]
	v_mfma_f32_16x16x32_bf16 v[54:57], v[158:161], v[166:169], v[54:57]
	v_mfma_f32_16x16x32_bf16 v[42:45], v[150:153], v[174:177], v[42:45]
	v_mfma_f32_16x16x32_bf16 v[38:41], v[158:161], v[174:177], v[38:41]
	v_mfma_f32_16x16x32_bf16 v[26:29], v[150:153], v[182:185], v[26:29]
	v_mfma_f32_16x16x32_bf16 v[22:25], v[158:161], v[182:185], v[22:25]
	v_mfma_f32_16x16x32_bf16 v[10:13], v[150:153], v[190:193], v[10:13]
	v_mfma_f32_16x16x32_bf16 v[6:9], v[158:161], v[190:193], v[6:9]
	v_mfma_f32_16x16x32_bf16 v[58:61], v[154:157], v[170:173], v[58:61]
	v_mfma_f32_16x16x32_bf16 v[54:57], v[162:165], v[170:173], v[54:57]
	v_mfma_f32_16x16x32_bf16 v[42:45], v[154:157], v[178:181], v[42:45]
	v_mfma_f32_16x16x32_bf16 v[38:41], v[162:165], v[178:181], v[38:41]
	v_mfma_f32_16x16x32_bf16 v[26:29], v[154:157], v[186:189], v[26:29]
	v_mfma_f32_16x16x32_bf16 v[22:25], v[162:165], v[186:189], v[22:25]
	v_mfma_f32_16x16x32_bf16 v[10:13], v[154:157], v[194:197], v[10:13]
	v_mfma_f32_16x16x32_bf16 v[6:9], v[162:165], v[194:197], v[6:9]
	s_barrier
	s_add_i32 s61, 0, 0x18000
	s_add_i32 s62, 0, 0x1c000
	v_add_u32_e32 v98, s61, v236
	v_add_u32_e32 v162, s62, v236
	ds_read_b128 v[86:89], v98
	ds_read_b128 v[90:93], v98 offset:1024
	ds_read_b128 v[94:97], v98 offset:2048
	ds_read_b128 v[98:101], v98 offset:3072
	ds_read_b128 v[150:153], v162
	ds_read_b128 v[154:157], v162 offset:1024
	ds_read_b128 v[158:161], v162 offset:2048
	ds_read_b128 v[162:165], v162 offset:3072
	s_add_u32 s44, s44, 0x80000
	s_addc_u32 s45, s45, 0
	s_mov_b32 m0, s52
	v_lshl_add_u64 v[242:243], s[44:45], 0, v[2:3]
	ds_read_b128 v[166:169], v237 offset:32768
	ds_read_b128 v[170:173], v237 offset:33792
	ds_read_b128 v[174:177], v237 offset:34816
	ds_read_b128 v[178:181], v237 offset:35840
	ds_read_b128 v[182:185], v237 offset:36864
	ds_read_b128 v[186:189], v237 offset:37888
	ds_read_b128 v[190:193], v237 offset:38912
	ds_read_b128 v[194:197], v237 offset:39936
	global_load_lds_dwordx4 v[242:243], off
	v_lshl_add_u64 v[242:243], s[44:45], 0, v[214:215]
	s_mov_b32 m0, s53
	s_nop 0
	global_load_lds_dwordx4 v[242:243], off
	s_waitcnt vmcnt(8)
	s_waitcnt lgkmcnt(0)
	s_barrier
	s_waitcnt lgkmcnt(0)
	v_mfma_f32_16x16x32_bf16 v[146:149], v[86:89], v[166:169], v[146:149]
	v_mfma_f32_16x16x32_bf16 v[142:145], v[94:97], v[166:169], v[142:145]
	v_mfma_f32_16x16x32_bf16 v[130:133], v[86:89], v[174:177], v[130:133]
	v_mfma_f32_16x16x32_bf16 v[126:129], v[94:97], v[174:177], v[126:129]
	v_mfma_f32_16x16x32_bf16 v[114:117], v[86:89], v[182:185], v[114:117]
	v_mfma_f32_16x16x32_bf16 v[110:113], v[94:97], v[182:185], v[110:113]
	v_mfma_f32_16x16x32_bf16 v[82:85], v[86:89], v[190:193], v[82:85]
	v_mfma_f32_16x16x32_bf16 v[78:81], v[94:97], v[190:193], v[78:81]
	v_mfma_f32_16x16x32_bf16 v[146:149], v[90:93], v[170:173], v[146:149]
	v_mfma_f32_16x16x32_bf16 v[142:145], v[98:101], v[170:173], v[142:145]
	v_mfma_f32_16x16x32_bf16 v[130:133], v[90:93], v[178:181], v[130:133]
	v_mfma_f32_16x16x32_bf16 v[126:129], v[98:101], v[178:181], v[126:129]
	v_mfma_f32_16x16x32_bf16 v[114:117], v[90:93], v[186:189], v[114:117]
	v_mfma_f32_16x16x32_bf16 v[110:113], v[98:101], v[186:189], v[110:113]
	v_mfma_f32_16x16x32_bf16 v[82:85], v[90:93], v[194:197], v[82:85]
	v_mfma_f32_16x16x32_bf16 v[78:81], v[98:101], v[194:197], v[78:81]
	v_mfma_f32_16x16x32_bf16 v[138:141], v[150:153], v[166:169], v[138:141]
	v_mfma_f32_16x16x32_bf16 v[134:137], v[158:161], v[166:169], v[134:137]
	v_mfma_f32_16x16x32_bf16 v[122:125], v[150:153], v[174:177], v[122:125]
	v_mfma_f32_16x16x32_bf16 v[118:121], v[158:161], v[174:177], v[118:121]
	v_mfma_f32_16x16x32_bf16 v[106:109], v[150:153], v[182:185], v[106:109]
	v_mfma_f32_16x16x32_bf16 v[102:105], v[158:161], v[182:185], v[102:105]
	v_mfma_f32_16x16x32_bf16 v[74:77], v[150:153], v[190:193], v[74:77]
	v_mfma_f32_16x16x32_bf16 v[70:73], v[158:161], v[190:193], v[70:73]
	v_mfma_f32_16x16x32_bf16 v[138:141], v[154:157], v[170:173], v[138:141]
	v_mfma_f32_16x16x32_bf16 v[134:137], v[162:165], v[170:173], v[134:137]
	v_mfma_f32_16x16x32_bf16 v[122:125], v[154:157], v[178:181], v[122:125]
	v_mfma_f32_16x16x32_bf16 v[118:121], v[162:165], v[178:181], v[118:121]
	v_mfma_f32_16x16x32_bf16 v[106:109], v[154:157], v[186:189], v[106:109]
	v_mfma_f32_16x16x32_bf16 v[102:105], v[162:165], v[186:189], v[102:105]
	v_mfma_f32_16x16x32_bf16 v[74:77], v[154:157], v[194:197], v[74:77]
	v_mfma_f32_16x16x32_bf16 v[70:73], v[162:165], v[194:197], v[70:73]
	s_barrier
; #define PG8_STAGE(bufoff, gbase, voff) do { _Pragma("unroll") for (int _i = 0; _i < 2; ++_i) \
;         __builtin_amdgcn_global_load_lds((const unsigned*)((const char*)(gbase) + (voff)[_i]), (LAS unsigned*)(lds + (bufoff) + ldsw + _i * 8192), 16, 0, 0); } while (0)
; #define PG8_LDA(dst, b, h) do { _Pragma("unroll") for (int m = 0; m < 4; ++m) _Pragma("unroll") for (int k = 0; k < 2; ++k) dst[m][k] = *(const LAS bf16x8*)(lds + PG8_SA(b, h) + aoff + m * 2048 + k * 1024); } while (0)
; #define PG8_MMA(ai, bj, At, Bt) do { __builtin_amdgcn_s_setprio(1); _Pragma("unroll") for (int m = 0; m < 4; ++m) _Pragma("unroll") for (int n = 0; n < 2; ++n) _Pragma("unroll") for (int k = 0; k < 2; ++k) \
;         acc[ai][bj][m][n] = __builtin_amdgcn_mfma_f32_16x16x32_bf16(Bt[n][k], At[m][k], acc[ai][bj][m][n], 0, 0, 0); __builtin_amdgcn_s_setprio(0); } while (0)
; #define PG8_WAIT_V(n) asm volatile("s_waitcnt vmcnt(" #n ")" ::: "memory")
; #define PG8_WAIT_L(n) asm volatile("s_waitcnt lgkmcnt(" #n ")" ::: "memory")
; #define PG8_BAR __builtin_amdgcn_s_barrier()
; #define PG8_SCHED __builtin_amdgcn_sched_barrier(0)
; template <class Epi, class Sched>
; __device__ __forceinline__ void gemm_phase(LAS unsigned char* lds, const Gemm g, const Sched& S, const Epi& E) {
;     ...
;             PG8_LDA(At, 1, 1); PG8_STAGE(PG8_SB(1, 0), b3, voffB); PG8_STAGE(PG8_SB(1, 1), b3 + hstepB, voffB); PG8_STAGE(PG8_SA(1, 0), a3, voffA);
;             PG8_WAIT_V(8); PG8_WAIT_L(0); PG8_BAR; PG8_MMA(1, 0, At, B0); PG8_MMA(1, 1, At, B1); PG8_BAR; PG8_SCHED;
;         }
;         if (wr == 0) PG8_BAR;
	s_add_i32 s44, s61, s49
	v_lshl_add_u64 v[228:229], v[228:229], 0, s[36:37]
	s_mov_b32 m0, s44
	ds_read_b128 v[166:169], v237 offset:49152
	ds_read_b128 v[170:173], v237 offset:50176
	ds_read_b128 v[174:177], v237 offset:51200
	ds_read_b128 v[178:181], v237 offset:52224
	ds_read_b128 v[182:185], v237 offset:53248
	ds_read_b128 v[186:189], v237 offset:54272
	ds_read_b128 v[190:193], v237 offset:55296
	ds_read_b128 v[194:197], v237 offset:56320
	global_load_lds_dwordx4 v[228:229], off
	s_add_i32 m0, s44, 0x2000
	s_add_u32 s42, s42, 0x80080
	v_lshl_add_u64 v[228:229], v[230:231], 0, s[36:37]
	s_addc_u32 s43, s43, 0
	s_add_i32 s44, s62, s49
	global_load_lds_dwordx4 v[228:229], off
	v_lshl_add_u64 v[228:229], s[42:43], 0, v[212:213]
	s_mov_b32 m0, s44
	s_nop 0
	global_load_lds_dwordx4 v[228:229], off
	v_lshl_add_u64 v[228:229], s[42:43], 0, v[216:217]
	s_add_i32 m0, s44, 0x2000
	s_nop 0
	global_load_lds_dwordx4 v[228:229], off
	v_lshl_add_u64 v[228:229], v[238:239], 0, s[36:37]
	s_mov_b32 m0, s54
	s_nop 0
	global_load_lds_dwordx4 v[228:229], off
	v_lshl_add_u64 v[228:229], v[240:241], 0, s[36:37]
	s_mov_b32 m0, s55
	s_nop 0
	global_load_lds_dwordx4 v[228:229], off
	s_waitcnt vmcnt(8)
	s_waitcnt lgkmcnt(0)
	s_barrier
	s_waitcnt lgkmcnt(0)
	v_mfma_f32_16x16x32_bf16 v[66:69], v[86:89], v[166:169], v[66:69]
	v_mfma_f32_16x16x32_bf16 v[62:65], v[94:97], v[166:169], v[62:65]
	v_mfma_f32_16x16x32_bf16 v[50:53], v[86:89], v[174:177], v[50:53]
	v_mfma_f32_16x16x32_bf16 v[46:49], v[94:97], v[174:177], v[46:49]
	v_mfma_f32_16x16x32_bf16 v[34:37], v[86:89], v[182:185], v[34:37]
	v_mfma_f32_16x16x32_bf16 v[30:33], v[94:97], v[182:185], v[30:33]
	v_mfma_f32_16x16x32_bf16 v[18:21], v[86:89], v[190:193], v[18:21]
	v_mfma_f32_16x16x32_bf16 v[14:17], v[94:97], v[190:193], v[14:17]
	v_mfma_f32_16x16x32_bf16 v[66:69], v[90:93], v[170:173], v[66:69]
	v_mfma_f32_16x16x32_bf16 v[62:65], v[98:101], v[170:173], v[62:65]
	v_mfma_f32_16x16x32_bf16 v[50:53], v[90:93], v[178:181], v[50:53]
	v_mfma_f32_16x16x32_bf16 v[46:49], v[98:101], v[178:181], v[46:49]
	v_mfma_f32_16x16x32_bf16 v[34:37], v[90:93], v[186:189], v[34:37]
	v_mfma_f32_16x16x32_bf16 v[30:33], v[98:101], v[186:189], v[30:33]
	v_mfma_f32_16x16x32_bf16 v[18:21], v[90:93], v[194:197], v[18:21]
	v_mfma_f32_16x16x32_bf16 v[14:17], v[98:101], v[194:197], v[14:17]
	v_mfma_f32_16x16x32_bf16 v[58:61], v[150:153], v[166:169], v[58:61]
	v_mfma_f32_16x16x32_bf16 v[54:57], v[158:161], v[166:169], v[54:57]
	v_mfma_f32_16x16x32_bf16 v[42:45], v[150:153], v[174:177], v[42:45]
	v_mfma_f32_16x16x32_bf16 v[38:41], v[158:161], v[174:177], v[38:41]
	v_mfma_f32_16x16x32_bf16 v[26:29], v[150:153], v[182:185], v[26:29]
	v_mfma_f32_16x16x32_bf16 v[22:25], v[158:161], v[182:185], v[22:25]
	v_mfma_f32_16x16x32_bf16 v[10:13], v[150:153], v[190:193], v[10:13]
	v_mfma_f32_16x16x32_bf16 v[6:9], v[158:161], v[190:193], v[6:9]
	v_mfma_f32_16x16x32_bf16 v[58:61], v[154:157], v[170:173], v[58:61]
	v_mfma_f32_16x16x32_bf16 v[54:57], v[162:165], v[170:173], v[54:57]
	v_mfma_f32_16x16x32_bf16 v[42:45], v[154:157], v[178:181], v[42:45]
	v_mfma_f32_16x16x32_bf16 v[38:41], v[162:165], v[178:181], v[38:41]
	v_mfma_f32_16x16x32_bf16 v[26:29], v[154:157], v[186:189], v[26:29]
	v_mfma_f32_16x16x32_bf16 v[22:25], v[162:165], v[186:189], v[22:25]
	v_mfma_f32_16x16x32_bf16 v[10:13], v[154:157], v[194:197], v[10:13]
	v_mfma_f32_16x16x32_bf16 v[6:9], v[162:165], v[194:197], v[6:9]
	s_barrier
	s_add_i32 s60, s60, 2
	s_add_u32 s38, s38, 0x100
	s_addc_u32 s39, s39, 0
	s_add_u32 s58, s58, 0x100
	s_addc_u32 s59, s59, 0
	s_cmp_gt_u32 s60, 29
	s_cbranch_scc0 .LBB0_513
	s_and_b64 vcc, exec, s[16:17]
	s_cbranch_vccz .LBB0_516
	s_barrier

; __device__ __forceinline__ unsigned xb_ld(unsigned* p)              { return __hip_atomic_load(p, __ATOMIC_RELAXED, __HIP_MEMORY_SCOPE_AGENT); }
; #define XB_SPIN(cond, bar) do { unsigned _sp = 0; while (cond) { __builtin_amdgcn_s_sleep(1); \
;     if ((++_sp & 255u) == 0u) { if (xb_ld(&(bar)[XB_TMO])) break; if (_sp > XB_SPIN_CAP) { atomicAdd(&(bar)[XB_TMO], 1u); break; } } } } while (0)
; __device__ __forceinline__ void xcd_barrier(const XcdBarrier& b) {
;     asm volatile("s_waitcnt vmcnt(0)" ::: "memory");
;     __syncthreads();
;     if (threadIdx.x == 0) {
;         unsigned* bar = b.bar;
;         __builtin_amdgcn_s_waitcnt(0);
;         unsigned nloc = b.st[0], nx = b.st[1];
;         if (nloc == 0u) { xcd_barrier_complete(bar, b.x, nloc, nx); b.st[0] = nloc; b.st[1] = nx; }
;         const unsigned k1 = b.st[2] + 1u, rank = b.st[3]; b.st[2] = k1;
;         (void)__hip_atomic_fetch_add(&bar[XB_XSUB(b.x)], 1u, __ATOMIC_RELAXED, __HIP_MEMORY_SCOPE_AGENT);
;         if (rank == 0u) {
;             XB_SPIN(xb_ld(&bar[XB_XSUB(b.x)]) < k1 * nloc, bar);
;             __builtin_amdgcn_fence(__ATOMIC_RELEASE, "agent");
;             asm volatile("s_waitcnt vmcnt(0)" ::: "memory");
;             (void)__hip_atomic_fetch_add(&bar[XB_TOP], 1u, __ATOMIC_RELAXED, __HIP_MEMORY_SCOPE_AGENT);
;         }
;         XB_SPIN(xb_ld(&bar[XB_TOP]) < k1 * nx, bar);
;         __builtin_amdgcn_fence(__ATOMIC_ACQUIRE, "agent");
;         asm volatile("s_waitcnt vmcnt(0)" ::: "memory");
;     }
;     __syncthreads();
.LBB0_550:
	v_readlane_b32 s4, v254, 45
	v_readlane_b32 s5, v254, 46
	s_andn2_b64 vcc, exec, s[4:5]
	s_cbranch_vccnz .LBB0_592
	s_setprio 0
	s_mov_b64 s[6:7], s[96:97]
	s_waitcnt vmcnt(0)
	s_barrier
	s_mov_b64 s[4:5], exec
	v_readlane_b32 s8, v254, 21
	v_readlane_b32 s9, v254, 22
	s_and_b64 s[8:9], s[4:5], s[8:9]
	s_mov_b64 exec, s[8:9]
	s_cbranch_execz .LBB0_591
	v_mov_b32_e32 v2, s93
	s_waitcnt vmcnt(0) expcnt(0) lgkmcnt(0)
	ds_read_b32 v4, v2
	ds_read_b32 v2, v2 offset:4
	s_waitcnt lgkmcnt(1)
	v_cmp_ne_u32_e32 vcc, 0, v4
	s_cbranch_vccnz .LBB0_566
	s_load_dwordx2 s[12:13], s[94:95], 0x4
	s_add_u32 s8, s6, 0x1000
	s_addc_u32 s9, s7, 0
	s_add_u32 s10, s6, 0x1100
	s_addc_u32 s11, s7, 0
	s_waitcnt lgkmcnt(0)
	s_mul_i32 s34, s12, s92
	s_add_u32 s12, s6, 0x1200
	s_mul_i32 s34, s34, s13
	s_addc_u32 s13, s7, 0
	s_add_u32 s14, s6, 0x1300
	s_addc_u32 s15, s7, 0
	s_mov_b32 s42, 1
	s_mov_b64 s[16:17], 0
	s_branch .LBB0_556

; __device__ __forceinline__ unsigned xb_ld(unsigned* p)              { return __hip_atomic_load(p, __ATOMIC_RELAXED, __HIP_MEMORY_SCOPE_AGENT); }
; #define XB_SPIN(cond, bar) do { unsigned _sp = 0; while (cond) { __builtin_amdgcn_s_sleep(1); \
;     if ((++_sp & 255u) == 0u) { if (xb_ld(&(bar)[XB_TMO])) break; if (_sp > XB_SPIN_CAP) { atomicAdd(&(bar)[XB_TMO], 1u); break; } } } } while (0)
; __device__ __forceinline__ void xcd_barrier(const XcdBarrier& b) {
;     asm volatile("s_waitcnt vmcnt(0)" ::: "memory");
;     __syncthreads();
;     if (threadIdx.x == 0) {
;         unsigned* bar = b.bar;
;         __builtin_amdgcn_s_waitcnt(0);
;         unsigned nloc = b.st[0], nx = b.st[1];
;         if (nloc == 0u) { xcd_barrier_complete(bar, b.x, nloc, nx); b.st[0] = nloc; b.st[1] = nx; }
;         const unsigned k1 = b.st[2] + 1u, rank = b.st[3]; b.st[2] = k1;
;         (void)__hip_atomic_fetch_add(&bar[XB_XSUB(b.x)], 1u, __ATOMIC_RELAXED, __HIP_MEMORY_SCOPE_AGENT);
;         if (rank == 0u) {
;             XB_SPIN(xb_ld(&bar[XB_XSUB(b.x)]) < k1 * nloc, bar);
;             __builtin_amdgcn_fence(__ATOMIC_RELEASE, "agent");
;             asm volatile("s_waitcnt vmcnt(0)" ::: "memory");
;             (void)__hip_atomic_fetch_add(&bar[XB_TOP], 1u, __ATOMIC_RELAXED, __HIP_MEMORY_SCOPE_AGENT);
;         }
;         XB_SPIN(xb_ld(&bar[XB_TOP]) < k1 * nx, bar);
;         __builtin_amdgcn_fence(__ATOMIC_ACQUIRE, "agent");
;         asm volatile("s_waitcnt vmcnt(0)" ::: "memory");
;     }
;     __syncthreads();
.LBB0_600:
	v_readlane_b32 s4, v254, 49
	v_readlane_b32 s5, v254, 50
	v_readlane_b32 s90, v254, 25
	v_readlane_b32 s94, v254, 28
	v_readlane_b32 s96, v254, 30
	v_readlane_b32 s66, v255, 6
	s_andn2_b64 vcc, exec, s[4:5]
	s_mov_b64 s[6:7], 0
	v_readlane_b32 s89, v254, 27
	v_readlane_b32 s91, v254, 26
	v_readlane_b32 s95, v254, 29
	v_readlane_b32 s97, v254, 31
	v_readlane_b32 s93, v254, 32
	v_readlane_b32 s70, v254, 23
	v_readlane_b32 s71, v254, 24
	v_readlane_b32 s62, v254, 18
	v_readlane_b32 s67, v255, 7
	s_mov_b64 s[46:47], 0
	s_cbranch_vccnz .LBB0_642
	s_setprio 0
	s_mov_b64 s[6:7], s[96:97]
	s_waitcnt vmcnt(0)
	s_barrier
	s_mov_b64 s[4:5], exec
	v_readlane_b32 s8, v254, 21
	v_readlane_b32 s9, v254, 22
	s_and_b64 s[8:9], s[4:5], s[8:9]
	s_mov_b64 exec, s[8:9]
	s_cbranch_execz .LBB0_641
	v_mov_b32_e32 v2, s93
	s_waitcnt vmcnt(0) expcnt(0) lgkmcnt(0)
	ds_read_b32 v4, v2
	ds_read_b32 v2, v2 offset:4
	s_waitcnt lgkmcnt(1)
	v_cmp_ne_u32_e32 vcc, 0, v4
	s_cbranch_vccnz .LBB0_616
	s_load_dwordx2 s[12:13], s[94:95], 0x4
	s_add_u32 s8, s6, 0x1000
	s_addc_u32 s9, s7, 0
	s_add_u32 s10, s6, 0x1100
	s_addc_u32 s11, s7, 0
	s_waitcnt lgkmcnt(0)
	s_mul_i32 s34, s12, s92
	s_add_u32 s12, s6, 0x1200
	s_mul_i32 s34, s34, s13
	s_addc_u32 s13, s7, 0
	s_add_u32 s14, s6, 0x1300
	s_addc_u32 s15, s7, 0
	s_mov_b32 s42, 1
	s_mov_b64 s[16:17], 0
	s_branch .LBB0_606

; #define PG8_STAGE(bufoff, gbase, voff) do { _Pragma("unroll") for (int _i = 0; _i < 2; ++_i) \
;         __builtin_amdgcn_global_load_lds((const unsigned*)((const char*)(gbase) + (voff)[_i]), (LAS unsigned*)(lds + (bufoff) + ldsw + _i * 8192), 16, 0, 0); } while (0)
; #define PG8_WAIT_V(n) asm volatile("s_waitcnt vmcnt(" #n ")" ::: "memory")
; #define PG8_BAR __builtin_amdgcn_s_barrier()
; template <class Epi, class Sched>
; __device__ __forceinline__ void gemm_phase(LAS unsigned char* lds, const Gemm g, const Sched& S, const Epi& E) {
;     ...
;     for (int i = 0; i < 2; ++i) { int R, C; stage_rc(tid * 16 + i * 8192, R, C); const int Rb = Epi::PERM ? ((R & ~31) + perm32(R & 31)) : R;
;         voffA[i] = (unsigned)(R * g.lda + C) * 2u; voffB[i] = (unsigned)(Rb * g.ldb + C) * 2u; }
;     const size_t kstep = (size_t)(BK * 2);
;     const size_t hstepA = (size_t)HALF * g.lda * 2, hstepB = (size_t)HALF * g.ldb * 2;
;     const size_t tstepA = 2 * hstepA, tstepB = 2 * hstepB;
;     const unsigned ldsw = (unsigned)wid * 1024u;
;     const int aoff = lds_byte(wr * 64 + fr, fq * 8), boff = lds_byte(wc * 32 + fr, fq * 8);
;     ...
;     Unit cur, nxt; int ui = 0;
;     if (!S.next(0, cur)) return;
;     f32x4 acc[2][2][4][2];
; #pragma unroll
;     for (int a = 0; a < 2; ++a)
; #pragma unroll
;         for (int b = 0; b < 2; ++b)
; #pragma unroll
;             for (int m = 0; m < 4; ++m)
; #pragma unroll
;                 for (int n = 0; n < 2; ++n) acc[a][b][m][n] = (f32x4){0.f, 0.f, 0.f, 0.f};
;     bf16x8 At[4][2], B0[2][2], B1[2][2];
;     const char* cA = (const char*)g.A + (size_t)cur.pm * tstepA + (size_t)cur.ka * 2; const char* cB = (const char*)g.Bt + (size_t)cur.pn * tstepB;
;     S.a_ready(cur);
;     PG8_STAGE(PG8_SB(0, 0), cB, voffB); PG8_STAGE(PG8_SB(0, 1), cB + hstepB, voffB); PG8_STAGE(PG8_SA(0, 0), cA, voffA); PG8_STAGE(PG8_SA(0, 1), cA + hstepA, voffA);
;     if (wr == 1) PG8_BAR;
;     PG8_WAIT_V(2); PG8_BAR;
;     PG8_STAGE(PG8_SB(1, 0), cB + kstep, voffB); PG8_STAGE(PG8_SA(1, 0), cA + kstep, voffA); PG8_STAGE(PG8_SB(1, 1), cB + hstepB + kstep, voffB);
;     PG8_WAIT_V(6); PG8_BAR;
.LBB0_646:
	s_and_b64 vcc, exec, s[4:5]
	s_cbranch_vccnz .LBB0_730
	v_ashrrev_i32_e32 v2, 31, v4
	v_lshrrev_b32_e32 v2, 26, v2
	v_add_u32_e32 v2, v4, v2
	v_ashrrev_i32_e32 v14, 6, v2
	v_bfe_i32 v2, v4, 27, 1
	v_lshlrev_b32_e32 v3, 4, v4
	v_lshrrev_b32_e32 v2, 22, v2
	v_add_u32_e32 v2, v3, v2
	v_and_b32_e32 v2, 0xfffffc00, v2
	v_sub_u32_e32 v2, v3, v2
	s_waitcnt vmcnt(0)
	v_lshrrev_b32_e32 v6, 4, v2
	v_bitop3_b32 v2, v6, v2, 32 bitop3:0x6c
	v_ashrrev_i32_e32 v7, 31, v2
	v_lshrrev_b32_e32 v7, 26, v7
	v_add_u32_e32 v7, v2, v7
	v_lshlrev_b32_e32 v6, 3, v14
	v_ashrrev_i32_e32 v15, 6, v7
	v_and_b32_e32 v7, 0xc0, v7
	v_and_b32_e32 v6, -16, v6
	v_sub_u32_e32 v2, v2, v7
	v_add_u32_e32 v6, v15, v6
	v_lshlrev_b32_e32 v8, 5, v14
	v_ashrrev_i16_sdwa v2, v232, sext(v2) dst_sel:DWORD dst_unused:UNUSED_PAD src0_sel:DWORD src1_sel:BYTE_0
	v_and_b32_e32 v8, 32, v8
	v_bfe_i32 v16, v2, 0, 16
	v_lshlrev_b32_e32 v2, 1, v6
	v_lshrrev_b32_e32 v7, 2, v6
	v_and_b32_e32 v9, 3, v15
	s_mov_b32 s4, 0xfffe0
	v_and_b32_e32 v2, 24, v2
	v_and_b32_e32 v7, 4, v7
	v_and_or_b32 v9, v6, s4, v9
	v_add_lshl_u32 v8, v8, v16, 1
	v_add_u32_e32 v3, 0x2000, v3
	v_or3_b32 v7, v9, v7, v2
	v_lshl_add_u32 v2, v6, 12, v8
	v_ashrrev_i32_e32 v6, 31, v3
	v_lshrrev_b32_e32 v6, 22, v6
	v_add_u32_e32 v6, v3, v6
	v_ashrrev_i32_e32 v17, 10, v6
	s_load_dwordx2 s[14:15], s[8:9], 0x98
	v_mul_i32_i24_e32 v6, 0x400, v17
	v_sub_u32_e32 v3, v3, v6
	v_lshrrev_b32_e32 v6, 4, v3
	v_bitop3_b32 v3, v6, v3, 32 bitop3:0x6c
	v_lshl_add_u32 v182, v7, 12, v8
	v_ashrrev_i32_e32 v7, 31, v3
	s_waitcnt lgkmcnt(0)
	s_add_u32 s42, s14, 0x9000000
	v_lshrrev_b32_e32 v7, 26, v7
	s_addc_u32 s43, s15, 0
	v_lshlrev_b32_e32 v6, 3, v17
	v_add_u32_e32 v7, v3, v7
	s_add_u32 s44, s14, 0x41c00000
	v_and_b32_e32 v6, -16, v6
	v_ashrrev_i32_e32 v18, 6, v7
	s_addc_u32 s45, s15, 0
	s_ashr_i32 s13, s12, 6
	v_add_u32_e32 v6, v18, v6
	v_and_b32_e32 v9, 3, v18
	s_ashr_i32 s25, s24, 31
	v_and_or_b32 v9, v6, s4, v9
	s_ashr_i32 s16, s12, 8
	s_lshl_b32 s46, s13, 10
	s_lshl_b64 s[4:5], s[24:25], 20
	s_add_u32 s26, s42, s4
	v_and_b32_e32 v7, 0xc0, v7
	s_addc_u32 s27, s43, s5
	s_ashr_i32 s23, s22, 31
	v_sub_u32_e32 v3, v3, v7
	s_lshl_b64 s[4:5], s[22:23], 20
	v_ashrrev_i16_sdwa v3, v232, sext(v3) dst_sel:DWORD dst_unused:UNUSED_PAD src0_sel:DWORD src1_sel:BYTE_0
	s_add_u32 s28, s44, s4
	v_lshlrev_b32_e32 v8, 5, v17
	v_bfe_i32 v19, v3, 0, 16
	v_lshlrev_b32_e32 v3, 1, v6
	v_lshrrev_b32_e32 v7, 2, v6
	s_addc_u32 s29, s45, s5
	s_add_i32 s47, s46, 0
	v_and_b32_e32 v8, 32, v8
	v_and_b32_e32 v3, 24, v3
	v_and_b32_e32 v7, 4, v7
	s_add_i32 m0, s47, 0x10000
	v_or3_b32 v3, v9, v7, v3
	v_add_lshl_u32 v7, v8, v19, 1
	global_load_lds_dwordx4 v182, s[28:29]
	s_add_i32 m0, s47, 0x12000
	v_lshl_add_u32 v186, v3, 12, v7
	s_add_u32 s4, s28, 0x80000
	global_load_lds_dwordx4 v186, s[28:29]
	s_addc_u32 s5, s29, 0
	s_add_i32 m0, s47, 0x14000
	s_add_i32 s48, s47, 0x2000
	global_load_lds_dwordx4 v182, s[4:5]
	s_add_i32 m0, s47, 0x16000
	v_lshl_add_u32 v184, v6, 12, v7
	global_load_lds_dwordx4 v186, s[4:5]
	s_mov_b32 m0, s47
	s_add_u32 s4, s26, 0x80000
	global_load_lds_dwordx4 v2, s[26:27]
	s_mov_b32 m0, s48
	s_addc_u32 s5, s27, 0
	s_add_i32 s49, s47, 0x4000
	global_load_lds_dwordx4 v184, s[26:27]
	s_mov_b32 m0, s49
	s_add_i32 s50, s47, 0x6000
	global_load_lds_dwordx4 v2, s[4:5]
	s_mov_b32 m0, s50
	v_mov_b32_e32 v183, v5
	global_load_lds_dwordx4 v184, s[4:5]
	v_mov_b32_e32 v187, v5
	v_mov_b32_e32 v3, v5
	v_mov_b32_e32 v185, v5
	s_cmp_eq_u32 s16, 1
	s_waitcnt vmcnt(0)
	v_lshl_add_u64 v[12:13], s[28:29], 0, v[182:183]
	v_lshl_add_u64 v[10:11], s[28:29], 0, v[186:187]
	v_lshl_add_u64 v[6:7], s[26:27], 0, v[2:3]
	s_cselect_b64 s[4:5], -1, 0
	s_cmp_lg_u32 s16, 1
	v_lshl_add_u64 v[8:9], s[26:27], 0, v[184:185]
	s_cbranch_scc1 .LBB0_649
	s_barrier
	s_setprio 1
.LBB0_649:
	s_add_u32 s8, s14, 0xd000000
	v_lshrrev_b32_e32 v20, 1, v4
	s_addc_u32 s9, s15, 0
	v_and_b32_e32 v189, 15, v4
	v_and_b32_e32 v21, 24, v20
	s_add_u32 s10, s14, 0x100000
	v_lshlrev_b32_e32 v20, 1, v21
	v_lshlrev_b32_e32 v22, 6, v189
	v_lshlrev_b32_e32 v4, 2, v4
	s_addc_u32 s11, s15, 0
	s_and_b32 s18, s13, 3
	v_or_b32_e32 v23, v22, v20
	s_lshl_b32 s13, s16, 13
	v_and_b32_e32 v4, 32, v4
	s_add_i32 m0, s47, 0x18000
	v_lshl_add_u64 v[12:13], v[12:13], 0, s[36:37]
	s_lshl_b32 s51, s16, 6
	v_bitop3_b32 v24, v23, s13, v4 bitop3:0xde
	s_lshl_b32 s13, s18, 12
	s_waitcnt vmcnt(2)
	s_barrier
	global_load_lds_dwordx4 v[12:13], off
	v_lshl_add_u64 v[10:11], v[10:11], 0, s[36:37]
	s_add_i32 m0, s47, 0x1a000
	s_add_i32 s52, s47, 0x8000
	s_add_i32 s53, s47, 0xa000
	global_load_lds_dwordx4 v[10:11], off
	v_lshl_add_u64 v[6:7], v[6:7], 0, s[36:37]
	s_mov_b32 m0, s52
	s_add_u32 s16, s28, 0x80080
	global_load_lds_dwordx4 v[6:7], off
	v_lshl_add_u64 v[6:7], v[8:9], 0, s[36:37]
	s_mov_b32 m0, s53
	s_addc_u32 s17, s29, 0
	global_load_lds_dwordx4 v[6:7], off
	s_add_i32 m0, s47, 0x1c000
	v_lshl_add_u64 v[6:7], s[16:17], 0, v[182:183]
	global_load_lds_dwordx4 v[6:7], off
	v_lshl_add_u64 v[6:7], s[16:17], 0, v[186:187]
	s_add_i32 m0, s47, 0x1e000
	v_lshl_or_b32 v188, s18, 5, v21
	global_load_lds_dwordx4 v[6:7], off
	v_bitop3_b32 v231, v23, s13, v4 bitop3:0xde
	v_lshlrev_b32_e32 v4, 2, v188
	v_lshl_add_u64 v[6:7], s[14:15], 0, v[4:5]
	s_mov_b64 s[16:17], 0x200000
	s_cmpk_lt_u32 s12, 0x100
	v_lshl_add_u64 v[190:191], v[6:7], 0, s[16:17]
	s_mov_b64 s[16:17], 0x600000
	s_cselect_b64 s[12:13], -1, 0
	v_lshl_add_u64 v[192:193], v[6:7], 0, s[16:17]
	s_lshl_b32 s16, s18, 10
	s_add_u32 s14, s14, s16
	s_addc_u32 s15, s15, 0
	v_mov_b32_e32 v23, v5
	v_lshl_add_u64 v[6:7], s[14:15], 0, v[22:23]
	v_mov_b32_e32 v21, v5
	v_lshlrev_b32_e32 v4, 15, v14
	v_lshl_add_u64 v[6:7], v[6:7], 0, v[20:21]
	s_mov_b64 s[14:15], 0x5000000
	v_and_b32_e32 v4, 0xffff0000, v4
	v_lshl_add_u64 v[194:195], v[6:7], 0, s[14:15]
	v_lshl_add_u32 v4, v15, 12, v4
	v_and_b32_e32 v6, 1, v14
	v_lshl_or_b32 v4, v6, 6, v4
	v_lshl_add_u32 v196, v16, 1, v4
	v_lshlrev_b32_e32 v4, 15, v17
	v_and_b32_e32 v4, 0xffff0000, v4
	s_waitcnt vmcnt(6)
	v_lshl_add_u32 v4, v18, 12, v4
	v_and_b32_e32 v6, 1, v17
	v_lshl_or_b32 v4, v6, 6, v4
	v_mov_b32_e32 v197, v5
	v_lshl_add_u32 v212, v19, 1, v4
	v_mov_b32_e32 v213, v5
	s_mov_b32 s54, 0
	v_add_u32_e32 v235, 0, v24
	s_barrier
	s_branch .LBB0_652
	s_nop 0
	s_nop 0
	s_nop 0
	s_nop 0
	s_nop 0
	s_nop 0
	s_nop 0
	s_nop 0
	s_nop 0
	s_nop 0
	s_nop 0
	s_nop 0
	s_nop 0

; #define PG8_STAGE(bufoff, gbase, voff) do { _Pragma("unroll") for (int _i = 0; _i < 2; ++_i) \
;         __builtin_amdgcn_global_load_lds((const unsigned*)((const char*)(gbase) + (voff)[_i]), (LAS unsigned*)(lds + (bufoff) + ldsw + _i * 8192), 16, 0, 0); } while (0)
; #define PG8_LDA(dst, b, h) do { _Pragma("unroll") for (int m = 0; m < 4; ++m) _Pragma("unroll") for (int k = 0; k < 2; ++k) dst[m][k] = *(const LAS bf16x8*)(lds + PG8_SA(b, h) + aoff + m * 2048 + k * 1024); } while (0)
; #define PG8_LDB(dst, b, h) do { _Pragma("unroll") for (int n = 0; n < 2; ++n) _Pragma("unroll") for (int k = 0; k < 2; ++k) dst[n][k] = *(const LAS bf16x8*)(lds + PG8_SB(b, h) + boff + n * 2048 + k * 1024); } while (0)
; #define PG8_MMA(ai, bj, At, Bt) do { __builtin_amdgcn_s_setprio(1); _Pragma("unroll") for (int m = 0; m < 4; ++m) _Pragma("unroll") for (int n = 0; n < 2; ++n) _Pragma("unroll") for (int k = 0; k < 2; ++k) \
;         acc[ai][bj][m][n] = __builtin_amdgcn_mfma_f32_16x16x32_bf16(Bt[n][k], At[m][k], acc[ai][bj][m][n], 0, 0, 0); __builtin_amdgcn_s_setprio(0); } while (0)
; #define PG8_WAIT_V(n) asm volatile("s_waitcnt vmcnt(" #n ")" ::: "memory")
; #define PG8_WAIT_L(n) asm volatile("s_waitcnt lgkmcnt(" #n ")" ::: "memory")
; #define PG8_BAR __builtin_amdgcn_s_barrier()
; #define PG8_SCHED __builtin_amdgcn_sched_barrier(0)
; template <class Epi, class Sched>
; __device__ __forceinline__ void gemm_phase(LAS unsigned char* lds, const Gemm g, const Sched& S, const Epi& E) {
;     ...
;             const bool last = (t == nt - 2);
;             const char* a1 = cA + (size_t)(t + 1) * kstep;
;             const char* a2 = last ? nA : cA + (size_t)(t + 2) * kstep; const char* b2 = last ? nB : cB + (size_t)(t + 2) * kstep;
;             const char* a3 = a2 + kstep; const char* b3 = b2 + kstep;
;             if (last && has_next) S.a_ready(nxt);
;             PG8_LDB(B0, 0, 0); PG8_LDB(B1, 0, 1); PG8_SCHED; PG8_LDA(At, 0, 0); PG8_STAGE(PG8_SA(1, 1), a1 + hstepA, voffA);
;             PG8_WAIT_V(8); PG8_WAIT_L(0); PG8_BAR; PG8_MMA(0, 0, At, B0); PG8_MMA(0, 1, At, B1); PG8_BAR; PG8_SCHED;
;             PG8_LDA(At, 0, 1); PG8_STAGE(PG8_SB(0, 0), b2, voffB); PG8_STAGE(PG8_SB(0, 1), b2 + hstepB, voffB); PG8_STAGE(PG8_SA(0, 0), a2, voffA);
;             PG8_WAIT_V(8); PG8_WAIT_L(0); PG8_BAR; PG8_MMA(1, 0, At, B0); PG8_MMA(1, 1, At, B1); PG8_BAR; PG8_SCHED;
.LBB0_655:
	s_add_u32 s28, s26, 0xfff80080
	s_addc_u32 s29, s27, -1
	s_add_i32 s57, 0, 0x10000
	s_cmp_eq_u32 s56, 28
	s_cselect_b32 s41, s17, s29
	s_cselect_b32 s40, s23, s28
	v_add_u32_e32 v4, s57, v231
	s_cselect_b32 s29, s15, s55
	s_cselect_b32 s28, s25, s34
	s_add_i32 s60, 0, 0x14000
	ds_read_b128 v[134:137], v4
	ds_read_b128 v[138:141], v4 offset:1024
	ds_read_b128 v[142:145], v4 offset:2048
	ds_read_b128 v[146:149], v4 offset:3072
	v_add_u32_e32 v4, s60, v231
	ds_read_b128 v[150:153], v4
	ds_read_b128 v[154:157], v4 offset:1024
	ds_read_b128 v[158:161], v4 offset:2048
	ds_read_b128 v[162:165], v4 offset:3072
	v_lshl_add_u64 v[236:237], s[26:27], 0, v[196:197]
	s_add_i32 m0, s47, 0xc000
	ds_read_b128 v[166:169], v235
	ds_read_b128 v[170:173], v235 offset:1024
	ds_read_b128 v[174:177], v235 offset:2048
	ds_read_b128 v[178:181], v235 offset:3072
	ds_read_b128 v[214:217], v235 offset:4096
	ds_read_b128 v[218:221], v235 offset:5120
	ds_read_b128 v[222:225], v235 offset:6144
	ds_read_b128 v[226:229], v235 offset:7168
	global_load_lds_dwordx4 v[236:237], off
	v_lshl_add_u64 v[236:237], s[26:27], 0, v[212:213]
	s_add_i32 m0, s47, 0xe000
	s_nop 0
	global_load_lds_dwordx4 v[236:237], off
	s_waitcnt vmcnt(8)
	s_waitcnt lgkmcnt(0)
	s_barrier
	s_waitcnt lgkmcnt(0)
	v_mfma_f32_16x16x32_bf16 v[130:133], v[134:137], v[166:169], v[130:133]
	v_mfma_f32_16x16x32_bf16 v[126:129], v[142:145], v[166:169], v[126:129]
	v_mfma_f32_16x16x32_bf16 v[114:117], v[134:137], v[174:177], v[114:117]
	v_mfma_f32_16x16x32_bf16 v[110:113], v[142:145], v[174:177], v[110:113]
	v_mfma_f32_16x16x32_bf16 v[98:101], v[134:137], v[214:217], v[98:101]
	v_mfma_f32_16x16x32_bf16 v[94:97], v[142:145], v[214:217], v[94:97]
	v_mfma_f32_16x16x32_bf16 v[82:85], v[134:137], v[222:225], v[82:85]
	v_mfma_f32_16x16x32_bf16 v[78:81], v[142:145], v[222:225], v[78:81]
	v_mfma_f32_16x16x32_bf16 v[130:133], v[138:141], v[170:173], v[130:133]
	v_mfma_f32_16x16x32_bf16 v[126:129], v[146:149], v[170:173], v[126:129]
	v_mfma_f32_16x16x32_bf16 v[114:117], v[138:141], v[178:181], v[114:117]
	v_mfma_f32_16x16x32_bf16 v[110:113], v[146:149], v[178:181], v[110:113]
	v_mfma_f32_16x16x32_bf16 v[98:101], v[138:141], v[218:221], v[98:101]
	v_mfma_f32_16x16x32_bf16 v[94:97], v[146:149], v[218:221], v[94:97]
	v_mfma_f32_16x16x32_bf16 v[82:85], v[138:141], v[226:229], v[82:85]
	v_mfma_f32_16x16x32_bf16 v[78:81], v[146:149], v[226:229], v[78:81]
	v_mfma_f32_16x16x32_bf16 v[122:125], v[150:153], v[166:169], v[122:125]
	v_mfma_f32_16x16x32_bf16 v[118:121], v[158:161], v[166:169], v[118:121]
	v_mfma_f32_16x16x32_bf16 v[106:109], v[150:153], v[174:177], v[106:109]
	v_mfma_f32_16x16x32_bf16 v[102:105], v[158:161], v[174:177], v[102:105]
	v_mfma_f32_16x16x32_bf16 v[90:93], v[150:153], v[214:217], v[90:93]
	v_mfma_f32_16x16x32_bf16 v[86:89], v[158:161], v[214:217], v[86:89]
	v_mfma_f32_16x16x32_bf16 v[74:77], v[150:153], v[222:225], v[74:77]
	v_mfma_f32_16x16x32_bf16 v[70:73], v[158:161], v[222:225], v[70:73]
	v_mfma_f32_16x16x32_bf16 v[122:125], v[154:157], v[170:173], v[122:125]
	v_mfma_f32_16x16x32_bf16 v[118:121], v[162:165], v[170:173], v[118:121]
	v_mfma_f32_16x16x32_bf16 v[106:109], v[154:157], v[178:181], v[106:109]
	v_mfma_f32_16x16x32_bf16 v[102:105], v[162:165], v[178:181], v[102:105]
	v_mfma_f32_16x16x32_bf16 v[90:93], v[154:157], v[218:221], v[90:93]
	v_mfma_f32_16x16x32_bf16 v[86:89], v[162:165], v[218:221], v[86:89]
	v_mfma_f32_16x16x32_bf16 v[74:77], v[154:157], v[226:229], v[74:77]
	v_mfma_f32_16x16x32_bf16 v[70:73], v[162:165], v[226:229], v[70:73]
	s_barrier
	s_add_i32 s57, s57, s46
	v_lshl_add_u64 v[236:237], s[28:29], 0, v[182:183]
	s_mov_b32 m0, s57
	ds_read_b128 v[166:169], v235 offset:16384
	ds_read_b128 v[170:173], v235 offset:17408
	ds_read_b128 v[174:177], v235 offset:18432
	ds_read_b128 v[178:181], v235 offset:19456
	ds_read_b128 v[214:217], v235 offset:20480
	ds_read_b128 v[218:221], v235 offset:21504
	ds_read_b128 v[222:225], v235 offset:22528
	ds_read_b128 v[226:229], v235 offset:23552
	global_load_lds_dwordx4 v[236:237], off
	s_add_i32 m0, s57, 0x2000
	s_add_u32 s58, s28, 0x80000
	v_lshl_add_u64 v[238:239], s[28:29], 0, v[186:187]
	s_addc_u32 s59, s29, 0
	s_add_i32 s57, s60, s46
	global_load_lds_dwordx4 v[238:239], off
	v_lshl_add_u64 v[240:241], s[58:59], 0, v[182:183]
	s_mov_b32 m0, s57
	v_lshl_add_u64 v[242:243], s[40:41], 0, v[184:185]
	global_load_lds_dwordx4 v[240:241], off
	v_lshl_add_u64 v[240:241], s[58:59], 0, v[186:187]
	s_add_i32 m0, s57, 0x2000
	s_nop 0
	global_load_lds_dwordx4 v[240:241], off
	v_lshl_add_u64 v[240:241], s[40:41], 0, v[2:3]
	s_mov_b32 m0, s47
	s_nop 0
	global_load_lds_dwordx4 v[240:241], off
	s_mov_b32 m0, s48
	s_nop 0
	global_load_lds_dwordx4 v[242:243], off
	s_waitcnt vmcnt(8)
	s_waitcnt lgkmcnt(0)
	s_barrier
; #define PG8_STAGE(bufoff, gbase, voff) do { _Pragma("unroll") for (int _i = 0; _i < 2; ++_i) \
;         __builtin_amdgcn_global_load_lds((const unsigned*)((const char*)(gbase) + (voff)[_i]), (LAS unsigned*)(lds + (bufoff) + ldsw + _i * 8192), 16, 0, 0); } while (0)
; #define PG8_LDA(dst, b, h) do { _Pragma("unroll") for (int m = 0; m < 4; ++m) _Pragma("unroll") for (int k = 0; k < 2; ++k) dst[m][k] = *(const LAS bf16x8*)(lds + PG8_SA(b, h) + aoff + m * 2048 + k * 1024); } while (0)
; #define PG8_LDB(dst, b, h) do { _Pragma("unroll") for (int n = 0; n < 2; ++n) _Pragma("unroll") for (int k = 0; k < 2; ++k) dst[n][k] = *(const LAS bf16x8*)(lds + PG8_SB(b, h) + boff + n * 2048 + k * 1024); } while (0)
; #define PG8_MMA(ai, bj, At, Bt) do { __builtin_amdgcn_s_setprio(1); _Pragma("unroll") for (int m = 0; m < 4; ++m) _Pragma("unroll") for (int n = 0; n < 2; ++n) _Pragma("unroll") for (int k = 0; k < 2; ++k) \
;         acc[ai][bj][m][n] = __builtin_amdgcn_mfma_f32_16x16x32_bf16(Bt[n][k], At[m][k], acc[ai][bj][m][n], 0, 0, 0); __builtin_amdgcn_s_setprio(0); } while (0)
; #define PG8_WAIT_V(n) asm volatile("s_waitcnt vmcnt(" #n ")" ::: "memory")
; #define PG8_WAIT_L(n) asm volatile("s_waitcnt lgkmcnt(" #n ")" ::: "memory")
; #define PG8_BAR __builtin_amdgcn_s_barrier()
; #define PG8_SCHED __builtin_amdgcn_sched_barrier(0)
; template <class Epi, class Sched>
; __device__ __forceinline__ void gemm_phase(LAS unsigned char* lds, const Gemm g, const Sched& S, const Epi& E) {
;     ...
;             PG8_WAIT_V(8); PG8_WAIT_L(0); PG8_BAR; PG8_MMA(1, 0, At, B0); PG8_MMA(1, 1, At, B1); PG8_BAR; PG8_SCHED;
;             PG8_LDB(B0, 1, 0); PG8_LDB(B1, 1, 1); PG8_SCHED; PG8_LDA(At, 1, 0); PG8_STAGE(PG8_SA(0, 1), a2 + hstepA, voffA);
;             PG8_WAIT_V(8); PG8_WAIT_L(0); PG8_BAR; PG8_MMA(0, 0, At, B0); PG8_MMA(0, 1, At, B1); PG8_BAR; PG8_SCHED;
	s_waitcnt lgkmcnt(0)
	v_mfma_f32_16x16x32_bf16 v[66:69], v[134:137], v[166:169], v[66:69]
	v_mfma_f32_16x16x32_bf16 v[62:65], v[142:145], v[166:169], v[62:65]
	v_mfma_f32_16x16x32_bf16 v[50:53], v[134:137], v[174:177], v[50:53]
	v_mfma_f32_16x16x32_bf16 v[46:49], v[142:145], v[174:177], v[46:49]
	v_mfma_f32_16x16x32_bf16 v[34:37], v[134:137], v[214:217], v[34:37]
	v_mfma_f32_16x16x32_bf16 v[30:33], v[142:145], v[214:217], v[30:33]
	v_mfma_f32_16x16x32_bf16 v[18:21], v[134:137], v[222:225], v[18:21]
	v_mfma_f32_16x16x32_bf16 v[14:17], v[142:145], v[222:225], v[14:17]
	v_mfma_f32_16x16x32_bf16 v[66:69], v[138:141], v[170:173], v[66:69]
	v_mfma_f32_16x16x32_bf16 v[62:65], v[146:149], v[170:173], v[62:65]
	v_mfma_f32_16x16x32_bf16 v[50:53], v[138:141], v[178:181], v[50:53]
	v_mfma_f32_16x16x32_bf16 v[46:49], v[146:149], v[178:181], v[46:49]
	v_mfma_f32_16x16x32_bf16 v[34:37], v[138:141], v[218:221], v[34:37]
	v_mfma_f32_16x16x32_bf16 v[30:33], v[146:149], v[218:221], v[30:33]
	v_mfma_f32_16x16x32_bf16 v[18:21], v[138:141], v[226:229], v[18:21]
	v_mfma_f32_16x16x32_bf16 v[14:17], v[146:149], v[226:229], v[14:17]
	v_mfma_f32_16x16x32_bf16 v[58:61], v[150:153], v[166:169], v[58:61]
	v_mfma_f32_16x16x32_bf16 v[54:57], v[158:161], v[166:169], v[54:57]
	v_mfma_f32_16x16x32_bf16 v[42:45], v[150:153], v[174:177], v[42:45]
	v_mfma_f32_16x16x32_bf16 v[38:41], v[158:161], v[174:177], v[38:41]
	v_mfma_f32_16x16x32_bf16 v[26:29], v[150:153], v[214:217], v[26:29]
	v_mfma_f32_16x16x32_bf16 v[22:25], v[158:161], v[214:217], v[22:25]
	v_mfma_f32_16x16x32_bf16 v[10:13], v[150:153], v[222:225], v[10:13]
	v_mfma_f32_16x16x32_bf16 v[6:9], v[158:161], v[222:225], v[6:9]
	v_mfma_f32_16x16x32_bf16 v[58:61], v[154:157], v[170:173], v[58:61]
	v_mfma_f32_16x16x32_bf16 v[54:57], v[162:165], v[170:173], v[54:57]
	v_mfma_f32_16x16x32_bf16 v[42:45], v[154:157], v[178:181], v[42:45]
	v_mfma_f32_16x16x32_bf16 v[38:41], v[162:165], v[178:181], v[38:41]
	v_mfma_f32_16x16x32_bf16 v[26:29], v[154:157], v[218:221], v[26:29]
	v_mfma_f32_16x16x32_bf16 v[22:25], v[162:165], v[218:221], v[22:25]
	v_mfma_f32_16x16x32_bf16 v[10:13], v[154:157], v[226:229], v[10:13]
	v_mfma_f32_16x16x32_bf16 v[6:9], v[162:165], v[226:229], v[6:9]
	s_barrier
	s_add_i32 s57, 0, 0x18000
	v_add_u32_e32 v4, s57, v231
	s_add_i32 s58, 0, 0x1c000
	ds_read_b128 v[134:137], v4
	ds_read_b128 v[138:141], v4 offset:1024
	ds_read_b128 v[142:145], v4 offset:2048
	ds_read_b128 v[146:149], v4 offset:3072
	v_add_u32_e32 v4, s58, v231
	ds_read_b128 v[150:153], v4
	ds_read_b128 v[154:157], v4 offset:1024
	ds_read_b128 v[158:161], v4 offset:2048
	ds_read_b128 v[162:165], v4 offset:3072
	s_add_u32 s40, s40, 0x80000
	s_addc_u32 s41, s41, 0
	s_mov_b32 m0, s49
	v_lshl_add_u64 v[244:245], s[40:41], 0, v[2:3]
	ds_read_b128 v[166:169], v235 offset:32768
	ds_read_b128 v[170:173], v235 offset:33792
	ds_read_b128 v[174:177], v235 offset:34816
	ds_read_b128 v[178:181], v235 offset:35840
	ds_read_b128 v[214:217], v235 offset:36864
	ds_read_b128 v[218:221], v235 offset:37888
	ds_read_b128 v[222:225], v235 offset:38912
	ds_read_b128 v[226:229], v235 offset:39936
	global_load_lds_dwordx4 v[244:245], off
	v_lshl_add_u64 v[244:245], s[40:41], 0, v[184:185]
	s_mov_b32 m0, s50
	s_nop 0
	global_load_lds_dwordx4 v[244:245], off
	s_waitcnt vmcnt(8)
	s_waitcnt lgkmcnt(0)
	s_barrier
	s_waitcnt lgkmcnt(0)
	v_mfma_f32_16x16x32_bf16 v[130:133], v[134:137], v[166:169], v[130:133]
	v_mfma_f32_16x16x32_bf16 v[126:129], v[142:145], v[166:169], v[126:129]
	v_mfma_f32_16x16x32_bf16 v[114:117], v[134:137], v[174:177], v[114:117]
	v_mfma_f32_16x16x32_bf16 v[110:113], v[142:145], v[174:177], v[110:113]
	v_mfma_f32_16x16x32_bf16 v[98:101], v[134:137], v[214:217], v[98:101]
	v_mfma_f32_16x16x32_bf16 v[94:97], v[142:145], v[214:217], v[94:97]
	v_mfma_f32_16x16x32_bf16 v[82:85], v[134:137], v[222:225], v[82:85]
	v_mfma_f32_16x16x32_bf16 v[78:81], v[142:145], v[222:225], v[78:81]
	v_mfma_f32_16x16x32_bf16 v[130:133], v[138:141], v[170:173], v[130:133]
	v_mfma_f32_16x16x32_bf16 v[126:129], v[146:149], v[170:173], v[126:129]
	v_mfma_f32_16x16x32_bf16 v[114:117], v[138:141], v[178:181], v[114:117]
	v_mfma_f32_16x16x32_bf16 v[110:113], v[146:149], v[178:181], v[110:113]
	v_mfma_f32_16x16x32_bf16 v[98:101], v[138:141], v[218:221], v[98:101]
	v_mfma_f32_16x16x32_bf16 v[94:97], v[146:149], v[218:221], v[94:97]
	v_mfma_f32_16x16x32_bf16 v[82:85], v[138:141], v[226:229], v[82:85]
	v_mfma_f32_16x16x32_bf16 v[78:81], v[146:149], v[226:229], v[78:81]
	v_mfma_f32_16x16x32_bf16 v[122:125], v[150:153], v[166:169], v[122:125]
	v_mfma_f32_16x16x32_bf16 v[118:121], v[158:161], v[166:169], v[118:121]
	v_mfma_f32_16x16x32_bf16 v[106:109], v[150:153], v[174:177], v[106:109]
	v_mfma_f32_16x16x32_bf16 v[102:105], v[158:161], v[174:177], v[102:105]
	v_mfma_f32_16x16x32_bf16 v[90:93], v[150:153], v[214:217], v[90:93]
	v_mfma_f32_16x16x32_bf16 v[86:89], v[158:161], v[214:217], v[86:89]
	v_mfma_f32_16x16x32_bf16 v[74:77], v[150:153], v[222:225], v[74:77]
	v_mfma_f32_16x16x32_bf16 v[70:73], v[158:161], v[222:225], v[70:73]
	v_mfma_f32_16x16x32_bf16 v[122:125], v[154:157], v[170:173], v[122:125]
	v_mfma_f32_16x16x32_bf16 v[118:121], v[162:165], v[170:173], v[118:121]
	v_mfma_f32_16x16x32_bf16 v[106:109], v[154:157], v[178:181], v[106:109]
	v_mfma_f32_16x16x32_bf16 v[102:105], v[162:165], v[178:181], v[102:105]
	v_mfma_f32_16x16x32_bf16 v[90:93], v[154:157], v[218:221], v[90:93]
	v_mfma_f32_16x16x32_bf16 v[86:89], v[162:165], v[218:221], v[86:89]
	v_mfma_f32_16x16x32_bf16 v[74:77], v[154:157], v[226:229], v[74:77]
	v_mfma_f32_16x16x32_bf16 v[70:73], v[162:165], v[226:229], v[70:73]
	s_barrier
; #define PG8_STAGE(bufoff, gbase, voff) do { _Pragma("unroll") for (int _i = 0; _i < 2; ++_i) \
;         __builtin_amdgcn_global_load_lds((const unsigned*)((const char*)(gbase) + (voff)[_i]), (LAS unsigned*)(lds + (bufoff) + ldsw + _i * 8192), 16, 0, 0); } while (0)
; #define PG8_LDA(dst, b, h) do { _Pragma("unroll") for (int m = 0; m < 4; ++m) _Pragma("unroll") for (int k = 0; k < 2; ++k) dst[m][k] = *(const LAS bf16x8*)(lds + PG8_SA(b, h) + aoff + m * 2048 + k * 1024); } while (0)
; #define PG8_MMA(ai, bj, At, Bt) do { __builtin_amdgcn_s_setprio(1); _Pragma("unroll") for (int m = 0; m < 4; ++m) _Pragma("unroll") for (int n = 0; n < 2; ++n) _Pragma("unroll") for (int k = 0; k < 2; ++k) \
;         acc[ai][bj][m][n] = __builtin_amdgcn_mfma_f32_16x16x32_bf16(Bt[n][k], At[m][k], acc[ai][bj][m][n], 0, 0, 0); __builtin_amdgcn_s_setprio(0); } while (0)
; #define PG8_WAIT_V(n) asm volatile("s_waitcnt vmcnt(" #n ")" ::: "memory")
; #define PG8_WAIT_L(n) asm volatile("s_waitcnt lgkmcnt(" #n ")" ::: "memory")
; #define PG8_BAR __builtin_amdgcn_s_barrier()
; #define PG8_SCHED __builtin_amdgcn_sched_barrier(0)
; template <class Epi, class Sched>
; __device__ __forceinline__ void gemm_phase(LAS unsigned char* lds, const Gemm g, const Sched& S, const Epi& E) {
;     ...
;             PG8_LDA(At, 1, 1); PG8_STAGE(PG8_SB(1, 0), b3, voffB); PG8_STAGE(PG8_SB(1, 1), b3 + hstepB, voffB); PG8_STAGE(PG8_SA(1, 0), a3, voffA);
;             PG8_WAIT_V(8); PG8_WAIT_L(0); PG8_BAR; PG8_MMA(1, 0, At, B0); PG8_MMA(1, 1, At, B1); PG8_BAR; PG8_SCHED;
;         }
;         if (wr == 0) PG8_BAR;
	s_add_i32 s40, s57, s46
	v_lshl_add_u64 v[236:237], v[236:237], 0, s[36:37]
	s_mov_b32 m0, s40
	ds_read_b128 v[166:169], v235 offset:49152
	ds_read_b128 v[170:173], v235 offset:50176
	ds_read_b128 v[174:177], v235 offset:51200
	ds_read_b128 v[178:181], v235 offset:52224
	ds_read_b128 v[214:217], v235 offset:53248
	ds_read_b128 v[218:221], v235 offset:54272
	ds_read_b128 v[222:225], v235 offset:55296
	ds_read_b128 v[226:229], v235 offset:56320
	global_load_lds_dwordx4 v[236:237], off
	s_add_i32 m0, s40, 0x2000
	s_add_u32 s28, s28, 0x80080
	v_lshl_add_u64 v[236:237], v[238:239], 0, s[36:37]
	s_addc_u32 s29, s29, 0
	s_add_i32 s40, s58, s46
	global_load_lds_dwordx4 v[236:237], off
	v_lshl_add_u64 v[236:237], s[28:29], 0, v[182:183]
	s_mov_b32 m0, s40
	s_nop 0
	global_load_lds_dwordx4 v[236:237], off
	v_lshl_add_u64 v[236:237], s[28:29], 0, v[186:187]
	s_add_i32 m0, s40, 0x2000
	s_nop 0
	global_load_lds_dwordx4 v[236:237], off
	v_lshl_add_u64 v[236:237], v[240:241], 0, s[36:37]
	s_mov_b32 m0, s52
	s_nop 0
	global_load_lds_dwordx4 v[236:237], off
	v_lshl_add_u64 v[236:237], v[242:243], 0, s[36:37]
	s_mov_b32 m0, s53
	s_nop 0
	global_load_lds_dwordx4 v[236:237], off
	s_waitcnt vmcnt(8)
	s_waitcnt lgkmcnt(0)
	s_barrier
	s_waitcnt lgkmcnt(0)
	v_mfma_f32_16x16x32_bf16 v[66:69], v[134:137], v[166:169], v[66:69]
	v_mfma_f32_16x16x32_bf16 v[62:65], v[142:145], v[166:169], v[62:65]
	v_mfma_f32_16x16x32_bf16 v[50:53], v[134:137], v[174:177], v[50:53]
	v_mfma_f32_16x16x32_bf16 v[46:49], v[142:145], v[174:177], v[46:49]
	v_mfma_f32_16x16x32_bf16 v[34:37], v[134:137], v[214:217], v[34:37]
	v_mfma_f32_16x16x32_bf16 v[30:33], v[142:145], v[214:217], v[30:33]
	v_mfma_f32_16x16x32_bf16 v[18:21], v[134:137], v[222:225], v[18:21]
	v_mfma_f32_16x16x32_bf16 v[14:17], v[142:145], v[222:225], v[14:17]
	v_mfma_f32_16x16x32_bf16 v[66:69], v[138:141], v[170:173], v[66:69]
	v_mfma_f32_16x16x32_bf16 v[62:65], v[146:149], v[170:173], v[62:65]
	v_mfma_f32_16x16x32_bf16 v[50:53], v[138:141], v[178:181], v[50:53]
	v_mfma_f32_16x16x32_bf16 v[46:49], v[146:149], v[178:181], v[46:49]
	v_mfma_f32_16x16x32_bf16 v[34:37], v[138:141], v[218:221], v[34:37]
	v_mfma_f32_16x16x32_bf16 v[30:33], v[146:149], v[218:221], v[30:33]
	v_mfma_f32_16x16x32_bf16 v[18:21], v[138:141], v[226:229], v[18:21]
	v_mfma_f32_16x16x32_bf16 v[14:17], v[146:149], v[226:229], v[14:17]
	v_mfma_f32_16x16x32_bf16 v[58:61], v[150:153], v[166:169], v[58:61]
	v_mfma_f32_16x16x32_bf16 v[54:57], v[158:161], v[166:169], v[54:57]
	v_mfma_f32_16x16x32_bf16 v[42:45], v[150:153], v[174:177], v[42:45]
	v_mfma_f32_16x16x32_bf16 v[38:41], v[158:161], v[174:177], v[38:41]
	v_mfma_f32_16x16x32_bf16 v[26:29], v[150:153], v[214:217], v[26:29]
	v_mfma_f32_16x16x32_bf16 v[22:25], v[158:161], v[214:217], v[22:25]
	v_mfma_f32_16x16x32_bf16 v[10:13], v[150:153], v[222:225], v[10:13]
	v_mfma_f32_16x16x32_bf16 v[6:9], v[158:161], v[222:225], v[6:9]
	v_mfma_f32_16x16x32_bf16 v[58:61], v[154:157], v[170:173], v[58:61]
	v_mfma_f32_16x16x32_bf16 v[54:57], v[162:165], v[170:173], v[54:57]
	v_mfma_f32_16x16x32_bf16 v[42:45], v[154:157], v[178:181], v[42:45]
	v_mfma_f32_16x16x32_bf16 v[38:41], v[162:165], v[178:181], v[38:41]
	v_mfma_f32_16x16x32_bf16 v[26:29], v[154:157], v[218:221], v[26:29]
	v_mfma_f32_16x16x32_bf16 v[22:25], v[162:165], v[218:221], v[22:25]
	v_mfma_f32_16x16x32_bf16 v[10:13], v[154:157], v[226:229], v[10:13]
	v_mfma_f32_16x16x32_bf16 v[6:9], v[162:165], v[226:229], v[6:9]
	s_barrier
	s_add_i32 s56, s56, 2
	s_add_u32 s26, s26, 0x100
	s_addc_u32 s27, s27, 0
	s_add_u32 s34, s34, 0x100
	s_addc_u32 s55, s55, 0
	s_cmp_gt_u32 s56, 29
	s_cbranch_scc0 .LBB0_655
	s_and_b64 vcc, exec, s[12:13]
	s_cbranch_vccz .LBB0_658
	s_barrier

; __device__ __forceinline__ unsigned xb_ld(unsigned* p)              { return __hip_atomic_load(p, __ATOMIC_RELAXED, __HIP_MEMORY_SCOPE_AGENT); }
; #define XB_SPIN(cond, bar) do { unsigned _sp = 0; while (cond) { __builtin_amdgcn_s_sleep(1); \
;     if ((++_sp & 255u) == 0u) { if (xb_ld(&(bar)[XB_TMO])) break; if (_sp > XB_SPIN_CAP) { atomicAdd(&(bar)[XB_TMO], 1u); break; } } } } while (0)
; __device__ __forceinline__ void xcd_barrier(const XcdBarrier& b) {
;     asm volatile("s_waitcnt vmcnt(0)" ::: "memory");
;     __syncthreads();
;     if (threadIdx.x == 0) {
;         unsigned* bar = b.bar;
;         __builtin_amdgcn_s_waitcnt(0);
;         unsigned nloc = b.st[0], nx = b.st[1];
;         if (nloc == 0u) { xcd_barrier_complete(bar, b.x, nloc, nx); b.st[0] = nloc; b.st[1] = nx; }
;         const unsigned k1 = b.st[2] + 1u, rank = b.st[3]; b.st[2] = k1;
;         (void)__hip_atomic_fetch_add(&bar[XB_XSUB(b.x)], 1u, __ATOMIC_RELAXED, __HIP_MEMORY_SCOPE_AGENT);
;         if (rank == 0u) {
;             XB_SPIN(xb_ld(&bar[XB_XSUB(b.x)]) < k1 * nloc, bar);
;             __builtin_amdgcn_fence(__ATOMIC_RELEASE, "agent");
;             asm volatile("s_waitcnt vmcnt(0)" ::: "memory");
;             (void)__hip_atomic_fetch_add(&bar[XB_TOP], 1u, __ATOMIC_RELAXED, __HIP_MEMORY_SCOPE_AGENT);
;         }
;         XB_SPIN(xb_ld(&bar[XB_TOP]) < k1 * nx, bar);
;         __builtin_amdgcn_fence(__ATOMIC_ACQUIRE, "agent");
;         asm volatile("s_waitcnt vmcnt(0)" ::: "memory");
;     }
;     __syncthreads();
.LBB0_730:
	v_readlane_b32 s4, v254, 45
	v_readlane_b32 s5, v254, 46
	s_andn2_b64 vcc, exec, s[4:5]
	s_cbranch_vccnz .LBB0_772
	s_setprio 0
	s_mov_b64 s[8:9], s[96:97]
	s_waitcnt vmcnt(0)
	s_waitcnt vmcnt(0)
	s_barrier
	s_mov_b64 s[4:5], exec
	v_readlane_b32 s10, v254, 21
	v_readlane_b32 s11, v254, 22
	s_and_b64 s[10:11], s[4:5], s[10:11]
	s_mov_b64 exec, s[10:11]
	s_cbranch_execz .LBB0_771
	v_mov_b32_e32 v2, s93
	s_waitcnt vmcnt(0) expcnt(0) lgkmcnt(0)
	ds_read_b32 v4, v2
	ds_read_b32 v2, v2 offset:4
	s_waitcnt lgkmcnt(1)
	v_cmp_ne_u32_e32 vcc, 0, v4
	s_cbranch_vccnz .LBB0_746
	s_load_dwordx2 s[14:15], s[94:95], 0x4
	s_add_u32 s10, s8, 0x1000
	s_addc_u32 s11, s9, 0
	s_add_u32 s12, s8, 0x1100
	s_addc_u32 s13, s9, 0
	s_waitcnt lgkmcnt(0)
	s_mul_i32 s34, s14, s92
	s_add_u32 s14, s8, 0x1200
	s_mul_i32 s34, s34, s15
	s_addc_u32 s15, s9, 0
	s_add_u32 s16, s8, 0x1300
	s_addc_u32 s17, s9, 0
	s_mov_b32 s44, 1
	s_mov_b64 s[18:19], 0
	s_branch .LBB0_736

; __device__ __forceinline__ unsigned xb_ld(unsigned* p)              { return __hip_atomic_load(p, __ATOMIC_RELAXED, __HIP_MEMORY_SCOPE_AGENT); }
; #define XB_SPIN(cond, bar) do { unsigned _sp = 0; while (cond) { __builtin_amdgcn_s_sleep(1); \
;     if ((++_sp & 255u) == 0u) { if (xb_ld(&(bar)[XB_TMO])) break; if (_sp > XB_SPIN_CAP) { atomicAdd(&(bar)[XB_TMO], 1u); break; } } } } while (0)
; __device__ __forceinline__ void xcd_barrier(const XcdBarrier& b) {
;     asm volatile("s_waitcnt vmcnt(0)" ::: "memory");
;     __syncthreads();
;     if (threadIdx.x == 0) {
;         unsigned* bar = b.bar;
;         __builtin_amdgcn_s_waitcnt(0);
;         unsigned nloc = b.st[0], nx = b.st[1];
;         if (nloc == 0u) { xcd_barrier_complete(bar, b.x, nloc, nx); b.st[0] = nloc; b.st[1] = nx; }
;         const unsigned k1 = b.st[2] + 1u, rank = b.st[3]; b.st[2] = k1;
;         (void)__hip_atomic_fetch_add(&bar[XB_XSUB(b.x)], 1u, __ATOMIC_RELAXED, __HIP_MEMORY_SCOPE_AGENT);
;         if (rank == 0u) {
;             XB_SPIN(xb_ld(&bar[XB_XSUB(b.x)]) < k1 * nloc, bar);
;             __builtin_amdgcn_fence(__ATOMIC_RELEASE, "agent");
;             asm volatile("s_waitcnt vmcnt(0)" ::: "memory");
;             (void)__hip_atomic_fetch_add(&bar[XB_TOP], 1u, __ATOMIC_RELAXED, __HIP_MEMORY_SCOPE_AGENT);
;         }
;         XB_SPIN(xb_ld(&bar[XB_TOP]) < k1 * nx, bar);
;         __builtin_amdgcn_fence(__ATOMIC_ACQUIRE, "agent");
;         asm volatile("s_waitcnt vmcnt(0)" ::: "memory");
;     }
;     __syncthreads();
.LBB0_827:
	v_readlane_b32 s4, v254, 49
	v_readlane_b32 s5, v254, 50
	s_andn2_b64 vcc, exec, s[4:5]
	v_readlane_b32 s70, v254, 23
	v_readlane_b32 s71, v254, 24
	v_readlane_b32 s61, v253, 49
	v_readlane_b32 s62, v254, 18
	s_cbranch_vccnz .LBB0_869
	s_setprio 0
	s_mov_b64 s[8:9], s[96:97]
	s_waitcnt vmcnt(0)
	s_waitcnt vmcnt(0)
	s_barrier
	s_mov_b64 s[4:5], exec
	v_readlane_b32 s10, v254, 21
	v_readlane_b32 s11, v254, 22
	s_and_b64 s[10:11], s[4:5], s[10:11]
	s_mov_b64 exec, s[10:11]
	s_cbranch_execz .LBB0_868
	v_mov_b32_e32 v2, s93
	s_waitcnt vmcnt(0) expcnt(0) lgkmcnt(0)
	ds_read_b32 v4, v2
	ds_read_b32 v2, v2 offset:4
	s_waitcnt lgkmcnt(1)
	v_cmp_ne_u32_e32 vcc, 0, v4
	s_cbranch_vccnz .LBB0_843
	s_load_dwordx2 s[14:15], s[94:95], 0x4
	s_add_u32 s10, s8, 0x1000
	s_addc_u32 s11, s9, 0
	s_add_u32 s12, s8, 0x1100
	s_addc_u32 s13, s9, 0
	s_waitcnt lgkmcnt(0)
	s_mul_i32 s34, s14, s92
	s_add_u32 s14, s8, 0x1200
	s_mul_i32 s34, s34, s15
	s_addc_u32 s15, s9, 0
	s_add_u32 s16, s8, 0x1300
	s_addc_u32 s17, s9, 0
	s_mov_b32 s44, 1
	s_mov_b64 s[18:19], 0
	s_branch .LBB0_833

; __device__ __forceinline__ unsigned xb_ld(unsigned* p)              { return __hip_atomic_load(p, __ATOMIC_RELAXED, __HIP_MEMORY_SCOPE_AGENT); }
; #define XB_SPIN(cond, bar) do { unsigned _sp = 0; while (cond) { __builtin_amdgcn_s_sleep(1); \
;     if ((++_sp & 255u) == 0u) { if (xb_ld(&(bar)[XB_TMO])) break; if (_sp > XB_SPIN_CAP) { atomicAdd(&(bar)[XB_TMO], 1u); break; } } } } while (0)
; __device__ __forceinline__ void xcd_barrier(const XcdBarrier& b) {
;     asm volatile("s_waitcnt vmcnt(0)" ::: "memory");
;     __syncthreads();
;     if (threadIdx.x == 0) {
;         unsigned* bar = b.bar;
;         __builtin_amdgcn_s_waitcnt(0);
;         unsigned nloc = b.st[0], nx = b.st[1];
;         if (nloc == 0u) { xcd_barrier_complete(bar, b.x, nloc, nx); b.st[0] = nloc; b.st[1] = nx; }
;         const unsigned k1 = b.st[2] + 1u, rank = b.st[3]; b.st[2] = k1;
;         (void)__hip_atomic_fetch_add(&bar[XB_XSUB(b.x)], 1u, __ATOMIC_RELAXED, __HIP_MEMORY_SCOPE_AGENT);
;         if (rank == 0u) {
;             XB_SPIN(xb_ld(&bar[XB_XSUB(b.x)]) < k1 * nloc, bar);
;             __builtin_amdgcn_fence(__ATOMIC_RELEASE, "agent");
;             asm volatile("s_waitcnt vmcnt(0)" ::: "memory");
;             (void)__hip_atomic_fetch_add(&bar[XB_TOP], 1u, __ATOMIC_RELAXED, __HIP_MEMORY_SCOPE_AGENT);
;         }
;         XB_SPIN(xb_ld(&bar[XB_TOP]) < k1 * nx, bar);
;         __builtin_amdgcn_fence(__ATOMIC_ACQUIRE, "agent");
;         asm volatile("s_waitcnt vmcnt(0)" ::: "memory");
;     }
;     __syncthreads();
.LBB0_873:
	v_readlane_b32 s4, v254, 53
	v_readlane_b32 s5, v254, 54
	s_andn2_b64 vcc, exec, s[4:5]
	s_cbranch_vccnz .LBB0_915
	s_setprio 0
	s_mov_b64 s[6:7], s[96:97]
	s_waitcnt vmcnt(0)
	s_waitcnt vmcnt(0)
	s_barrier
	s_mov_b64 s[4:5], exec
	v_readlane_b32 s8, v254, 21
	v_readlane_b32 s9, v254, 22
	s_and_b64 s[8:9], s[4:5], s[8:9]
	s_mov_b64 exec, s[8:9]
	s_cbranch_execz .LBB0_914
	v_mov_b32_e32 v2, s93
	s_waitcnt vmcnt(0) expcnt(0) lgkmcnt(0)
	ds_read_b32 v4, v2
	ds_read_b32 v2, v2 offset:4
	s_waitcnt lgkmcnt(1)
	v_cmp_ne_u32_e32 vcc, 0, v4
	s_cbranch_vccnz .LBB0_889
	s_load_dwordx2 s[12:13], s[94:95], 0x4
	s_add_u32 s8, s6, 0x1000
	s_addc_u32 s9, s7, 0
	s_add_u32 s10, s6, 0x1100
	s_addc_u32 s11, s7, 0
	s_waitcnt lgkmcnt(0)
	s_mul_i32 s34, s12, s92
	s_add_u32 s12, s6, 0x1200
	s_mul_i32 s34, s34, s13
	s_addc_u32 s13, s7, 0
	s_add_u32 s14, s6, 0x1300
	s_addc_u32 s15, s7, 0
	s_mov_b32 s42, 1
	s_mov_b64 s[16:17], 0
	s_branch .LBB0_879

; __device__ __forceinline__ unsigned xb_ld(unsigned* p)              { return __hip_atomic_load(p, __ATOMIC_RELAXED, __HIP_MEMORY_SCOPE_AGENT); }
; #define XB_SPIN(cond, bar) do { unsigned _sp = 0; while (cond) { __builtin_amdgcn_s_sleep(1); \
;     if ((++_sp & 255u) == 0u) { if (xb_ld(&(bar)[XB_TMO])) break; if (_sp > XB_SPIN_CAP) { atomicAdd(&(bar)[XB_TMO], 1u); break; } } } } while (0)
; __device__ __forceinline__ void xcd_barrier(const XcdBarrier& b) {
;     asm volatile("s_waitcnt vmcnt(0)" ::: "memory");
;     __syncthreads();
;     if (threadIdx.x == 0) {
;         unsigned* bar = b.bar;
;         __builtin_amdgcn_s_waitcnt(0);
;         unsigned nloc = b.st[0], nx = b.st[1];
;         if (nloc == 0u) { xcd_barrier_complete(bar, b.x, nloc, nx); b.st[0] = nloc; b.st[1] = nx; }
;         const unsigned k1 = b.st[2] + 1u, rank = b.st[3]; b.st[2] = k1;
;         (void)__hip_atomic_fetch_add(&bar[XB_XSUB(b.x)], 1u, __ATOMIC_RELAXED, __HIP_MEMORY_SCOPE_AGENT);
;         if (rank == 0u) {
;             XB_SPIN(xb_ld(&bar[XB_XSUB(b.x)]) < k1 * nloc, bar);
;             __builtin_amdgcn_fence(__ATOMIC_RELEASE, "agent");
;             asm volatile("s_waitcnt vmcnt(0)" ::: "memory");
;             (void)__hip_atomic_fetch_add(&bar[XB_TOP], 1u, __ATOMIC_RELAXED, __HIP_MEMORY_SCOPE_AGENT);
;         }
;         XB_SPIN(xb_ld(&bar[XB_TOP]) < k1 * nx, bar);
;         __builtin_amdgcn_fence(__ATOMIC_ACQUIRE, "agent");
;         asm volatile("s_waitcnt vmcnt(0)" ::: "memory");
;     }
;     __syncthreads();
.LBB0_938:
	v_readlane_b32 s4, v254, 45
	v_readlane_b32 s5, v254, 46
	s_andn2_b64 vcc, exec, s[4:5]
	s_cbranch_vccnz .LBB0_980
	s_setprio 0
	s_mov_b64 s[6:7], s[96:97]
	s_waitcnt vmcnt(0)
	s_waitcnt vmcnt(0)
	s_barrier
	s_mov_b64 s[4:5], exec
	v_readlane_b32 s8, v254, 21
	v_readlane_b32 s9, v254, 22
	s_and_b64 s[8:9], s[4:5], s[8:9]
	s_mov_b64 exec, s[8:9]
	s_cbranch_execz .LBB0_979
	v_mov_b32_e32 v2, s93
	s_waitcnt vmcnt(0) expcnt(0) lgkmcnt(0)
	ds_read_b32 v4, v2
	ds_read_b32 v2, v2 offset:4
	s_waitcnt lgkmcnt(1)
	v_cmp_ne_u32_e32 vcc, 0, v4
	s_cbranch_vccnz .LBB0_954
	s_load_dwordx2 s[12:13], s[94:95], 0x4
	s_add_u32 s8, s6, 0x1000
	s_addc_u32 s9, s7, 0
	s_add_u32 s10, s6, 0x1100
	s_addc_u32 s11, s7, 0
	s_waitcnt lgkmcnt(0)
	s_mul_i32 s34, s12, s92
	s_add_u32 s12, s6, 0x1200
	s_mul_i32 s34, s34, s13
	s_addc_u32 s13, s7, 0
	s_add_u32 s14, s6, 0x1300
	s_addc_u32 s15, s7, 0
	s_mov_b32 s42, 1
	s_mov_b64 s[16:17], 0
	s_branch .LBB0_944

; #define PG8_STAGE(bufoff, gbase, voff) do { _Pragma("unroll") for (int _i = 0; _i < 2; ++_i) \
;         __builtin_amdgcn_global_load_lds((const unsigned*)((const char*)(gbase) + (voff)[_i]), (LAS unsigned*)(lds + (bufoff) + ldsw + _i * 8192), 16, 0, 0); } while (0)
; #define PG8_BAR __builtin_amdgcn_s_barrier()
; template <class Epi, class Sched>
; __device__ __forceinline__ void gemm_phase(LAS unsigned char* lds, const Gemm g, const Sched& S, const Epi& E) {
;     ...
;     for (int i = 0; i < 2; ++i) { int R, C; stage_rc(tid * 16 + i * 8192, R, C); const int Rb = Epi::PERM ? ((R & ~31) + perm32(R & 31)) : R;
;         voffA[i] = (unsigned)(R * g.lda + C) * 2u; voffB[i] = (unsigned)(Rb * g.ldb + C) * 2u; }
;     const size_t kstep = (size_t)(BK * 2);
;     const size_t hstepA = (size_t)HALF * g.lda * 2, hstepB = (size_t)HALF * g.ldb * 2;
;     const size_t tstepA = 2 * hstepA, tstepB = 2 * hstepB;
;     const unsigned ldsw = (unsigned)wid * 1024u;
;     const int aoff = lds_byte(wr * 64 + fr, fq * 8), boff = lds_byte(wc * 32 + fr, fq * 8);
;     ...
;     Unit cur, nxt; int ui = 0;
;     if (!S.next(0, cur)) return;
;     f32x4 acc[2][2][4][2];
; #pragma unroll
;     for (int a = 0; a < 2; ++a)
; #pragma unroll
;         for (int b = 0; b < 2; ++b)
; #pragma unroll
;             for (int m = 0; m < 4; ++m)
; #pragma unroll
;                 for (int n = 0; n < 2; ++n) acc[a][b][m][n] = (f32x4){0.f, 0.f, 0.f, 0.f};
;     bf16x8 At[4][2], B0[2][2], B1[2][2];
;     const char* cA = (const char*)g.A + (size_t)cur.pm * tstepA + (size_t)cur.ka * 2; const char* cB = (const char*)g.Bt + (size_t)cur.pn * tstepB;
;     S.a_ready(cur);
;     PG8_STAGE(PG8_SB(0, 0), cB, voffB); PG8_STAGE(PG8_SB(0, 1), cB + hstepB, voffB); PG8_STAGE(PG8_SA(0, 0), cA, voffA); PG8_STAGE(PG8_SA(0, 1), cA + hstepA, voffA);
;     if (wr == 1) PG8_BAR;
.LBB0_992:
	v_readlane_b32 s4, v253, 41
	v_mov_b32_e32 v169, v0
	v_readlane_b32 s5, v253, 42
	s_andn2_b64 vcc, exec, s[4:5]
	v_readfirstlane_b32 s51, v169
	s_cbranch_vccnz .LBB0_1073
	s_waitcnt vmcnt(0)
	v_lshlrev_b32_e32 v7, 4, v169
	v_add_u32_e32 v3, 0x2000, v7
	v_ashrrev_i32_e32 v2, 31, v3
	v_lshrrev_b32_e32 v2, 22, v2
	v_add_u32_e32 v2, v3, v2
	v_ashrrev_i32_e32 v4, 10, v2
	v_mul_i32_i24_e32 v6, 0x400, v4
	v_sub_u32_e32 v3, v3, v6
	v_lshrrev_b32_e32 v6, 4, v3
	v_bitop3_b32 v3, v6, v3, 32 bitop3:0x6c
	v_ashrrev_i32_e32 v6, 31, v3
	v_lshrrev_b32_e32 v6, 26, v6
	v_add_u32_e32 v6, v3, v6
	v_ashrrev_i32_e32 v8, 6, v6
	v_and_b32_e32 v6, 0xc0, v6
	v_lshlrev_b32_e32 v2, 5, v4
	v_sub_u32_e32 v3, v3, v6
	v_lshlrev_b32_e32 v4, 3, v4
	v_ashrrev_i16_sdwa v3, v232, sext(v3) dst_sel:DWORD dst_unused:UNUSED_PAD src0_sel:DWORD src1_sel:BYTE_0
	v_and_b32_e32 v4, -16, v4
	v_and_b32_e32 v2, 32, v2
	v_bfe_i32 v3, v3, 0, 16
	v_add_u32_e32 v4, v8, v4
	v_add_u32_e32 v9, v2, v3
	v_mul_lo_u32 v6, v4, s6
	v_add_lshl_u32 v134, v9, v6, 1
	v_mul_lo_u32 v6, v4, s22
	v_add_lshl_u32 v136, v9, v6, 1
	v_bfe_i32 v9, v169, 27, 1
	v_lshrrev_b32_e32 v9, 22, v9
	v_add_u32_e32 v9, v7, v9
	v_and_b32_e32 v9, 0xfffffc00, v9
	v_sub_u32_e32 v7, v7, v9
	v_readlane_b32 s4, v254, 14
	v_ashrrev_i32_e32 v4, 31, v169
	v_lshrrev_b32_e32 v9, 4, v7
	s_mul_i32 s4, s4, s7
	s_lshl_b32 s34, s22, 8
	v_lshrrev_b32_e32 v4, 26, v4
	v_bitop3_b32 v7, v9, v7, 32 bitop3:0x6c
	s_ashr_i32 s5, s4, 31
	s_lshl_b64 s[20:21], s[34:35], 1
	v_add_u32_e32 v4, v169, v4
	v_ashrrev_i32_e32 v9, 31, v7
	s_lshl_b64 s[26:27], s[4:5], 1
	v_readlane_b32 s4, v253, 62
	v_readlane_b32 s23, v253, 61
	v_ashrrev_i32_e32 v8, 6, v4
	v_lshrrev_b32_e32 v9, 26, v9
	s_mul_i32 s4, s20, s4
	s_mul_hi_u32 s5, s20, s23
	v_lshlrev_b32_e32 v4, 5, v8
	v_add_u32_e32 v9, v7, v9
	v_lshlrev_b32_e32 v8, 3, v8
	s_add_i32 s4, s5, s4
	s_bfe_u32 s5, s22, 0x10017
	s_ashr_i32 s50, s51, 6
	v_ashrrev_i32_e32 v10, 6, v9
	v_and_b32_e32 v8, -16, v8
	s_mul_i32 s5, s5, s23
	s_ashr_i32 s52, s51, 8
	s_lshl_b32 s55, s6, 8
	s_lshl_b32 s56, s6, 9
	s_lshl_b32 s57, s50, 10
	v_add_u32_e32 v8, v10, v8
	s_add_i32 s4, s4, s5
	s_mul_i32 s5, s20, s23
	v_mul_lo_u32 v10, v8, s6
	v_mul_lo_u32 v8, v8, s22
	s_add_u32 s22, s12, s5
	v_and_b32_e32 v9, 0xc0, v9
	s_addc_u32 s23, s13, s4
	v_readlane_b32 s4, v253, 63
	v_readlane_b32 s24, v254, 13
	v_sub_u32_e32 v7, v7, v9
	s_mul_i32 s4, s56, s4
	s_mul_hi_u32 s5, s56, s24
	v_ashrrev_i16_sdwa v7, v232, sext(v7) dst_sel:DWORD dst_unused:UNUSED_PAD src0_sel:DWORD src1_sel:BYTE_0
	s_add_i32 s5, s5, s4
	s_mul_i32 s4, s56, s24
	v_and_b32_e32 v4, 32, v4
	v_bfe_i32 v7, v7, 0, 16
	s_add_u32 s24, s16, s4
	v_add_u32_e32 v9, v4, v7
	s_addc_u32 s25, s17, s5
	s_add_i32 s58, s57, 0
	v_add_lshl_u32 v138, v9, v10, 1
	s_add_i32 m0, s58, 0x10000
	v_add_lshl_u32 v140, v9, v8, 1
	global_load_lds_dwordx4 v138, s[24:25]
	s_add_i32 m0, s58, 0x12000
	s_add_u32 s4, s24, s55
	global_load_lds_dwordx4 v134, s[24:25]
	s_addc_u32 s5, s25, 0
	s_add_i32 m0, s58, 0x14000
	s_nop 0
	global_load_lds_dwordx4 v138, s[4:5]
	s_add_i32 m0, s58, 0x16000
	s_add_u32 s26, s22, s26
	s_addc_u32 s27, s23, s27
	s_add_i32 s59, s58, 0x2000
	global_load_lds_dwordx4 v134, s[4:5]
	s_mov_b32 m0, s58
	s_add_u32 s22, s26, s34
	global_load_lds_dwordx4 v140, s[26:27]
	s_mov_b32 m0, s59
	s_addc_u32 s23, s27, 0
	s_add_i32 s60, s58, 0x4000
	global_load_lds_dwordx4 v136, s[26:27]
	s_mov_b32 m0, s60
	s_add_i32 s61, s58, 0x6000
	global_load_lds_dwordx4 v140, s[22:23]
	s_mov_b32 m0, s61
	s_cmp_eq_u32 s52, 1
	global_load_lds_dwordx4 v136, s[22:23]
	s_cselect_b64 s[22:23], -1, 0
	s_cmp_lg_u32 s52, 1
	s_cbranch_scc1 .LBB0_995
	s_barrier
	s_setprio 1
; #define PG8_STAGE(bufoff, gbase, voff) do { _Pragma("unroll") for (int _i = 0; _i < 2; ++_i) \
;         __builtin_amdgcn_global_load_lds((const unsigned*)((const char*)(gbase) + (voff)[_i]), (LAS unsigned*)(lds + (bufoff) + ldsw + _i * 8192), 16, 0, 0); } while (0)
; #define PG8_WAIT_V(n) asm volatile("s_waitcnt vmcnt(" #n ")" ::: "memory")
; #define PG8_BAR __builtin_amdgcn_s_barrier()
; template <class Epi, class Sched>
; __device__ __forceinline__ void gemm_phase(LAS unsigned char* lds, const Gemm g, const Sched& S, const Epi& E) {
;     ...
;     f32x4 acc[2][2][4][2];
; #pragma unroll
;     for (int a = 0; a < 2; ++a)
; #pragma unroll
;         for (int b = 0; b < 2; ++b)
; #pragma unroll
;             for (int m = 0; m < 4; ++m)
; #pragma unroll
;                 for (int n = 0; n < 2; ++n) acc[a][b][m][n] = (f32x4){0.f, 0.f, 0.f, 0.f};
;     ...
;     PG8_STAGE(PG8_SB(0, 0), cB, voffB); PG8_STAGE(PG8_SB(0, 1), cB + hstepB, voffB); PG8_STAGE(PG8_SA(0, 0), cA, voffA); PG8_STAGE(PG8_SA(0, 1), cA + hstepA, voffA);
;     if (wr == 1) PG8_BAR;
;     PG8_WAIT_V(2); PG8_BAR;
;     PG8_STAGE(PG8_SB(1, 0), cB + kstep, voffB); PG8_STAGE(PG8_SA(1, 0), cA + kstep, voffA); PG8_STAGE(PG8_SB(1, 1), cB + hstepB + kstep, voffB);
;     PG8_WAIT_V(6); PG8_BAR;
;     for (;;) {
.LBB0_995:
	v_mov_b32_e32 v139, v5
	v_lshl_add_u64 v[10:11], s[24:25], 0, v[138:139]
	v_mov_b32_e32 v135, v5
	v_lshl_add_u64 v[12:13], s[24:25], 0, v[134:135]
	v_mov_b32_e32 v141, v5
	s_add_i32 m0, s58, 0x18000
	v_lshl_add_u64 v[10:11], v[10:11], 0, s[36:37]
	v_lshl_add_u64 v[18:19], s[26:27], 0, v[140:141]
	v_mov_b32_e32 v137, v5
	s_waitcnt vmcnt(2)
	s_barrier
	global_load_lds_dwordx4 v[10:11], off
	v_lshl_add_u64 v[10:11], v[12:13], 0, s[36:37]
	s_add_i32 m0, s58, 0x1a000
	s_add_i32 s62, s58, 0x8000
	v_lshl_add_u64 v[20:21], s[26:27], 0, v[136:137]
	global_load_lds_dwordx4 v[10:11], off
	v_lshl_add_u64 v[10:11], v[18:19], 0, s[36:37]
	s_mov_b32 m0, s62
	s_add_i32 s63, s58, 0xa000
	v_lshl_add_u64 v[14:15], s[4:5], 0, v[138:139]
	global_load_lds_dwordx4 v[10:11], off
	v_lshl_add_u64 v[10:11], v[20:21], 0, s[36:37]
	s_mov_b32 m0, s63
	v_lshl_add_u64 v[16:17], s[4:5], 0, v[134:135]
	global_load_lds_dwordx4 v[10:11], off
	s_add_i32 m0, s58, 0x1c000
	v_lshl_add_u64 v[10:11], v[14:15], 0, s[36:37]
	global_load_lds_dwordx4 v[10:11], off
	v_lshl_add_u64 v[10:11], v[16:17], 0, s[36:37]
	s_add_i32 m0, s58, 0x1e000
	v_and_b32_e32 v168, 15, v169
	global_load_lds_dwordx4 v[10:11], off
	v_and_b32_e32 v9, 48, v169
	v_lshlrev_b32_e32 v10, 2, v169
	s_and_b32 s54, s50, 3
	s_lshr_b32 s64, s6, 6
	v_lshl_or_b32 v9, v168, 6, v9
	s_lshl_b32 s4, s52, 13
	v_and_b32_e32 v10, 32, v10
	v_bitop3_b32 v11, v9, s4, v10 bitop3:0xde
	s_lshl_b32 s4, s54, 12
	s_add_i32 s65, s64, -2
	s_cmpk_lt_u32 s51, 0x100
	v_bitop3_b32 v148, v9, s4, v10 bitop3:0xde
	s_cselect_b64 s[28:29], -1, 0
	s_add_u32 s4, s34, 0x80
	v_add_u32_e32 v4, v8, v4
	s_addc_u32 s5, 0, 0
	v_add_lshl_u32 v4, v4, v7, 1
	v_add_u32_e32 v2, v6, v2
	v_lshl_add_u64 v[142:143], s[4:5], 0, v[4:5]
	v_add_lshl_u32 v4, v2, v3, 1
	s_waitcnt vmcnt(6)
	v_lshl_add_u64 v[144:145], s[4:5], 0, v[4:5]
	v_mov_b32_e32 v4, v5
	v_mov_b32_e32 v2, v5
	v_mov_b32_e32 v3, v5
	v_add_u32_e32 v149, 0, v11
	v_mov_b64_e32 v[8:9], v[4:5]
	v_mov_b64_e32 v[12:13], v[4:5]
	v_mov_b64_e32 v[16:17], v[4:5]
	v_mov_b64_e32 v[20:21], v[4:5]
	v_mov_b64_e32 v[24:25], v[4:5]
	v_mov_b64_e32 v[32:33], v[4:5]
	v_mov_b64_e32 v[40:41], v[4:5]
	v_mov_b64_e32 v[48:49], v[4:5]
	v_mov_b64_e32 v[28:29], v[4:5]
	v_mov_b64_e32 v[36:37], v[4:5]
	v_mov_b64_e32 v[44:45], v[4:5]
	v_mov_b64_e32 v[52:53], v[4:5]
	v_mov_b64_e32 v[56:57], v[4:5]
	v_mov_b64_e32 v[60:61], v[4:5]
	v_mov_b64_e32 v[64:65], v[4:5]
	v_mov_b64_e32 v[68:69], v[4:5]
	v_mov_b64_e32 v[72:73], v[4:5]
	v_mov_b64_e32 v[76:77], v[4:5]
	v_mov_b64_e32 v[80:81], v[4:5]
	v_mov_b64_e32 v[84:85], v[4:5]
	v_mov_b64_e32 v[88:89], v[4:5]
	v_mov_b64_e32 v[96:97], v[4:5]
	v_mov_b64_e32 v[104:105], v[4:5]
	v_mov_b64_e32 v[116:117], v[4:5]
	v_mov_b64_e32 v[92:93], v[4:5]
	v_mov_b64_e32 v[100:101], v[4:5]
	v_mov_b64_e32 v[108:109], v[4:5]
	v_mov_b64_e32 v[112:113], v[4:5]
	v_mov_b64_e32 v[120:121], v[4:5]
	v_mov_b64_e32 v[124:125], v[4:5]
	v_mov_b64_e32 v[128:129], v[4:5]
	v_mov_b64_e32 v[132:133], v[4:5]
	v_readlane_b32 s4, v254, 13
	s_mov_b32 s66, 0
	v_mov_b64_e32 v[6:7], v[2:3]
	v_mov_b64_e32 v[10:11], v[2:3]
	v_mov_b64_e32 v[14:15], v[2:3]
	v_mov_b64_e32 v[18:19], v[2:3]
	v_mov_b64_e32 v[22:23], v[2:3]
	v_mov_b64_e32 v[30:31], v[2:3]
	v_mov_b64_e32 v[38:39], v[2:3]
	v_mov_b64_e32 v[46:47], v[2:3]
	v_mov_b64_e32 v[26:27], v[2:3]
	v_mov_b64_e32 v[34:35], v[2:3]
	v_mov_b64_e32 v[42:43], v[2:3]
	v_mov_b64_e32 v[50:51], v[2:3]
	v_mov_b64_e32 v[54:55], v[2:3]
	v_mov_b64_e32 v[58:59], v[2:3]
	v_mov_b64_e32 v[62:63], v[2:3]
	v_mov_b64_e32 v[66:67], v[2:3]
	v_mov_b64_e32 v[70:71], v[2:3]
	v_mov_b64_e32 v[74:75], v[2:3]
	v_mov_b64_e32 v[78:79], v[2:3]
	v_mov_b64_e32 v[82:83], v[2:3]
	v_mov_b64_e32 v[86:87], v[2:3]
	v_mov_b64_e32 v[94:95], v[2:3]
	v_mov_b64_e32 v[102:103], v[2:3]
	v_mov_b64_e32 v[114:115], v[2:3]
	v_mov_b64_e32 v[90:91], v[2:3]
	v_mov_b64_e32 v[98:99], v[2:3]
	v_mov_b64_e32 v[106:107], v[2:3]
	v_mov_b64_e32 v[110:111], v[2:3]
	v_mov_b64_e32 v[118:119], v[2:3]
	v_mov_b64_e32 v[122:123], v[2:3]
	v_mov_b64_e32 v[126:127], v[2:3]
	v_mov_b64_e32 v[130:131], v[2:3]
	s_mov_b32 s6, s4
	v_readlane_b32 s53, v253, 61
	s_barrier
	s_branch .LBB0_998
	s_nop 0
	s_nop 0
	s_nop 0
	s_nop 0
	s_nop 0
	s_nop 0
	s_nop 0
	s_nop 0
	s_nop 0
	s_nop 0
	s_nop 0

; #define PG8_STAGE(bufoff, gbase, voff) do { _Pragma("unroll") for (int _i = 0; _i < 2; ++_i) \
;         __builtin_amdgcn_global_load_lds((const unsigned*)((const char*)(gbase) + (voff)[_i]), (LAS unsigned*)(lds + (bufoff) + ldsw + _i * 8192), 16, 0, 0); } while (0)
; #define PG8_LDA(dst, b, h) do { _Pragma("unroll") for (int m = 0; m < 4; ++m) _Pragma("unroll") for (int k = 0; k < 2; ++k) dst[m][k] = *(const LAS bf16x8*)(lds + PG8_SA(b, h) + aoff + m * 2048 + k * 1024); } while (0)
; #define PG8_LDB(dst, b, h) do { _Pragma("unroll") for (int n = 0; n < 2; ++n) _Pragma("unroll") for (int k = 0; k < 2; ++k) dst[n][k] = *(const LAS bf16x8*)(lds + PG8_SB(b, h) + boff + n * 2048 + k * 1024); } while (0)
; #define PG8_MMA(ai, bj, At, Bt) do { __builtin_amdgcn_s_setprio(1); _Pragma("unroll") for (int m = 0; m < 4; ++m) _Pragma("unroll") for (int n = 0; n < 2; ++n) _Pragma("unroll") for (int k = 0; k < 2; ++k) \
;         acc[ai][bj][m][n] = __builtin_amdgcn_mfma_f32_16x16x32_bf16(Bt[n][k], At[m][k], acc[ai][bj][m][n], 0, 0, 0); __builtin_amdgcn_s_setprio(0); } while (0)
; #define PG8_WAIT_V(n) asm volatile("s_waitcnt vmcnt(" #n ")" ::: "memory")
; #define PG8_WAIT_L(n) asm volatile("s_waitcnt lgkmcnt(" #n ")" ::: "memory")
; #define PG8_BAR __builtin_amdgcn_s_barrier()
; #define PG8_SCHED __builtin_amdgcn_sched_barrier(0)
; template <class Epi, class Sched>
; __device__ __forceinline__ void gemm_phase(LAS unsigned char* lds, const Gemm g, const Sched& S, const Epi& E) {
;     ...
;             const bool last = (t == nt - 2);
;             const char* a1 = cA + (size_t)(t + 1) * kstep;
;             const char* a2 = last ? nA : cA + (size_t)(t + 2) * kstep; const char* b2 = last ? nB : cB + (size_t)(t + 2) * kstep;
;             const char* a3 = a2 + kstep; const char* b3 = b2 + kstep;
;             if (last && has_next) S.a_ready(nxt);
;             PG8_LDB(B0, 0, 0); PG8_LDB(B1, 0, 1); PG8_SCHED; PG8_LDA(At, 0, 0); PG8_STAGE(PG8_SA(1, 1), a1 + hstepA, voffA);
;             PG8_WAIT_V(8); PG8_WAIT_L(0); PG8_BAR; PG8_MMA(0, 0, At, B0); PG8_MMA(0, 1, At, B1); PG8_BAR; PG8_SCHED;
;             PG8_LDA(At, 0, 1); PG8_STAGE(PG8_SB(0, 0), b2, voffB); PG8_STAGE(PG8_SB(0, 1), b2 + hstepB, voffB); PG8_STAGE(PG8_SA(0, 0), a2, voffA);
;             PG8_WAIT_V(8); PG8_WAIT_L(0); PG8_BAR; PG8_MMA(1, 0, At, B0); PG8_MMA(1, 1, At, B1); PG8_BAR; PG8_SCHED;
.LBB0_1009:
	s_add_i32 s43, s48, 2
	s_add_u32 s70, s26, s46
	s_addc_u32 s49, s27, s47
	s_add_u32 s72, s24, s46
	s_addc_u32 s71, s25, s47
	s_add_i32 s73, 0, 0x10000
	s_cmp_eq_u32 s65, s48
	s_cselect_b32 s49, s5, s49
	s_cselect_b32 s48, s4, s70
	v_add_u32_e32 v4, s73, v148
	s_cselect_b32 s71, s45, s71
	s_cselect_b32 s70, s44, s72
	s_add_i32 s72, 0, 0x14000
	ds_read_b128 v[150:153], v4
	ds_read_b128 v[154:157], v4 offset:1024
	ds_read_b128 v[158:161], v4 offset:2048
	ds_read_b128 v[162:165], v4 offset:3072
	v_add_u32_e32 v4, s72, v148
	ds_read_b128 v[170:173], v4
	ds_read_b128 v[174:177], v4 offset:1024
	ds_read_b128 v[178:181], v4 offset:2048
	ds_read_b128 v[182:185], v4 offset:3072
	v_lshl_add_u64 v[166:167], s[26:27], 0, v[146:147]
	s_add_i32 m0, s58, 0xc000
	ds_read_b128 v[186:189], v149
	ds_read_b128 v[190:193], v149 offset:1024
	ds_read_b128 v[194:197], v149 offset:2048
	ds_read_b128 v[212:215], v149 offset:3072
	ds_read_b128 v[216:219], v149 offset:4096
	ds_read_b128 v[220:223], v149 offset:5120
	ds_read_b128 v[224:227], v149 offset:6144
	ds_read_b128 v[228:231], v149 offset:7168
	global_load_lds_dwordx4 v[166:167], off
	v_lshl_add_u64 v[166:167], s[26:27], 0, v[2:3]
	s_add_i32 m0, s58, 0xe000
	s_nop 0
	global_load_lds_dwordx4 v[166:167], off
	s_waitcnt vmcnt(8)
	s_waitcnt lgkmcnt(0)
	s_barrier
	s_waitcnt lgkmcnt(0)
	v_mfma_f32_16x16x32_bf16 v[130:133], v[150:153], v[186:189], v[130:133]
	v_mfma_f32_16x16x32_bf16 v[126:129], v[158:161], v[186:189], v[126:129]
	v_mfma_f32_16x16x32_bf16 v[122:125], v[150:153], v[194:197], v[122:125]
	v_mfma_f32_16x16x32_bf16 v[118:121], v[158:161], v[194:197], v[118:121]
	v_mfma_f32_16x16x32_bf16 v[110:113], v[150:153], v[216:219], v[110:113]
	v_mfma_f32_16x16x32_bf16 v[106:109], v[158:161], v[216:219], v[106:109]
	v_mfma_f32_16x16x32_bf16 v[98:101], v[150:153], v[224:227], v[98:101]
	v_mfma_f32_16x16x32_bf16 v[90:93], v[158:161], v[224:227], v[90:93]
	v_mfma_f32_16x16x32_bf16 v[130:133], v[154:157], v[190:193], v[130:133]
	v_mfma_f32_16x16x32_bf16 v[126:129], v[162:165], v[190:193], v[126:129]
	v_mfma_f32_16x16x32_bf16 v[122:125], v[154:157], v[212:215], v[122:125]
	v_mfma_f32_16x16x32_bf16 v[118:121], v[162:165], v[212:215], v[118:121]
	v_mfma_f32_16x16x32_bf16 v[110:113], v[154:157], v[220:223], v[110:113]
	v_mfma_f32_16x16x32_bf16 v[106:109], v[162:165], v[220:223], v[106:109]
	v_mfma_f32_16x16x32_bf16 v[98:101], v[154:157], v[228:231], v[98:101]
	v_mfma_f32_16x16x32_bf16 v[90:93], v[162:165], v[228:231], v[90:93]
	v_mfma_f32_16x16x32_bf16 v[114:117], v[170:173], v[186:189], v[114:117]
	v_mfma_f32_16x16x32_bf16 v[102:105], v[178:181], v[186:189], v[102:105]
	v_mfma_f32_16x16x32_bf16 v[94:97], v[170:173], v[194:197], v[94:97]
	v_mfma_f32_16x16x32_bf16 v[86:89], v[178:181], v[194:197], v[86:89]
	v_mfma_f32_16x16x32_bf16 v[82:85], v[170:173], v[216:219], v[82:85]
	v_mfma_f32_16x16x32_bf16 v[78:81], v[178:181], v[216:219], v[78:81]
	v_mfma_f32_16x16x32_bf16 v[74:77], v[170:173], v[224:227], v[74:77]
	v_mfma_f32_16x16x32_bf16 v[70:73], v[178:181], v[224:227], v[70:73]
	v_mfma_f32_16x16x32_bf16 v[114:117], v[174:177], v[190:193], v[114:117]
	v_mfma_f32_16x16x32_bf16 v[102:105], v[182:185], v[190:193], v[102:105]
	v_mfma_f32_16x16x32_bf16 v[94:97], v[174:177], v[212:215], v[94:97]
	v_mfma_f32_16x16x32_bf16 v[86:89], v[182:185], v[212:215], v[86:89]
	v_mfma_f32_16x16x32_bf16 v[82:85], v[174:177], v[220:223], v[82:85]
	v_mfma_f32_16x16x32_bf16 v[78:81], v[182:185], v[220:223], v[78:81]
	v_mfma_f32_16x16x32_bf16 v[74:77], v[174:177], v[228:231], v[74:77]
	v_mfma_f32_16x16x32_bf16 v[70:73], v[182:185], v[228:231], v[70:73]
	s_barrier
	s_add_i32 s73, s73, s57
	v_lshl_add_u64 v[166:167], s[70:71], 0, v[138:139]
	s_mov_b32 m0, s73
	ds_read_b128 v[186:189], v149 offset:16384
	ds_read_b128 v[190:193], v149 offset:17408
	ds_read_b128 v[194:197], v149 offset:18432
	ds_read_b128 v[212:215], v149 offset:19456
	ds_read_b128 v[216:219], v149 offset:20480
	ds_read_b128 v[220:223], v149 offset:21504
	ds_read_b128 v[224:227], v149 offset:22528
	ds_read_b128 v[228:231], v149 offset:23552
	global_load_lds_dwordx4 v[166:167], off
	s_add_i32 m0, s73, 0x2000
	v_lshl_add_u64 v[236:237], s[70:71], 0, v[134:135]
	s_add_u32 s70, s70, s55
	s_addc_u32 s71, s71, 0
	s_add_i32 s72, s72, s57
	global_load_lds_dwordx4 v[236:237], off
	v_lshl_add_u64 v[238:239], s[70:71], 0, v[138:139]
	s_mov_b32 m0, s72
	v_lshl_add_u64 v[240:241], s[70:71], 0, v[134:135]
	global_load_lds_dwordx4 v[238:239], off
	s_add_i32 m0, s72, 0x2000
	v_lshl_add_u64 v[242:243], s[48:49], 0, v[140:141]
	global_load_lds_dwordx4 v[240:241], off
	s_mov_b32 m0, s58
	v_lshl_add_u64 v[244:245], s[48:49], 0, v[136:137]
	global_load_lds_dwordx4 v[242:243], off
	s_mov_b32 m0, s59
	s_nop 0
	global_load_lds_dwordx4 v[244:245], off
	s_waitcnt vmcnt(8)
	s_waitcnt lgkmcnt(0)
	s_barrier
; #define PG8_STAGE(bufoff, gbase, voff) do { _Pragma("unroll") for (int _i = 0; _i < 2; ++_i) \
;         __builtin_amdgcn_global_load_lds((const unsigned*)((const char*)(gbase) + (voff)[_i]), (LAS unsigned*)(lds + (bufoff) + ldsw + _i * 8192), 16, 0, 0); } while (0)
; #define PG8_LDA(dst, b, h) do { _Pragma("unroll") for (int m = 0; m < 4; ++m) _Pragma("unroll") for (int k = 0; k < 2; ++k) dst[m][k] = *(const LAS bf16x8*)(lds + PG8_SA(b, h) + aoff + m * 2048 + k * 1024); } while (0)
; #define PG8_LDB(dst, b, h) do { _Pragma("unroll") for (int n = 0; n < 2; ++n) _Pragma("unroll") for (int k = 0; k < 2; ++k) dst[n][k] = *(const LAS bf16x8*)(lds + PG8_SB(b, h) + boff + n * 2048 + k * 1024); } while (0)
; #define PG8_MMA(ai, bj, At, Bt) do { __builtin_amdgcn_s_setprio(1); _Pragma("unroll") for (int m = 0; m < 4; ++m) _Pragma("unroll") for (int n = 0; n < 2; ++n) _Pragma("unroll") for (int k = 0; k < 2; ++k) \
;         acc[ai][bj][m][n] = __builtin_amdgcn_mfma_f32_16x16x32_bf16(Bt[n][k], At[m][k], acc[ai][bj][m][n], 0, 0, 0); __builtin_amdgcn_s_setprio(0); } while (0)
; #define PG8_WAIT_V(n) asm volatile("s_waitcnt vmcnt(" #n ")" ::: "memory")
; #define PG8_WAIT_L(n) asm volatile("s_waitcnt lgkmcnt(" #n ")" ::: "memory")
; #define PG8_BAR __builtin_amdgcn_s_barrier()
; #define PG8_SCHED __builtin_amdgcn_sched_barrier(0)
; template <class Epi, class Sched>
; __device__ __forceinline__ void gemm_phase(LAS unsigned char* lds, const Gemm g, const Sched& S, const Epi& E) {
;     ...
;             PG8_WAIT_V(8); PG8_WAIT_L(0); PG8_BAR; PG8_MMA(1, 0, At, B0); PG8_MMA(1, 1, At, B1); PG8_BAR; PG8_SCHED;
;             PG8_LDB(B0, 1, 0); PG8_LDB(B1, 1, 1); PG8_SCHED; PG8_LDA(At, 1, 0); PG8_STAGE(PG8_SA(0, 1), a2 + hstepA, voffA);
;             PG8_WAIT_V(8); PG8_WAIT_L(0); PG8_BAR; PG8_MMA(0, 0, At, B0); PG8_MMA(0, 1, At, B1); PG8_BAR; PG8_SCHED;
	s_waitcnt lgkmcnt(0)
	v_mfma_f32_16x16x32_bf16 v[66:69], v[150:153], v[186:189], v[66:69]
	v_mfma_f32_16x16x32_bf16 v[62:65], v[158:161], v[186:189], v[62:65]
	v_mfma_f32_16x16x32_bf16 v[58:61], v[150:153], v[194:197], v[58:61]
	v_mfma_f32_16x16x32_bf16 v[54:57], v[158:161], v[194:197], v[54:57]
	v_mfma_f32_16x16x32_bf16 v[50:53], v[150:153], v[216:219], v[50:53]
	v_mfma_f32_16x16x32_bf16 v[42:45], v[158:161], v[216:219], v[42:45]
	v_mfma_f32_16x16x32_bf16 v[34:37], v[150:153], v[224:227], v[34:37]
	v_mfma_f32_16x16x32_bf16 v[26:29], v[158:161], v[224:227], v[26:29]
	v_mfma_f32_16x16x32_bf16 v[66:69], v[154:157], v[190:193], v[66:69]
	v_mfma_f32_16x16x32_bf16 v[62:65], v[162:165], v[190:193], v[62:65]
	v_mfma_f32_16x16x32_bf16 v[58:61], v[154:157], v[212:215], v[58:61]
	v_mfma_f32_16x16x32_bf16 v[54:57], v[162:165], v[212:215], v[54:57]
	v_mfma_f32_16x16x32_bf16 v[50:53], v[154:157], v[220:223], v[50:53]
	v_mfma_f32_16x16x32_bf16 v[42:45], v[162:165], v[220:223], v[42:45]
	v_mfma_f32_16x16x32_bf16 v[34:37], v[154:157], v[228:231], v[34:37]
	v_mfma_f32_16x16x32_bf16 v[26:29], v[162:165], v[228:231], v[26:29]
	v_mfma_f32_16x16x32_bf16 v[46:49], v[170:173], v[186:189], v[46:49]
	v_mfma_f32_16x16x32_bf16 v[38:41], v[178:181], v[186:189], v[38:41]
	v_mfma_f32_16x16x32_bf16 v[30:33], v[170:173], v[194:197], v[30:33]
	v_mfma_f32_16x16x32_bf16 v[22:25], v[178:181], v[194:197], v[22:25]
	v_mfma_f32_16x16x32_bf16 v[18:21], v[170:173], v[216:219], v[18:21]
	v_mfma_f32_16x16x32_bf16 v[14:17], v[178:181], v[216:219], v[14:17]
	v_mfma_f32_16x16x32_bf16 v[10:13], v[170:173], v[224:227], v[10:13]
	v_mfma_f32_16x16x32_bf16 v[6:9], v[178:181], v[224:227], v[6:9]
	v_mfma_f32_16x16x32_bf16 v[46:49], v[174:177], v[190:193], v[46:49]
	v_mfma_f32_16x16x32_bf16 v[38:41], v[182:185], v[190:193], v[38:41]
	v_mfma_f32_16x16x32_bf16 v[30:33], v[174:177], v[212:215], v[30:33]
	v_mfma_f32_16x16x32_bf16 v[22:25], v[182:185], v[212:215], v[22:25]
	v_mfma_f32_16x16x32_bf16 v[18:21], v[174:177], v[220:223], v[18:21]
	v_mfma_f32_16x16x32_bf16 v[14:17], v[182:185], v[220:223], v[14:17]
	v_mfma_f32_16x16x32_bf16 v[10:13], v[174:177], v[228:231], v[10:13]
	v_mfma_f32_16x16x32_bf16 v[6:9], v[182:185], v[228:231], v[6:9]
	s_barrier
	s_add_i32 s70, 0, 0x18000
	v_add_u32_e32 v4, s70, v148
	s_add_i32 s71, 0, 0x1c000
	ds_read_b128 v[150:153], v4
	ds_read_b128 v[154:157], v4 offset:1024
	ds_read_b128 v[158:161], v4 offset:2048
	ds_read_b128 v[162:165], v4 offset:3072
	v_add_u32_e32 v4, s71, v148
	ds_read_b128 v[170:173], v4
	ds_read_b128 v[174:177], v4 offset:1024
	ds_read_b128 v[178:181], v4 offset:2048
	ds_read_b128 v[182:185], v4 offset:3072
	s_add_u32 s48, s48, s34
	s_addc_u32 s49, s49, 0
	s_mov_b32 m0, s60
	v_lshl_add_u64 v[246:247], s[48:49], 0, v[140:141]
	ds_read_b128 v[186:189], v149 offset:32768
	ds_read_b128 v[190:193], v149 offset:33792
	ds_read_b128 v[194:197], v149 offset:34816
	ds_read_b128 v[212:215], v149 offset:35840
	ds_read_b128 v[216:219], v149 offset:36864
	ds_read_b128 v[220:223], v149 offset:37888
	ds_read_b128 v[224:227], v149 offset:38912
	ds_read_b128 v[228:231], v149 offset:39936
	global_load_lds_dwordx4 v[246:247], off
	v_lshl_add_u64 v[246:247], s[48:49], 0, v[136:137]
	s_mov_b32 m0, s61
	s_nop 0
	global_load_lds_dwordx4 v[246:247], off
	s_waitcnt vmcnt(8)
	s_waitcnt lgkmcnt(0)
	s_barrier
	s_waitcnt lgkmcnt(0)
	v_mfma_f32_16x16x32_bf16 v[130:133], v[150:153], v[186:189], v[130:133]
	v_mfma_f32_16x16x32_bf16 v[126:129], v[158:161], v[186:189], v[126:129]
	v_mfma_f32_16x16x32_bf16 v[122:125], v[150:153], v[194:197], v[122:125]
	v_mfma_f32_16x16x32_bf16 v[118:121], v[158:161], v[194:197], v[118:121]
	v_mfma_f32_16x16x32_bf16 v[110:113], v[150:153], v[216:219], v[110:113]
	v_mfma_f32_16x16x32_bf16 v[106:109], v[158:161], v[216:219], v[106:109]
	v_mfma_f32_16x16x32_bf16 v[98:101], v[150:153], v[224:227], v[98:101]
	v_mfma_f32_16x16x32_bf16 v[90:93], v[158:161], v[224:227], v[90:93]
	v_mfma_f32_16x16x32_bf16 v[130:133], v[154:157], v[190:193], v[130:133]
	v_mfma_f32_16x16x32_bf16 v[126:129], v[162:165], v[190:193], v[126:129]
	v_mfma_f32_16x16x32_bf16 v[122:125], v[154:157], v[212:215], v[122:125]
	v_mfma_f32_16x16x32_bf16 v[118:121], v[162:165], v[212:215], v[118:121]
	v_mfma_f32_16x16x32_bf16 v[110:113], v[154:157], v[220:223], v[110:113]
	v_mfma_f32_16x16x32_bf16 v[106:109], v[162:165], v[220:223], v[106:109]
	v_mfma_f32_16x16x32_bf16 v[98:101], v[154:157], v[228:231], v[98:101]
	v_mfma_f32_16x16x32_bf16 v[90:93], v[162:165], v[228:231], v[90:93]
	v_mfma_f32_16x16x32_bf16 v[114:117], v[170:173], v[186:189], v[114:117]
	v_mfma_f32_16x16x32_bf16 v[102:105], v[178:181], v[186:189], v[102:105]
	v_mfma_f32_16x16x32_bf16 v[94:97], v[170:173], v[194:197], v[94:97]
	v_mfma_f32_16x16x32_bf16 v[86:89], v[178:181], v[194:197], v[86:89]
	v_mfma_f32_16x16x32_bf16 v[82:85], v[170:173], v[216:219], v[82:85]
	v_mfma_f32_16x16x32_bf16 v[78:81], v[178:181], v[216:219], v[78:81]
	v_mfma_f32_16x16x32_bf16 v[74:77], v[170:173], v[224:227], v[74:77]
	v_mfma_f32_16x16x32_bf16 v[70:73], v[178:181], v[224:227], v[70:73]
	v_mfma_f32_16x16x32_bf16 v[114:117], v[174:177], v[190:193], v[114:117]
	v_mfma_f32_16x16x32_bf16 v[102:105], v[182:185], v[190:193], v[102:105]
	v_mfma_f32_16x16x32_bf16 v[94:97], v[174:177], v[212:215], v[94:97]
	v_mfma_f32_16x16x32_bf16 v[86:89], v[182:185], v[212:215], v[86:89]
	v_mfma_f32_16x16x32_bf16 v[82:85], v[174:177], v[220:223], v[82:85]
	v_mfma_f32_16x16x32_bf16 v[78:81], v[182:185], v[220:223], v[78:81]
	v_mfma_f32_16x16x32_bf16 v[74:77], v[174:177], v[228:231], v[74:77]
	v_mfma_f32_16x16x32_bf16 v[70:73], v[182:185], v[228:231], v[70:73]
	s_barrier
; #define PG8_STAGE(bufoff, gbase, voff) do { _Pragma("unroll") for (int _i = 0; _i < 2; ++_i) \
;         __builtin_amdgcn_global_load_lds((const unsigned*)((const char*)(gbase) + (voff)[_i]), (LAS unsigned*)(lds + (bufoff) + ldsw + _i * 8192), 16, 0, 0); } while (0)
; #define PG8_LDA(dst, b, h) do { _Pragma("unroll") for (int m = 0; m < 4; ++m) _Pragma("unroll") for (int k = 0; k < 2; ++k) dst[m][k] = *(const LAS bf16x8*)(lds + PG8_SA(b, h) + aoff + m * 2048 + k * 1024); } while (0)
; #define PG8_MMA(ai, bj, At, Bt) do { __builtin_amdgcn_s_setprio(1); _Pragma("unroll") for (int m = 0; m < 4; ++m) _Pragma("unroll") for (int n = 0; n < 2; ++n) _Pragma("unroll") for (int k = 0; k < 2; ++k) \
;         acc[ai][bj][m][n] = __builtin_amdgcn_mfma_f32_16x16x32_bf16(Bt[n][k], At[m][k], acc[ai][bj][m][n], 0, 0, 0); __builtin_amdgcn_s_setprio(0); } while (0)
; #define PG8_WAIT_V(n) asm volatile("s_waitcnt vmcnt(" #n ")" ::: "memory")
; #define PG8_WAIT_L(n) asm volatile("s_waitcnt lgkmcnt(" #n ")" ::: "memory")
; #define PG8_BAR __builtin_amdgcn_s_barrier()
; #define PG8_SCHED __builtin_amdgcn_sched_barrier(0)
; template <class Epi, class Sched>
; __device__ __forceinline__ void gemm_phase(LAS unsigned char* lds, const Gemm g, const Sched& S, const Epi& E) {
;     ...
;             PG8_LDA(At, 1, 1); PG8_STAGE(PG8_SB(1, 0), b3, voffB); PG8_STAGE(PG8_SB(1, 1), b3 + hstepB, voffB); PG8_STAGE(PG8_SA(1, 0), a3, voffA);
;             PG8_WAIT_V(8); PG8_WAIT_L(0); PG8_BAR; PG8_MMA(1, 0, At, B0); PG8_MMA(1, 1, At, B1); PG8_BAR; PG8_SCHED;
;         }
;         if (wr == 0) PG8_BAR;
	s_add_i32 s48, s70, s57
	v_lshl_add_u64 v[166:167], v[166:167], 0, s[36:37]
	s_mov_b32 m0, s48
	ds_read_b128 v[186:189], v149 offset:49152
	ds_read_b128 v[190:193], v149 offset:50176
	ds_read_b128 v[194:197], v149 offset:51200
	ds_read_b128 v[212:215], v149 offset:52224
	ds_read_b128 v[216:219], v149 offset:53248
	ds_read_b128 v[220:223], v149 offset:54272
	ds_read_b128 v[224:227], v149 offset:55296
	ds_read_b128 v[228:231], v149 offset:56320
	global_load_lds_dwordx4 v[166:167], off
	v_lshl_add_u64 v[166:167], v[236:237], 0, s[36:37]
	s_add_i32 m0, s48, 0x2000
	s_add_i32 s48, s71, s57
	global_load_lds_dwordx4 v[166:167], off
	v_lshl_add_u64 v[166:167], v[238:239], 0, s[36:37]
	s_mov_b32 m0, s48
	s_nop 0
	global_load_lds_dwordx4 v[166:167], off
	v_lshl_add_u64 v[166:167], v[240:241], 0, s[36:37]
	s_add_i32 m0, s48, 0x2000
	s_nop 0
	global_load_lds_dwordx4 v[166:167], off
	v_lshl_add_u64 v[166:167], v[242:243], 0, s[36:37]
	s_mov_b32 m0, s62
	s_nop 0
	global_load_lds_dwordx4 v[166:167], off
	v_lshl_add_u64 v[166:167], v[244:245], 0, s[36:37]
	s_mov_b32 m0, s63
	s_nop 0
	global_load_lds_dwordx4 v[166:167], off
	s_waitcnt vmcnt(8)
	s_waitcnt lgkmcnt(0)
	s_barrier
	s_waitcnt lgkmcnt(0)
	v_mfma_f32_16x16x32_bf16 v[66:69], v[150:153], v[186:189], v[66:69]
	v_mfma_f32_16x16x32_bf16 v[62:65], v[158:161], v[186:189], v[62:65]
	v_mfma_f32_16x16x32_bf16 v[58:61], v[150:153], v[194:197], v[58:61]
	v_mfma_f32_16x16x32_bf16 v[54:57], v[158:161], v[194:197], v[54:57]
	v_mfma_f32_16x16x32_bf16 v[50:53], v[150:153], v[216:219], v[50:53]
	v_mfma_f32_16x16x32_bf16 v[42:45], v[158:161], v[216:219], v[42:45]
	v_mfma_f32_16x16x32_bf16 v[34:37], v[150:153], v[224:227], v[34:37]
	v_mfma_f32_16x16x32_bf16 v[26:29], v[158:161], v[224:227], v[26:29]
	v_mfma_f32_16x16x32_bf16 v[66:69], v[154:157], v[190:193], v[66:69]
	v_mfma_f32_16x16x32_bf16 v[62:65], v[162:165], v[190:193], v[62:65]
	v_mfma_f32_16x16x32_bf16 v[58:61], v[154:157], v[212:215], v[58:61]
	v_mfma_f32_16x16x32_bf16 v[54:57], v[162:165], v[212:215], v[54:57]
	v_mfma_f32_16x16x32_bf16 v[50:53], v[154:157], v[220:223], v[50:53]
	v_mfma_f32_16x16x32_bf16 v[42:45], v[162:165], v[220:223], v[42:45]
	v_mfma_f32_16x16x32_bf16 v[34:37], v[154:157], v[228:231], v[34:37]
	v_mfma_f32_16x16x32_bf16 v[26:29], v[162:165], v[228:231], v[26:29]
	v_mfma_f32_16x16x32_bf16 v[46:49], v[170:173], v[186:189], v[46:49]
	v_mfma_f32_16x16x32_bf16 v[38:41], v[178:181], v[186:189], v[38:41]
	v_mfma_f32_16x16x32_bf16 v[30:33], v[170:173], v[194:197], v[30:33]
	v_mfma_f32_16x16x32_bf16 v[22:25], v[178:181], v[194:197], v[22:25]
	v_mfma_f32_16x16x32_bf16 v[18:21], v[170:173], v[216:219], v[18:21]
	v_mfma_f32_16x16x32_bf16 v[14:17], v[178:181], v[216:219], v[14:17]
	v_mfma_f32_16x16x32_bf16 v[10:13], v[170:173], v[224:227], v[10:13]
	v_mfma_f32_16x16x32_bf16 v[6:9], v[178:181], v[224:227], v[6:9]
	v_mfma_f32_16x16x32_bf16 v[46:49], v[174:177], v[190:193], v[46:49]
	v_mfma_f32_16x16x32_bf16 v[38:41], v[182:185], v[190:193], v[38:41]
	v_mfma_f32_16x16x32_bf16 v[30:33], v[174:177], v[212:215], v[30:33]
	v_mfma_f32_16x16x32_bf16 v[22:25], v[182:185], v[212:215], v[22:25]
	v_mfma_f32_16x16x32_bf16 v[18:21], v[174:177], v[220:223], v[18:21]
	v_mfma_f32_16x16x32_bf16 v[14:17], v[182:185], v[220:223], v[14:17]
	v_mfma_f32_16x16x32_bf16 v[10:13], v[174:177], v[228:231], v[10:13]
	v_mfma_f32_16x16x32_bf16 v[6:9], v[182:185], v[228:231], v[6:9]
	s_barrier
	s_add_u32 s46, s46, 0x100
	s_addc_u32 s47, s47, 0
	v_lshl_add_u64 v[146:147], v[146:147], 0, s[30:31]
	v_lshl_add_u64 v[2:3], v[2:3], 0, s[30:31]
	s_cmp_ge_u32 s43, s64
	s_mov_b32 s48, s43
	s_cbranch_scc0 .LBB0_1009
	s_and_b64 vcc, exec, s[28:29]
	s_cbranch_vccz .LBB0_1012
	s_barrier

; __device__ __forceinline__ unsigned xb_ld(unsigned* p)              { return __hip_atomic_load(p, __ATOMIC_RELAXED, __HIP_MEMORY_SCOPE_AGENT); }
; #define XB_SPIN(cond, bar) do { unsigned _sp = 0; while (cond) { __builtin_amdgcn_s_sleep(1); \
;     if ((++_sp & 255u) == 0u) { if (xb_ld(&(bar)[XB_TMO])) break; if (_sp > XB_SPIN_CAP) { atomicAdd(&(bar)[XB_TMO], 1u); break; } } } } while (0)
; __device__ __forceinline__ void xcd_barrier(const XcdBarrier& b) {
;     asm volatile("s_waitcnt vmcnt(0)" ::: "memory");
;     __syncthreads();
;     if (threadIdx.x == 0) {
;         unsigned* bar = b.bar;
;         __builtin_amdgcn_s_waitcnt(0);
;         unsigned nloc = b.st[0], nx = b.st[1];
;         if (nloc == 0u) { xcd_barrier_complete(bar, b.x, nloc, nx); b.st[0] = nloc; b.st[1] = nx; }
;         const unsigned k1 = b.st[2] + 1u, rank = b.st[3]; b.st[2] = k1;
;         (void)__hip_atomic_fetch_add(&bar[XB_XSUB(b.x)], 1u, __ATOMIC_RELAXED, __HIP_MEMORY_SCOPE_AGENT);
;         if (rank == 0u) {
;             XB_SPIN(xb_ld(&bar[XB_XSUB(b.x)]) < k1 * nloc, bar);
;             __builtin_amdgcn_fence(__ATOMIC_RELEASE, "agent");
;             asm volatile("s_waitcnt vmcnt(0)" ::: "memory");
;             (void)__hip_atomic_fetch_add(&bar[XB_TOP], 1u, __ATOMIC_RELAXED, __HIP_MEMORY_SCOPE_AGENT);
;         }
;         XB_SPIN(xb_ld(&bar[XB_TOP]) < k1 * nx, bar);
;         __builtin_amdgcn_fence(__ATOMIC_ACQUIRE, "agent");
;         asm volatile("s_waitcnt vmcnt(0)" ::: "memory");
;     }
;     __syncthreads();
.LBB0_1074:
	s_setprio 0
	s_mov_b64 s[6:7], s[96:97]
	s_waitcnt vmcnt(0)
	s_waitcnt vmcnt(0) lgkmcnt(0)
	s_barrier
	s_mov_b64 s[4:5], exec
	v_readlane_b32 s8, v254, 21
	v_readlane_b32 s9, v254, 22
	s_and_b64 s[8:9], s[4:5], s[8:9]
	s_mov_b64 exec, s[8:9]
	s_cbranch_execnz .LBB0_1075
	s_getpc_b64 s[98:99]
